# WS2b: as WS2 but the last 4096 of the 40960 phase-0 rows are converted by workgroups 128..255 only (they skip the channel-map routine)
# baseline (speedup 1.0000x reference)
; __device__ void p0_xconv(const Args& a) {
;     f16* XH = (f16*)(a.ws + WS_XH); float* SS = (float*)(a.ws + WS_SS);
;     int tid_ = threadIdx.x; asm volatile("" : "+v"(tid_));
;     const int lane = tid_ & 63, wv = tid_ >> 6;
;     const int nwv = (int)gridDim.x * 8;
;     for (int row0 = (int)blockIdx.x * 8 + wv; row0 < MROWS; row0 += 4 * nwv) {
;         f32x4 v[4][4];
; #pragma unroll
;         for (int r = 0; r < 4; ++r) {
;             const int row = row0 + r * nwv;
;             if (row < MROWS) {
;                 const float* src = (row < ROWS_PROMPT) ? a.x_prompt + (size_t)row * DM : a.x_sample + (size_t)(row - ROWS_PROMPT) * DM;
; #pragma unroll
;                 for (int i = 0; i < 4; ++i) v[r][i] = __builtin_nontemporal_load((const f32x4*)(src + i * 256 + lane * 4));
;             }
;         }
; #pragma unroll
;         for (int r = 0; r < 4; ++r) {
;             const int row = row0 + r * nwv;
;             if (row < MROWS) {
;                 float ss = 0.f;
; #pragma unroll
;                 for (int i = 0; i < 4; ++i) {
;                     const f32x4 x = v[r][i];
;                     ss += (x[0] * x[0] + x[1] * x[1]) + (x[2] * x[2] + x[3] * x[3]);
;                     f16x4 h; h[0] = (f16)x[0]; h[1] = (f16)x[1]; h[2] = (f16)x[2]; h[3] = (f16)x[3];
;                     *(f16x4*)(XH + (size_t)row * DM + i * 256 + lane * 4) = h;
;                 }
; #pragma unroll
;                 for (int o = 1; o < 64; o <<= 1) ss += __shfl_xor(ss, o);
;                 if (lane < 16) SS[(size_t)row * 16 + lane] = (lane == 0) ? ss : 0.f;
.Lws_x:
	v_and_b32_e32 v136, 63, v0
	v_lshrrev_b32_e32 v137, 6, v0
	s_nop 0
	v_readfirstlane_b32 s3, v137
	s_nop 3
	s_lshl_b32 s4, s2, 2
	s_add_i32 s3, s3, s4
	s_add_i32 s3, s3, -4
	s_mov_b64 s[12:13], 1
	v_xor_b32_e32 v130, 1, v136
	v_lshlrev_b32_e32 v130, 2, v130
	v_xor_b32_e32 v131, 2, v136
	v_lshlrev_b32_e32 v131, 2, v131
	v_xor_b32_e32 v132, 4, v136
	v_lshlrev_b32_e32 v132, 2, v132
	v_xor_b32_e32 v133, 8, v136
	v_lshlrev_b32_e32 v133, 2, v133
	v_xor_b32_e32 v134, 16, v136
	v_lshlrev_b32_e32 v134, 2, v134
	v_xor_b32_e32 v135, 32, v136
	v_lshlrev_b32_e32 v135, 2, v135
	v_lshlrev_b32_e32 v140, 4, v136
	v_lshlrev_b32_e32 v144, 3, v136
	v_lshlrev_b32_e32 v186, 2, v136
	v_lshlrev_b32_e32 v190, 4, v136
	v_lshlrev_b32_e32 v194, 3, v136
	v_lshlrev_b32_e32 v198, 2, v136
	v_lshlrev_b32_e32 v141, 4, v136
	v_add_u32_e32 v141, 0x400000, v141
	v_lshlrev_b32_e32 v145, 3, v136
	v_add_u32_e32 v145, 0x200000, v145
	v_lshlrev_b32_e32 v187, 2, v136
	v_add_u32_e32 v187, 0x10000, v187
	v_lshlrev_b32_e32 v191, 4, v136
	v_add_u32_e32 v191, 0x200000, v191
	v_lshlrev_b32_e32 v195, 3, v136
	v_add_u32_e32 v195, 0x100000, v195
	v_lshlrev_b32_e32 v199, 2, v136
	v_add_u32_e32 v199, 0x8000, v199
	v_lshlrev_b32_e32 v142, 4, v136
	v_add_u32_e32 v142, 0x800000, v142
	v_lshlrev_b32_e32 v146, 3, v136
	v_add_u32_e32 v146, 0x400000, v146
	v_lshlrev_b32_e32 v188, 2, v136
	v_add_u32_e32 v188, 0x20000, v188
	v_lshlrev_b32_e32 v192, 4, v136
	v_add_u32_e32 v192, 0x400000, v192
	v_lshlrev_b32_e32 v196, 3, v136
	v_add_u32_e32 v196, 0x200000, v196
	v_lshlrev_b32_e32 v200, 2, v136
	v_add_u32_e32 v200, 0x10000, v200
	v_lshlrev_b32_e32 v143, 4, v136
	v_add_u32_e32 v143, 0xc00000, v143
	v_lshlrev_b32_e32 v147, 3, v136
	v_add_u32_e32 v147, 0x600000, v147
	v_lshlrev_b32_e32 v189, 2, v136
	v_add_u32_e32 v189, 0x30000, v189
	v_lshlrev_b32_e32 v193, 4, v136
	v_add_u32_e32 v193, 0x600000, v193
	v_lshlrev_b32_e32 v197, 3, v136
	v_add_u32_e32 v197, 0x300000, v197
	v_lshlrev_b32_e32 v201, 2, v136
	v_add_u32_e32 v201, 0x18000, v201
	s_add_i32 s9, s3, 0xfffffe00
	s_cmpk_lt_u32 s2, 0x80
	s_cbranch_scc1 .Lws_xlo
	s_add_i32 s6, s3, 0x0
	s_lshl_b32 s6, s6, 12
	s_add_u32 s4, s16, s6
	s_addc_u32 s5, s17, 0
	global_load_dwordx4 v[2:5], v140, s[4:5] nt
	global_load_dwordx4 v[6:9], v140, s[4:5] offset:1024 nt
	global_load_dwordx4 v[10:13], v140, s[4:5] offset:2048 nt
	global_load_dwordx4 v[14:17], v140, s[4:5] offset:3072 nt
	global_load_dwordx4 v[18:21], v141, s[4:5] nt
	global_load_dwordx4 v[22:25], v141, s[4:5] offset:1024 nt
	global_load_dwordx4 v[26:29], v141, s[4:5] offset:2048 nt
	global_load_dwordx4 v[30:33], v141, s[4:5] offset:3072 nt
	global_load_dwordx4 v[34:37], v142, s[4:5] nt
	global_load_dwordx4 v[38:41], v142, s[4:5] offset:1024 nt
	global_load_dwordx4 v[42:45], v142, s[4:5] offset:2048 nt
	global_load_dwordx4 v[46:49], v142, s[4:5] offset:3072 nt
	global_load_dwordx4 v[50:53], v143, s[4:5] nt
	global_load_dwordx4 v[54:57], v143, s[4:5] offset:1024 nt
	global_load_dwordx4 v[58:61], v143, s[4:5] offset:2048 nt
	global_load_dwordx4 v[62:65], v143, s[4:5] offset:3072 nt
	s_add_i32 s6, s3, 0x1000
	s_lshl_b32 s6, s6, 12
	s_add_u32 s4, s16, s6
	s_addc_u32 s5, s17, 0
	global_load_dwordx4 v[66:69], v140, s[4:5] nt
	global_load_dwordx4 v[70:73], v140, s[4:5] offset:1024 nt
	global_load_dwordx4 v[74:77], v140, s[4:5] offset:2048 nt
	global_load_dwordx4 v[78:81], v140, s[4:5] offset:3072 nt
	global_load_dwordx4 v[82:85], v141, s[4:5] nt
	global_load_dwordx4 v[86:89], v141, s[4:5] offset:1024 nt
	global_load_dwordx4 v[90:93], v141, s[4:5] offset:2048 nt
	global_load_dwordx4 v[94:97], v141, s[4:5] offset:3072 nt
	global_load_dwordx4 v[98:101], v142, s[4:5] nt
	global_load_dwordx4 v[102:105], v142, s[4:5] offset:1024 nt
	global_load_dwordx4 v[106:109], v142, s[4:5] offset:2048 nt
	global_load_dwordx4 v[110:113], v142, s[4:5] offset:3072 nt
	global_load_dwordx4 v[114:117], v143, s[4:5] nt
	global_load_dwordx4 v[118:121], v143, s[4:5] offset:1024 nt
	global_load_dwordx4 v[122:125], v143, s[4:5] offset:2048 nt
	global_load_dwordx4 v[126:129], v143, s[4:5] offset:3072 nt
	s_waitcnt vmcnt(16)
	s_add_i32 s6, s3, 0x0
	s_lshl_b32 s7, s6, 11
	s_add_u32 s10, s40, s7
	s_addc_u32 s11, s41, 0
	s_lshl_b32 s7, s6, 6
	s_add_u32 s6, s40, s7
	s_addc_u32 s7, s41, 0
	s_add_u32 s6, s6, 0x1f800000
	s_addc_u32 s7, s7, 0
	v_mul_f32_e32 v150, v3, v3
	v_mul_f32_e32 v151, v5, v5
	v_fmac_f32_e32 v150, v2, v2
	v_fmac_f32_e32 v151, v4, v4
	v_add_f32_e32 v160, v150, v151
	v_cvt_pk_f16_f32 v170, v2, v3
	v_cvt_pk_f16_f32 v171, v4, v5
	v_mul_f32_e32 v150, v7, v7
	v_mul_f32_e32 v151, v9, v9
	v_fmac_f32_e32 v150, v6, v6
	v_fmac_f32_e32 v151, v8, v8
	v_add_f32_e32 v152, v150, v151
	v_add_f32_e32 v160, v160, v152
	v_cvt_pk_f16_f32 v172, v6, v7
	v_cvt_pk_f16_f32 v173, v8, v9
	v_mul_f32_e32 v150, v11, v11
	v_mul_f32_e32 v151, v13, v13
	v_fmac_f32_e32 v150, v10, v10
	v_fmac_f32_e32 v151, v12, v12
	v_add_f32_e32 v152, v150, v151
	v_add_f32_e32 v160, v160, v152
	v_cvt_pk_f16_f32 v174, v10, v11
	v_cvt_pk_f16_f32 v175, v12, v13
	v_mul_f32_e32 v150, v15, v15
	v_mul_f32_e32 v151, v17, v17
	v_fmac_f32_e32 v150, v14, v14
	v_fmac_f32_e32 v151, v16, v16
	v_add_f32_e32 v152, v150, v151
	v_add_f32_e32 v160, v160, v152
	v_cvt_pk_f16_f32 v176, v14, v15
	v_cvt_pk_f16_f32 v177, v16, v17
	global_store_dwordx2 v144, v[170:171], s[10:11]
	global_store_dwordx2 v144, v[172:173], s[10:11] offset:512
	global_store_dwordx2 v144, v[174:175], s[10:11] offset:1024
	global_store_dwordx2 v144, v[176:177], s[10:11] offset:1536
	v_mul_f32_e32 v150, v19, v19
	v_mul_f32_e32 v151, v21, v21
	v_fmac_f32_e32 v150, v18, v18
	v_fmac_f32_e32 v151, v20, v20
	v_add_f32_e32 v161, v150, v151
; __device__ void p0_xconv(const Args& a) {
;     ...
;         for (int r = 0; r < 4; ++r) {
;             const int row = row0 + r * nwv;
;             if (row < MROWS) {
;                 float ss = 0.f;
; #pragma unroll
;                 for (int i = 0; i < 4; ++i) {
;                     const f32x4 x = v[r][i];
;                     ss += (x[0] * x[0] + x[1] * x[1]) + (x[2] * x[2] + x[3] * x[3]);
;                     f16x4 h; h[0] = (f16)x[0]; h[1] = (f16)x[1]; h[2] = (f16)x[2]; h[3] = (f16)x[3];
;                     *(f16x4*)(XH + (size_t)row * DM + i * 256 + lane * 4) = h;
;                 }
; #pragma unroll
;                 for (int o = 1; o < 64; o <<= 1) ss += __shfl_xor(ss, o);
	v_cvt_pk_f16_f32 v178, v18, v19
	v_cvt_pk_f16_f32 v179, v20, v21
	v_mul_f32_e32 v150, v23, v23
	v_mul_f32_e32 v151, v25, v25
	v_fmac_f32_e32 v150, v22, v22
	v_fmac_f32_e32 v151, v24, v24
	v_add_f32_e32 v152, v150, v151
	v_add_f32_e32 v161, v161, v152
	v_cvt_pk_f16_f32 v180, v22, v23
	v_cvt_pk_f16_f32 v181, v24, v25
	v_mul_f32_e32 v150, v27, v27
	v_mul_f32_e32 v151, v29, v29
	v_fmac_f32_e32 v150, v26, v26
	v_fmac_f32_e32 v151, v28, v28
	v_add_f32_e32 v152, v150, v151
	v_add_f32_e32 v161, v161, v152
	v_cvt_pk_f16_f32 v182, v26, v27
	v_cvt_pk_f16_f32 v183, v28, v29
	v_mul_f32_e32 v150, v31, v31
	v_mul_f32_e32 v151, v33, v33
	v_fmac_f32_e32 v150, v30, v30
	v_fmac_f32_e32 v151, v32, v32
	v_add_f32_e32 v152, v150, v151
	v_add_f32_e32 v161, v161, v152
	v_cvt_pk_f16_f32 v184, v30, v31
	v_cvt_pk_f16_f32 v185, v32, v33
	global_store_dwordx2 v145, v[178:179], s[10:11]
	global_store_dwordx2 v145, v[180:181], s[10:11] offset:512
	global_store_dwordx2 v145, v[182:183], s[10:11] offset:1024
	global_store_dwordx2 v145, v[184:185], s[10:11] offset:1536
	v_mul_f32_e32 v150, v35, v35
	v_mul_f32_e32 v151, v37, v37
	v_fmac_f32_e32 v150, v34, v34
	v_fmac_f32_e32 v151, v36, v36
	v_add_f32_e32 v162, v150, v151
	v_cvt_pk_f16_f32 v170, v34, v35
	v_cvt_pk_f16_f32 v171, v36, v37
	v_mul_f32_e32 v150, v39, v39
	v_mul_f32_e32 v151, v41, v41
	v_fmac_f32_e32 v150, v38, v38
	v_fmac_f32_e32 v151, v40, v40
	v_add_f32_e32 v152, v150, v151
	v_add_f32_e32 v162, v162, v152
	v_cvt_pk_f16_f32 v172, v38, v39
	v_cvt_pk_f16_f32 v173, v40, v41
	v_mul_f32_e32 v150, v43, v43
	v_mul_f32_e32 v151, v45, v45
	v_fmac_f32_e32 v150, v42, v42
	v_fmac_f32_e32 v151, v44, v44
	v_add_f32_e32 v152, v150, v151
	v_add_f32_e32 v162, v162, v152
	v_cvt_pk_f16_f32 v174, v42, v43
	v_cvt_pk_f16_f32 v175, v44, v45
	v_mul_f32_e32 v150, v47, v47
	v_mul_f32_e32 v151, v49, v49
	v_fmac_f32_e32 v150, v46, v46
	v_fmac_f32_e32 v151, v48, v48
	v_add_f32_e32 v152, v150, v151
	v_add_f32_e32 v162, v162, v152
	v_cvt_pk_f16_f32 v176, v46, v47
	v_cvt_pk_f16_f32 v177, v48, v49
	global_store_dwordx2 v146, v[170:171], s[10:11]
	global_store_dwordx2 v146, v[172:173], s[10:11] offset:512
	global_store_dwordx2 v146, v[174:175], s[10:11] offset:1024
	global_store_dwordx2 v146, v[176:177], s[10:11] offset:1536
	v_mul_f32_e32 v150, v51, v51
	v_mul_f32_e32 v151, v53, v53
	v_fmac_f32_e32 v150, v50, v50
	v_fmac_f32_e32 v151, v52, v52
	v_add_f32_e32 v163, v150, v151
	v_cvt_pk_f16_f32 v178, v50, v51
	v_cvt_pk_f16_f32 v179, v52, v53
	v_mul_f32_e32 v150, v55, v55
	v_mul_f32_e32 v151, v57, v57
	v_fmac_f32_e32 v150, v54, v54
	v_fmac_f32_e32 v151, v56, v56
	v_add_f32_e32 v152, v150, v151
	v_add_f32_e32 v163, v163, v152
	v_cvt_pk_f16_f32 v180, v54, v55
	v_cvt_pk_f16_f32 v181, v56, v57
	v_mul_f32_e32 v150, v59, v59
	v_mul_f32_e32 v151, v61, v61
	v_fmac_f32_e32 v150, v58, v58
	v_fmac_f32_e32 v151, v60, v60
	v_add_f32_e32 v152, v150, v151
	v_add_f32_e32 v163, v163, v152
	v_cvt_pk_f16_f32 v182, v58, v59
	v_cvt_pk_f16_f32 v183, v60, v61
	v_mul_f32_e32 v150, v63, v63
	v_mul_f32_e32 v151, v65, v65
	v_fmac_f32_e32 v150, v62, v62
	v_fmac_f32_e32 v151, v64, v64
	v_add_f32_e32 v152, v150, v151
	v_add_f32_e32 v163, v163, v152
	v_cvt_pk_f16_f32 v184, v62, v63
	v_cvt_pk_f16_f32 v185, v64, v65
	global_store_dwordx2 v147, v[178:179], s[10:11]
	global_store_dwordx2 v147, v[180:181], s[10:11] offset:512
	global_store_dwordx2 v147, v[182:183], s[10:11] offset:1024
	global_store_dwordx2 v147, v[184:185], s[10:11] offset:1536
	ds_bpermute_b32 v164, v130, v160
	ds_bpermute_b32 v165, v130, v161
	ds_bpermute_b32 v166, v130, v162
	ds_bpermute_b32 v167, v130, v163
	s_waitcnt lgkmcnt(0)
	v_add_f32_e32 v160, v160, v164
	v_add_f32_e32 v161, v161, v165
	v_add_f32_e32 v162, v162, v166
	v_add_f32_e32 v163, v163, v167
	ds_bpermute_b32 v164, v131, v160
	ds_bpermute_b32 v165, v131, v161
	ds_bpermute_b32 v166, v131, v162
	ds_bpermute_b32 v167, v131, v163
	s_waitcnt lgkmcnt(0)
	v_add_f32_e32 v160, v160, v164
	v_add_f32_e32 v161, v161, v165
	v_add_f32_e32 v162, v162, v166
	v_add_f32_e32 v163, v163, v167
	ds_bpermute_b32 v164, v132, v160
	ds_bpermute_b32 v165, v132, v161
	ds_bpermute_b32 v166, v132, v162
	ds_bpermute_b32 v167, v132, v163
	s_waitcnt lgkmcnt(0)
	v_add_f32_e32 v160, v160, v164
	v_add_f32_e32 v161, v161, v165
	v_add_f32_e32 v162, v162, v166
	v_add_f32_e32 v163, v163, v167
	ds_bpermute_b32 v164, v133, v160
	ds_bpermute_b32 v165, v133, v161
	ds_bpermute_b32 v166, v133, v162
	ds_bpermute_b32 v167, v133, v163
	s_waitcnt lgkmcnt(0)
	v_add_f32_e32 v160, v160, v164
	v_add_f32_e32 v161, v161, v165
	v_add_f32_e32 v162, v162, v166
	v_add_f32_e32 v163, v163, v167
	ds_bpermute_b32 v164, v134, v160
	ds_bpermute_b32 v165, v134, v161
	ds_bpermute_b32 v166, v134, v162
	ds_bpermute_b32 v167, v134, v163
	s_waitcnt lgkmcnt(0)
	v_add_f32_e32 v160, v160, v164
	v_add_f32_e32 v161, v161, v165
	v_add_f32_e32 v162, v162, v166
	v_add_f32_e32 v163, v163, v167
	ds_bpermute_b32 v164, v135, v160
	ds_bpermute_b32 v165, v135, v161
	ds_bpermute_b32 v166, v135, v162
	ds_bpermute_b32 v167, v135, v163
	s_waitcnt lgkmcnt(0)
; __device__ void p0_xconv(const Args& a) {
;     ...
;     for (int row0 = (int)blockIdx.x * 8 + wv; row0 < MROWS; row0 += 4 * nwv) {
;         f32x4 v[4][4];
; #pragma unroll
;         for (int r = 0; r < 4; ++r) {
;             const int row = row0 + r * nwv;
;             if (row < MROWS) {
;                 const float* src = (row < ROWS_PROMPT) ? a.x_prompt + (size_t)row * DM : a.x_sample + (size_t)(row - ROWS_PROMPT) * DM;
; #pragma unroll
;                 for (int i = 0; i < 4; ++i) v[r][i] = __builtin_nontemporal_load((const f32x4*)(src + i * 256 + lane * 4));
;             }
;         }
; #pragma unroll
;         for (int r = 0; r < 4; ++r) {
;             const int row = row0 + r * nwv;
;             if (row < MROWS) {
;                 float ss = 0.f;
; #pragma unroll
;                 for (int i = 0; i < 4; ++i) {
;                     const f32x4 x = v[r][i];
;                     ss += (x[0] * x[0] + x[1] * x[1]) + (x[2] * x[2] + x[3] * x[3]);
;                     f16x4 h; h[0] = (f16)x[0]; h[1] = (f16)x[1]; h[2] = (f16)x[2]; h[3] = (f16)x[3];
;                     *(f16x4*)(XH + (size_t)row * DM + i * 256 + lane * 4) = h;
;                 }
; #pragma unroll
;                 for (int o = 1; o < 64; o <<= 1) ss += __shfl_xor(ss, o);
;                 if (lane < 16) SS[(size_t)row * 16 + lane] = (lane == 0) ? ss : 0.f;
	v_add_f32_e32 v160, v160, v164
	v_add_f32_e32 v161, v161, v165
	v_add_f32_e32 v162, v162, v166
	v_add_f32_e32 v163, v163, v167
	v_cndmask_b32_e64 v164, 0, v160, s[12:13]
	v_cndmask_b32_e64 v165, 0, v161, s[12:13]
	v_cndmask_b32_e64 v166, 0, v162, s[12:13]
	v_cndmask_b32_e64 v167, 0, v163, s[12:13]
	s_mov_b64 exec, 0xffff
	global_store_dword v186, v164, s[6:7]
	global_store_dword v187, v165, s[6:7]
	global_store_dword v188, v166, s[6:7]
	global_store_dword v189, v167, s[6:7]
	s_mov_b64 exec, -1
	s_add_i32 s6, s3, 0x2000
	s_lshl_b32 s6, s6, 12
	s_add_u32 s4, s16, s6
	s_addc_u32 s5, s17, 0
	global_load_dwordx4 v[2:5], v140, s[4:5] nt
	global_load_dwordx4 v[6:9], v140, s[4:5] offset:1024 nt
	global_load_dwordx4 v[10:13], v140, s[4:5] offset:2048 nt
	global_load_dwordx4 v[14:17], v140, s[4:5] offset:3072 nt
	global_load_dwordx4 v[18:21], v141, s[4:5] nt
	global_load_dwordx4 v[22:25], v141, s[4:5] offset:1024 nt
	global_load_dwordx4 v[26:29], v141, s[4:5] offset:2048 nt
	global_load_dwordx4 v[30:33], v141, s[4:5] offset:3072 nt
	global_load_dwordx4 v[34:37], v142, s[4:5] nt
	global_load_dwordx4 v[38:41], v142, s[4:5] offset:1024 nt
	global_load_dwordx4 v[42:45], v142, s[4:5] offset:2048 nt
	global_load_dwordx4 v[46:49], v142, s[4:5] offset:3072 nt
	global_load_dwordx4 v[50:53], v143, s[4:5] nt
	global_load_dwordx4 v[54:57], v143, s[4:5] offset:1024 nt
	global_load_dwordx4 v[58:61], v143, s[4:5] offset:2048 nt
	global_load_dwordx4 v[62:65], v143, s[4:5] offset:3072 nt
	s_waitcnt vmcnt(36)
	s_add_i32 s6, s3, 0x1000
	s_lshl_b32 s7, s6, 11
	s_add_u32 s10, s40, s7
	s_addc_u32 s11, s41, 0
	s_lshl_b32 s7, s6, 6
	s_add_u32 s6, s40, s7
	s_addc_u32 s7, s41, 0
	s_add_u32 s6, s6, 0x1f800000
	s_addc_u32 s7, s7, 0
	v_mul_f32_e32 v150, v67, v67
	v_mul_f32_e32 v151, v69, v69
	v_fmac_f32_e32 v150, v66, v66
	v_fmac_f32_e32 v151, v68, v68
	v_add_f32_e32 v160, v150, v151
	v_cvt_pk_f16_f32 v170, v66, v67
	v_cvt_pk_f16_f32 v171, v68, v69
	v_mul_f32_e32 v150, v71, v71
	v_mul_f32_e32 v151, v73, v73
	v_fmac_f32_e32 v150, v70, v70
	v_fmac_f32_e32 v151, v72, v72
	v_add_f32_e32 v152, v150, v151
	v_add_f32_e32 v160, v160, v152
	v_cvt_pk_f16_f32 v172, v70, v71
	v_cvt_pk_f16_f32 v173, v72, v73
	v_mul_f32_e32 v150, v75, v75
	v_mul_f32_e32 v151, v77, v77
	v_fmac_f32_e32 v150, v74, v74
	v_fmac_f32_e32 v151, v76, v76
	v_add_f32_e32 v152, v150, v151
	v_add_f32_e32 v160, v160, v152
	v_cvt_pk_f16_f32 v174, v74, v75
	v_cvt_pk_f16_f32 v175, v76, v77
	v_mul_f32_e32 v150, v79, v79
	v_mul_f32_e32 v151, v81, v81
	v_fmac_f32_e32 v150, v78, v78
	v_fmac_f32_e32 v151, v80, v80
	v_add_f32_e32 v152, v150, v151
	v_add_f32_e32 v160, v160, v152
	v_cvt_pk_f16_f32 v176, v78, v79
	v_cvt_pk_f16_f32 v177, v80, v81
	global_store_dwordx2 v144, v[170:171], s[10:11]
	global_store_dwordx2 v144, v[172:173], s[10:11] offset:512
	global_store_dwordx2 v144, v[174:175], s[10:11] offset:1024
	global_store_dwordx2 v144, v[176:177], s[10:11] offset:1536
	v_mul_f32_e32 v150, v83, v83
	v_mul_f32_e32 v151, v85, v85
	v_fmac_f32_e32 v150, v82, v82
	v_fmac_f32_e32 v151, v84, v84
	v_add_f32_e32 v161, v150, v151
	v_cvt_pk_f16_f32 v178, v82, v83
	v_cvt_pk_f16_f32 v179, v84, v85
	v_mul_f32_e32 v150, v87, v87
	v_mul_f32_e32 v151, v89, v89
	v_fmac_f32_e32 v150, v86, v86
	v_fmac_f32_e32 v151, v88, v88
	v_add_f32_e32 v152, v150, v151
	v_add_f32_e32 v161, v161, v152
	v_cvt_pk_f16_f32 v180, v86, v87
	v_cvt_pk_f16_f32 v181, v88, v89
	v_mul_f32_e32 v150, v91, v91
	v_mul_f32_e32 v151, v93, v93
	v_fmac_f32_e32 v150, v90, v90
	v_fmac_f32_e32 v151, v92, v92
	v_add_f32_e32 v152, v150, v151
	v_add_f32_e32 v161, v161, v152
	v_cvt_pk_f16_f32 v182, v90, v91
	v_cvt_pk_f16_f32 v183, v92, v93
	v_mul_f32_e32 v150, v95, v95
	v_mul_f32_e32 v151, v97, v97
	v_fmac_f32_e32 v150, v94, v94
	v_fmac_f32_e32 v151, v96, v96
	v_add_f32_e32 v152, v150, v151
	v_add_f32_e32 v161, v161, v152
	v_cvt_pk_f16_f32 v184, v94, v95
	v_cvt_pk_f16_f32 v185, v96, v97
	global_store_dwordx2 v145, v[178:179], s[10:11]
	global_store_dwordx2 v145, v[180:181], s[10:11] offset:512
	global_store_dwordx2 v145, v[182:183], s[10:11] offset:1024
	global_store_dwordx2 v145, v[184:185], s[10:11] offset:1536
	v_mul_f32_e32 v150, v99, v99
	v_mul_f32_e32 v151, v101, v101
	v_fmac_f32_e32 v150, v98, v98
	v_fmac_f32_e32 v151, v100, v100
	v_add_f32_e32 v162, v150, v151
	v_cvt_pk_f16_f32 v170, v98, v99
	v_cvt_pk_f16_f32 v171, v100, v101
	v_mul_f32_e32 v150, v103, v103
	v_mul_f32_e32 v151, v105, v105
	v_fmac_f32_e32 v150, v102, v102
	v_fmac_f32_e32 v151, v104, v104
	v_add_f32_e32 v152, v150, v151
	v_add_f32_e32 v162, v162, v152
	v_cvt_pk_f16_f32 v172, v102, v103
	v_cvt_pk_f16_f32 v173, v104, v105
	v_mul_f32_e32 v150, v107, v107
	v_mul_f32_e32 v151, v109, v109
	v_fmac_f32_e32 v150, v106, v106
	v_fmac_f32_e32 v151, v108, v108
	v_add_f32_e32 v152, v150, v151
	v_add_f32_e32 v162, v162, v152
	v_cvt_pk_f16_f32 v174, v106, v107
	v_cvt_pk_f16_f32 v175, v108, v109
	v_mul_f32_e32 v150, v111, v111
	v_mul_f32_e32 v151, v113, v113
	v_fmac_f32_e32 v150, v110, v110
	v_fmac_f32_e32 v151, v112, v112
	v_add_f32_e32 v152, v150, v151
	v_add_f32_e32 v162, v162, v152
	v_cvt_pk_f16_f32 v176, v110, v111
	v_cvt_pk_f16_f32 v177, v112, v113
	global_store_dwordx2 v146, v[170:171], s[10:11]
	global_store_dwordx2 v146, v[172:173], s[10:11] offset:512
	global_store_dwordx2 v146, v[174:175], s[10:11] offset:1024
	global_store_dwordx2 v146, v[176:177], s[10:11] offset:1536
	v_mul_f32_e32 v150, v115, v115
	v_mul_f32_e32 v151, v117, v117
	v_fmac_f32_e32 v150, v114, v114
	v_fmac_f32_e32 v151, v116, v116
	v_add_f32_e32 v163, v150, v151
	v_cvt_pk_f16_f32 v178, v114, v115
	v_cvt_pk_f16_f32 v179, v116, v117
	v_mul_f32_e32 v150, v119, v119
	v_mul_f32_e32 v151, v121, v121
	v_fmac_f32_e32 v150, v118, v118
	v_fmac_f32_e32 v151, v120, v120
	v_add_f32_e32 v152, v150, v151
	v_add_f32_e32 v163, v163, v152
	v_cvt_pk_f16_f32 v180, v118, v119
	v_cvt_pk_f16_f32 v181, v120, v121
	v_mul_f32_e32 v150, v123, v123
	v_mul_f32_e32 v151, v125, v125
	v_fmac_f32_e32 v150, v122, v122
	v_fmac_f32_e32 v151, v124, v124
	v_add_f32_e32 v152, v150, v151
	v_add_f32_e32 v163, v163, v152
	v_cvt_pk_f16_f32 v182, v122, v123
	v_cvt_pk_f16_f32 v183, v124, v125
	v_mul_f32_e32 v150, v127, v127
	v_mul_f32_e32 v151, v129, v129
	v_fmac_f32_e32 v150, v126, v126
	v_fmac_f32_e32 v151, v128, v128
	v_add_f32_e32 v152, v150, v151
	v_add_f32_e32 v163, v163, v152
	v_cvt_pk_f16_f32 v184, v126, v127
	v_cvt_pk_f16_f32 v185, v128, v129
	global_store_dwordx2 v147, v[178:179], s[10:11]
	global_store_dwordx2 v147, v[180:181], s[10:11] offset:512
	global_store_dwordx2 v147, v[182:183], s[10:11] offset:1024
	global_store_dwordx2 v147, v[184:185], s[10:11] offset:1536
	ds_bpermute_b32 v164, v130, v160
	ds_bpermute_b32 v165, v130, v161
	ds_bpermute_b32 v166, v130, v162
	ds_bpermute_b32 v167, v130, v163
	s_waitcnt lgkmcnt(0)
; __device__ void p0_xconv(const Args& a) {
;     ...
;     for (int row0 = (int)blockIdx.x * 8 + wv; row0 < MROWS; row0 += 4 * nwv) {
;         f32x4 v[4][4];
; #pragma unroll
;         for (int r = 0; r < 4; ++r) {
;             const int row = row0 + r * nwv;
;             if (row < MROWS) {
;                 const float* src = (row < ROWS_PROMPT) ? a.x_prompt + (size_t)row * DM : a.x_sample + (size_t)(row - ROWS_PROMPT) * DM;
; #pragma unroll
;                 for (int i = 0; i < 4; ++i) v[r][i] = __builtin_nontemporal_load((const f32x4*)(src + i * 256 + lane * 4));
;             }
;         }
; #pragma unroll
;         for (int r = 0; r < 4; ++r) {
;             const int row = row0 + r * nwv;
;             if (row < MROWS) {
;                 float ss = 0.f;
; #pragma unroll
;                 for (int i = 0; i < 4; ++i) {
;                     const f32x4 x = v[r][i];
;                     ss += (x[0] * x[0] + x[1] * x[1]) + (x[2] * x[2] + x[3] * x[3]);
;                     f16x4 h; h[0] = (f16)x[0]; h[1] = (f16)x[1]; h[2] = (f16)x[2]; h[3] = (f16)x[3];
;                     *(f16x4*)(XH + (size_t)row * DM + i * 256 + lane * 4) = h;
;                 }
; #pragma unroll
;                 for (int o = 1; o < 64; o <<= 1) ss += __shfl_xor(ss, o);
;                 if (lane < 16) SS[(size_t)row * 16 + lane] = (lane == 0) ? ss : 0.f;
	v_add_f32_e32 v160, v160, v164
	v_add_f32_e32 v161, v161, v165
	v_add_f32_e32 v162, v162, v166
	v_add_f32_e32 v163, v163, v167
	ds_bpermute_b32 v164, v131, v160
	ds_bpermute_b32 v165, v131, v161
	ds_bpermute_b32 v166, v131, v162
	ds_bpermute_b32 v167, v131, v163
	s_waitcnt lgkmcnt(0)
	v_add_f32_e32 v160, v160, v164
	v_add_f32_e32 v161, v161, v165
	v_add_f32_e32 v162, v162, v166
	v_add_f32_e32 v163, v163, v167
	ds_bpermute_b32 v164, v132, v160
	ds_bpermute_b32 v165, v132, v161
	ds_bpermute_b32 v166, v132, v162
	ds_bpermute_b32 v167, v132, v163
	s_waitcnt lgkmcnt(0)
	v_add_f32_e32 v160, v160, v164
	v_add_f32_e32 v161, v161, v165
	v_add_f32_e32 v162, v162, v166
	v_add_f32_e32 v163, v163, v167
	ds_bpermute_b32 v164, v133, v160
	ds_bpermute_b32 v165, v133, v161
	ds_bpermute_b32 v166, v133, v162
	ds_bpermute_b32 v167, v133, v163
	s_waitcnt lgkmcnt(0)
	v_add_f32_e32 v160, v160, v164
	v_add_f32_e32 v161, v161, v165
	v_add_f32_e32 v162, v162, v166
	v_add_f32_e32 v163, v163, v167
	ds_bpermute_b32 v164, v134, v160
	ds_bpermute_b32 v165, v134, v161
	ds_bpermute_b32 v166, v134, v162
	ds_bpermute_b32 v167, v134, v163
	s_waitcnt lgkmcnt(0)
	v_add_f32_e32 v160, v160, v164
	v_add_f32_e32 v161, v161, v165
	v_add_f32_e32 v162, v162, v166
	v_add_f32_e32 v163, v163, v167
	ds_bpermute_b32 v164, v135, v160
	ds_bpermute_b32 v165, v135, v161
	ds_bpermute_b32 v166, v135, v162
	ds_bpermute_b32 v167, v135, v163
	s_waitcnt lgkmcnt(0)
	v_add_f32_e32 v160, v160, v164
	v_add_f32_e32 v161, v161, v165
	v_add_f32_e32 v162, v162, v166
	v_add_f32_e32 v163, v163, v167
	v_cndmask_b32_e64 v164, 0, v160, s[12:13]
	v_cndmask_b32_e64 v165, 0, v161, s[12:13]
	v_cndmask_b32_e64 v166, 0, v162, s[12:13]
	v_cndmask_b32_e64 v167, 0, v163, s[12:13]
	s_mov_b64 exec, 0xffff
	global_store_dword v186, v164, s[6:7]
	global_store_dword v187, v165, s[6:7]
	global_store_dword v188, v166, s[6:7]
	global_store_dword v189, v167, s[6:7]
	s_mov_b64 exec, -1
	s_add_i32 s6, s3, 0x3000
	s_lshl_b32 s6, s6, 12
	s_add_u32 s4, s16, s6
	s_addc_u32 s5, s17, 0
	global_load_dwordx4 v[66:69], v140, s[4:5] nt
	global_load_dwordx4 v[70:73], v140, s[4:5] offset:1024 nt
	global_load_dwordx4 v[74:77], v140, s[4:5] offset:2048 nt
	global_load_dwordx4 v[78:81], v140, s[4:5] offset:3072 nt
	global_load_dwordx4 v[82:85], v141, s[4:5] nt
	global_load_dwordx4 v[86:89], v141, s[4:5] offset:1024 nt
	global_load_dwordx4 v[90:93], v141, s[4:5] offset:2048 nt
	global_load_dwordx4 v[94:97], v141, s[4:5] offset:3072 nt
	global_load_dwordx4 v[98:101], v142, s[4:5] nt
	global_load_dwordx4 v[102:105], v142, s[4:5] offset:1024 nt
	global_load_dwordx4 v[106:109], v142, s[4:5] offset:2048 nt
	global_load_dwordx4 v[110:113], v142, s[4:5] offset:3072 nt
	global_load_dwordx4 v[114:117], v143, s[4:5] nt
	global_load_dwordx4 v[118:121], v143, s[4:5] offset:1024 nt
	global_load_dwordx4 v[122:125], v143, s[4:5] offset:2048 nt
	global_load_dwordx4 v[126:129], v143, s[4:5] offset:3072 nt
	s_waitcnt vmcnt(36)
	s_add_i32 s6, s3, 0x2000
	s_lshl_b32 s7, s6, 11
	s_add_u32 s10, s40, s7
	s_addc_u32 s11, s41, 0
	s_lshl_b32 s7, s6, 6
	s_add_u32 s6, s40, s7
	s_addc_u32 s7, s41, 0
	s_add_u32 s6, s6, 0x1f800000
	s_addc_u32 s7, s7, 0
	v_mul_f32_e32 v150, v3, v3
	v_mul_f32_e32 v151, v5, v5
	v_fmac_f32_e32 v150, v2, v2
	v_fmac_f32_e32 v151, v4, v4
	v_add_f32_e32 v160, v150, v151
	v_cvt_pk_f16_f32 v170, v2, v3
	v_cvt_pk_f16_f32 v171, v4, v5
	v_mul_f32_e32 v150, v7, v7
	v_mul_f32_e32 v151, v9, v9
	v_fmac_f32_e32 v150, v6, v6
	v_fmac_f32_e32 v151, v8, v8
	v_add_f32_e32 v152, v150, v151
	v_add_f32_e32 v160, v160, v152
	v_cvt_pk_f16_f32 v172, v6, v7
	v_cvt_pk_f16_f32 v173, v8, v9
	v_mul_f32_e32 v150, v11, v11
	v_mul_f32_e32 v151, v13, v13
	v_fmac_f32_e32 v150, v10, v10
	v_fmac_f32_e32 v151, v12, v12
	v_add_f32_e32 v152, v150, v151
	v_add_f32_e32 v160, v160, v152
	v_cvt_pk_f16_f32 v174, v10, v11
	v_cvt_pk_f16_f32 v175, v12, v13
	v_mul_f32_e32 v150, v15, v15
	v_mul_f32_e32 v151, v17, v17
	v_fmac_f32_e32 v150, v14, v14
	v_fmac_f32_e32 v151, v16, v16
	v_add_f32_e32 v152, v150, v151
	v_add_f32_e32 v160, v160, v152
	v_cvt_pk_f16_f32 v176, v14, v15
	v_cvt_pk_f16_f32 v177, v16, v17
	global_store_dwordx2 v144, v[170:171], s[10:11]
	global_store_dwordx2 v144, v[172:173], s[10:11] offset:512
	global_store_dwordx2 v144, v[174:175], s[10:11] offset:1024
	global_store_dwordx2 v144, v[176:177], s[10:11] offset:1536
	v_mul_f32_e32 v150, v19, v19
	v_mul_f32_e32 v151, v21, v21
	v_fmac_f32_e32 v150, v18, v18
	v_fmac_f32_e32 v151, v20, v20
	v_add_f32_e32 v161, v150, v151
	v_cvt_pk_f16_f32 v178, v18, v19
	v_cvt_pk_f16_f32 v179, v20, v21
	v_mul_f32_e32 v150, v23, v23
	v_mul_f32_e32 v151, v25, v25
	v_fmac_f32_e32 v150, v22, v22
	v_fmac_f32_e32 v151, v24, v24
	v_add_f32_e32 v152, v150, v151
	v_add_f32_e32 v161, v161, v152
	v_cvt_pk_f16_f32 v180, v22, v23
	v_cvt_pk_f16_f32 v181, v24, v25
	v_mul_f32_e32 v150, v27, v27
	v_mul_f32_e32 v151, v29, v29
	v_fmac_f32_e32 v150, v26, v26
	v_fmac_f32_e32 v151, v28, v28
	v_add_f32_e32 v152, v150, v151
	v_add_f32_e32 v161, v161, v152
	v_cvt_pk_f16_f32 v182, v26, v27
	v_cvt_pk_f16_f32 v183, v28, v29
	v_mul_f32_e32 v150, v31, v31
	v_mul_f32_e32 v151, v33, v33
	v_fmac_f32_e32 v150, v30, v30
	v_fmac_f32_e32 v151, v32, v32
	v_add_f32_e32 v152, v150, v151
	v_add_f32_e32 v161, v161, v152
	v_cvt_pk_f16_f32 v184, v30, v31
	v_cvt_pk_f16_f32 v185, v32, v33
	global_store_dwordx2 v145, v[178:179], s[10:11]
	global_store_dwordx2 v145, v[180:181], s[10:11] offset:512
	global_store_dwordx2 v145, v[182:183], s[10:11] offset:1024
	global_store_dwordx2 v145, v[184:185], s[10:11] offset:1536
	v_mul_f32_e32 v150, v35, v35
	v_mul_f32_e32 v151, v37, v37
	v_fmac_f32_e32 v150, v34, v34
; __device__ void p0_xconv(const Args& a) {
;     ...
;     for (int row0 = (int)blockIdx.x * 8 + wv; row0 < MROWS; row0 += 4 * nwv) {
;         f32x4 v[4][4];
; #pragma unroll
;         for (int r = 0; r < 4; ++r) {
;             const int row = row0 + r * nwv;
;             if (row < MROWS) {
;                 const float* src = (row < ROWS_PROMPT) ? a.x_prompt + (size_t)row * DM : a.x_sample + (size_t)(row - ROWS_PROMPT) * DM;
; #pragma unroll
;                 for (int i = 0; i < 4; ++i) v[r][i] = __builtin_nontemporal_load((const f32x4*)(src + i * 256 + lane * 4));
;             }
;         }
; #pragma unroll
;         for (int r = 0; r < 4; ++r) {
;             const int row = row0 + r * nwv;
;             if (row < MROWS) {
;                 float ss = 0.f;
; #pragma unroll
;                 for (int i = 0; i < 4; ++i) {
;                     const f32x4 x = v[r][i];
;                     ss += (x[0] * x[0] + x[1] * x[1]) + (x[2] * x[2] + x[3] * x[3]);
;                     f16x4 h; h[0] = (f16)x[0]; h[1] = (f16)x[1]; h[2] = (f16)x[2]; h[3] = (f16)x[3];
;                     *(f16x4*)(XH + (size_t)row * DM + i * 256 + lane * 4) = h;
;                 }
; #pragma unroll
;                 for (int o = 1; o < 64; o <<= 1) ss += __shfl_xor(ss, o);
;                 if (lane < 16) SS[(size_t)row * 16 + lane] = (lane == 0) ? ss : 0.f;
	v_fmac_f32_e32 v151, v36, v36
	v_add_f32_e32 v162, v150, v151
	v_cvt_pk_f16_f32 v170, v34, v35
	v_cvt_pk_f16_f32 v171, v36, v37
	v_mul_f32_e32 v150, v39, v39
	v_mul_f32_e32 v151, v41, v41
	v_fmac_f32_e32 v150, v38, v38
	v_fmac_f32_e32 v151, v40, v40
	v_add_f32_e32 v152, v150, v151
	v_add_f32_e32 v162, v162, v152
	v_cvt_pk_f16_f32 v172, v38, v39
	v_cvt_pk_f16_f32 v173, v40, v41
	v_mul_f32_e32 v150, v43, v43
	v_mul_f32_e32 v151, v45, v45
	v_fmac_f32_e32 v150, v42, v42
	v_fmac_f32_e32 v151, v44, v44
	v_add_f32_e32 v152, v150, v151
	v_add_f32_e32 v162, v162, v152
	v_cvt_pk_f16_f32 v174, v42, v43
	v_cvt_pk_f16_f32 v175, v44, v45
	v_mul_f32_e32 v150, v47, v47
	v_mul_f32_e32 v151, v49, v49
	v_fmac_f32_e32 v150, v46, v46
	v_fmac_f32_e32 v151, v48, v48
	v_add_f32_e32 v152, v150, v151
	v_add_f32_e32 v162, v162, v152
	v_cvt_pk_f16_f32 v176, v46, v47
	v_cvt_pk_f16_f32 v177, v48, v49
	global_store_dwordx2 v146, v[170:171], s[10:11]
	global_store_dwordx2 v146, v[172:173], s[10:11] offset:512
	global_store_dwordx2 v146, v[174:175], s[10:11] offset:1024
	global_store_dwordx2 v146, v[176:177], s[10:11] offset:1536
	v_mul_f32_e32 v150, v51, v51
	v_mul_f32_e32 v151, v53, v53
	v_fmac_f32_e32 v150, v50, v50
	v_fmac_f32_e32 v151, v52, v52
	v_add_f32_e32 v163, v150, v151
	v_cvt_pk_f16_f32 v178, v50, v51
	v_cvt_pk_f16_f32 v179, v52, v53
	v_mul_f32_e32 v150, v55, v55
	v_mul_f32_e32 v151, v57, v57
	v_fmac_f32_e32 v150, v54, v54
	v_fmac_f32_e32 v151, v56, v56
	v_add_f32_e32 v152, v150, v151
	v_add_f32_e32 v163, v163, v152
	v_cvt_pk_f16_f32 v180, v54, v55
	v_cvt_pk_f16_f32 v181, v56, v57
	v_mul_f32_e32 v150, v59, v59
	v_mul_f32_e32 v151, v61, v61
	v_fmac_f32_e32 v150, v58, v58
	v_fmac_f32_e32 v151, v60, v60
	v_add_f32_e32 v152, v150, v151
	v_add_f32_e32 v163, v163, v152
	v_cvt_pk_f16_f32 v182, v58, v59
	v_cvt_pk_f16_f32 v183, v60, v61
	v_mul_f32_e32 v150, v63, v63
	v_mul_f32_e32 v151, v65, v65
	v_fmac_f32_e32 v150, v62, v62
	v_fmac_f32_e32 v151, v64, v64
	v_add_f32_e32 v152, v150, v151
	v_add_f32_e32 v163, v163, v152
	v_cvt_pk_f16_f32 v184, v62, v63
	v_cvt_pk_f16_f32 v185, v64, v65
	global_store_dwordx2 v147, v[178:179], s[10:11]
	global_store_dwordx2 v147, v[180:181], s[10:11] offset:512
	global_store_dwordx2 v147, v[182:183], s[10:11] offset:1024
	global_store_dwordx2 v147, v[184:185], s[10:11] offset:1536
	ds_bpermute_b32 v164, v130, v160
	ds_bpermute_b32 v165, v130, v161
	ds_bpermute_b32 v166, v130, v162
	ds_bpermute_b32 v167, v130, v163
	s_waitcnt lgkmcnt(0)
	v_add_f32_e32 v160, v160, v164
	v_add_f32_e32 v161, v161, v165
	v_add_f32_e32 v162, v162, v166
	v_add_f32_e32 v163, v163, v167
	ds_bpermute_b32 v164, v131, v160
	ds_bpermute_b32 v165, v131, v161
	ds_bpermute_b32 v166, v131, v162
	ds_bpermute_b32 v167, v131, v163
	s_waitcnt lgkmcnt(0)
	v_add_f32_e32 v160, v160, v164
	v_add_f32_e32 v161, v161, v165
	v_add_f32_e32 v162, v162, v166
	v_add_f32_e32 v163, v163, v167
	ds_bpermute_b32 v164, v132, v160
	ds_bpermute_b32 v165, v132, v161
	ds_bpermute_b32 v166, v132, v162
	ds_bpermute_b32 v167, v132, v163
	s_waitcnt lgkmcnt(0)
	v_add_f32_e32 v160, v160, v164
	v_add_f32_e32 v161, v161, v165
	v_add_f32_e32 v162, v162, v166
	v_add_f32_e32 v163, v163, v167
	ds_bpermute_b32 v164, v133, v160
	ds_bpermute_b32 v165, v133, v161
	ds_bpermute_b32 v166, v133, v162
	ds_bpermute_b32 v167, v133, v163
	s_waitcnt lgkmcnt(0)
	v_add_f32_e32 v160, v160, v164
	v_add_f32_e32 v161, v161, v165
	v_add_f32_e32 v162, v162, v166
	v_add_f32_e32 v163, v163, v167
	ds_bpermute_b32 v164, v134, v160
	ds_bpermute_b32 v165, v134, v161
	ds_bpermute_b32 v166, v134, v162
	ds_bpermute_b32 v167, v134, v163
	s_waitcnt lgkmcnt(0)
	v_add_f32_e32 v160, v160, v164
	v_add_f32_e32 v161, v161, v165
	v_add_f32_e32 v162, v162, v166
	v_add_f32_e32 v163, v163, v167
	ds_bpermute_b32 v164, v135, v160
	ds_bpermute_b32 v165, v135, v161
	ds_bpermute_b32 v166, v135, v162
	ds_bpermute_b32 v167, v135, v163
	s_waitcnt lgkmcnt(0)
	v_add_f32_e32 v160, v160, v164
	v_add_f32_e32 v161, v161, v165
	v_add_f32_e32 v162, v162, v166
	v_add_f32_e32 v163, v163, v167
	v_cndmask_b32_e64 v164, 0, v160, s[12:13]
	v_cndmask_b32_e64 v165, 0, v161, s[12:13]
	v_cndmask_b32_e64 v166, 0, v162, s[12:13]
	v_cndmask_b32_e64 v167, 0, v163, s[12:13]
	s_mov_b64 exec, 0xffff
	global_store_dword v186, v164, s[6:7]
	global_store_dword v187, v165, s[6:7]
	global_store_dword v188, v166, s[6:7]
	global_store_dword v189, v167, s[6:7]
	s_mov_b64 exec, -1
	s_add_i32 s6, s3, 0x0
	s_lshl_b32 s6, s6, 12
	s_add_u32 s4, s18, s6
	s_addc_u32 s5, s19, 0
	global_load_dwordx4 v[2:5], v140, s[4:5] nt
	global_load_dwordx4 v[6:9], v140, s[4:5] offset:1024 nt
	global_load_dwordx4 v[10:13], v140, s[4:5] offset:2048 nt
	global_load_dwordx4 v[14:17], v140, s[4:5] offset:3072 nt
	global_load_dwordx4 v[18:21], v141, s[4:5] nt
	global_load_dwordx4 v[22:25], v141, s[4:5] offset:1024 nt
	global_load_dwordx4 v[26:29], v141, s[4:5] offset:2048 nt
	global_load_dwordx4 v[30:33], v141, s[4:5] offset:3072 nt
	global_load_dwordx4 v[34:37], v142, s[4:5] nt
	global_load_dwordx4 v[38:41], v142, s[4:5] offset:1024 nt
	global_load_dwordx4 v[42:45], v142, s[4:5] offset:2048 nt
	global_load_dwordx4 v[46:49], v142, s[4:5] offset:3072 nt
	global_load_dwordx4 v[50:53], v143, s[4:5] nt
	global_load_dwordx4 v[54:57], v143, s[4:5] offset:1024 nt
	global_load_dwordx4 v[58:61], v143, s[4:5] offset:2048 nt
	global_load_dwordx4 v[62:65], v143, s[4:5] offset:3072 nt
	s_waitcnt vmcnt(36)
; __device__ void p0_xconv(const Args& a) {
;     ...
;             if (row < MROWS) {
;                 const float* src = (row < ROWS_PROMPT) ? a.x_prompt + (size_t)row * DM : a.x_sample + (size_t)(row - ROWS_PROMPT) * DM;
; #pragma unroll
;                 for (int i = 0; i < 4; ++i) v[r][i] = __builtin_nontemporal_load((const f32x4*)(src + i * 256 + lane * 4));
;             }
;         }
; #pragma unroll
;         for (int r = 0; r < 4; ++r) {
;             const int row = row0 + r * nwv;
;             if (row < MROWS) {
;                 float ss = 0.f;
; #pragma unroll
;                 for (int i = 0; i < 4; ++i) {
;                     const f32x4 x = v[r][i];
;                     ss += (x[0] * x[0] + x[1] * x[1]) + (x[2] * x[2] + x[3] * x[3]);
;                     f16x4 h; h[0] = (f16)x[0]; h[1] = (f16)x[1]; h[2] = (f16)x[2]; h[3] = (f16)x[3];
;                     *(f16x4*)(XH + (size_t)row * DM + i * 256 + lane * 4) = h;
;                 }
; #pragma unroll
;                 for (int o = 1; o < 64; o <<= 1) ss += __shfl_xor(ss, o);
	s_add_i32 s6, s3, 0x3000
	s_lshl_b32 s7, s6, 11
	s_add_u32 s10, s40, s7
	s_addc_u32 s11, s41, 0
	s_lshl_b32 s7, s6, 6
	s_add_u32 s6, s40, s7
	s_addc_u32 s7, s41, 0
	s_add_u32 s6, s6, 0x1f800000
	s_addc_u32 s7, s7, 0
	v_mul_f32_e32 v150, v67, v67
	v_mul_f32_e32 v151, v69, v69
	v_fmac_f32_e32 v150, v66, v66
	v_fmac_f32_e32 v151, v68, v68
	v_add_f32_e32 v160, v150, v151
	v_cvt_pk_f16_f32 v170, v66, v67
	v_cvt_pk_f16_f32 v171, v68, v69
	v_mul_f32_e32 v150, v71, v71
	v_mul_f32_e32 v151, v73, v73
	v_fmac_f32_e32 v150, v70, v70
	v_fmac_f32_e32 v151, v72, v72
	v_add_f32_e32 v152, v150, v151
	v_add_f32_e32 v160, v160, v152
	v_cvt_pk_f16_f32 v172, v70, v71
	v_cvt_pk_f16_f32 v173, v72, v73
	v_mul_f32_e32 v150, v75, v75
	v_mul_f32_e32 v151, v77, v77
	v_fmac_f32_e32 v150, v74, v74
	v_fmac_f32_e32 v151, v76, v76
	v_add_f32_e32 v152, v150, v151
	v_add_f32_e32 v160, v160, v152
	v_cvt_pk_f16_f32 v174, v74, v75
	v_cvt_pk_f16_f32 v175, v76, v77
	v_mul_f32_e32 v150, v79, v79
	v_mul_f32_e32 v151, v81, v81
	v_fmac_f32_e32 v150, v78, v78
	v_fmac_f32_e32 v151, v80, v80
	v_add_f32_e32 v152, v150, v151
	v_add_f32_e32 v160, v160, v152
	v_cvt_pk_f16_f32 v176, v78, v79
	v_cvt_pk_f16_f32 v177, v80, v81
	global_store_dwordx2 v144, v[170:171], s[10:11]
	global_store_dwordx2 v144, v[172:173], s[10:11] offset:512
	global_store_dwordx2 v144, v[174:175], s[10:11] offset:1024
	global_store_dwordx2 v144, v[176:177], s[10:11] offset:1536
	v_mul_f32_e32 v150, v83, v83
	v_mul_f32_e32 v151, v85, v85
	v_fmac_f32_e32 v150, v82, v82
	v_fmac_f32_e32 v151, v84, v84
	v_add_f32_e32 v161, v150, v151
	v_cvt_pk_f16_f32 v178, v82, v83
	v_cvt_pk_f16_f32 v179, v84, v85
	v_mul_f32_e32 v150, v87, v87
	v_mul_f32_e32 v151, v89, v89
	v_fmac_f32_e32 v150, v86, v86
	v_fmac_f32_e32 v151, v88, v88
	v_add_f32_e32 v152, v150, v151
	v_add_f32_e32 v161, v161, v152
	v_cvt_pk_f16_f32 v180, v86, v87
	v_cvt_pk_f16_f32 v181, v88, v89
	v_mul_f32_e32 v150, v91, v91
	v_mul_f32_e32 v151, v93, v93
	v_fmac_f32_e32 v150, v90, v90
	v_fmac_f32_e32 v151, v92, v92
	v_add_f32_e32 v152, v150, v151
	v_add_f32_e32 v161, v161, v152
	v_cvt_pk_f16_f32 v182, v90, v91
	v_cvt_pk_f16_f32 v183, v92, v93
	v_mul_f32_e32 v150, v95, v95
	v_mul_f32_e32 v151, v97, v97
	v_fmac_f32_e32 v150, v94, v94
	v_fmac_f32_e32 v151, v96, v96
	v_add_f32_e32 v152, v150, v151
	v_add_f32_e32 v161, v161, v152
	v_cvt_pk_f16_f32 v184, v94, v95
	v_cvt_pk_f16_f32 v185, v96, v97
	global_store_dwordx2 v145, v[178:179], s[10:11]
	global_store_dwordx2 v145, v[180:181], s[10:11] offset:512
	global_store_dwordx2 v145, v[182:183], s[10:11] offset:1024
	global_store_dwordx2 v145, v[184:185], s[10:11] offset:1536
	v_mul_f32_e32 v150, v99, v99
	v_mul_f32_e32 v151, v101, v101
	v_fmac_f32_e32 v150, v98, v98
	v_fmac_f32_e32 v151, v100, v100
	v_add_f32_e32 v162, v150, v151
	v_cvt_pk_f16_f32 v170, v98, v99
	v_cvt_pk_f16_f32 v171, v100, v101
	v_mul_f32_e32 v150, v103, v103
	v_mul_f32_e32 v151, v105, v105
	v_fmac_f32_e32 v150, v102, v102
	v_fmac_f32_e32 v151, v104, v104
	v_add_f32_e32 v152, v150, v151
	v_add_f32_e32 v162, v162, v152
	v_cvt_pk_f16_f32 v172, v102, v103
	v_cvt_pk_f16_f32 v173, v104, v105
	v_mul_f32_e32 v150, v107, v107
	v_mul_f32_e32 v151, v109, v109
	v_fmac_f32_e32 v150, v106, v106
	v_fmac_f32_e32 v151, v108, v108
	v_add_f32_e32 v152, v150, v151
	v_add_f32_e32 v162, v162, v152
	v_cvt_pk_f16_f32 v174, v106, v107
	v_cvt_pk_f16_f32 v175, v108, v109
	v_mul_f32_e32 v150, v111, v111
	v_mul_f32_e32 v151, v113, v113
	v_fmac_f32_e32 v150, v110, v110
	v_fmac_f32_e32 v151, v112, v112
	v_add_f32_e32 v152, v150, v151
	v_add_f32_e32 v162, v162, v152
	v_cvt_pk_f16_f32 v176, v110, v111
	v_cvt_pk_f16_f32 v177, v112, v113
	global_store_dwordx2 v146, v[170:171], s[10:11]
	global_store_dwordx2 v146, v[172:173], s[10:11] offset:512
	global_store_dwordx2 v146, v[174:175], s[10:11] offset:1024
	global_store_dwordx2 v146, v[176:177], s[10:11] offset:1536
	v_mul_f32_e32 v150, v115, v115
	v_mul_f32_e32 v151, v117, v117
	v_fmac_f32_e32 v150, v114, v114
	v_fmac_f32_e32 v151, v116, v116
	v_add_f32_e32 v163, v150, v151
	v_cvt_pk_f16_f32 v178, v114, v115
	v_cvt_pk_f16_f32 v179, v116, v117
	v_mul_f32_e32 v150, v119, v119
	v_mul_f32_e32 v151, v121, v121
	v_fmac_f32_e32 v150, v118, v118
	v_fmac_f32_e32 v151, v120, v120
	v_add_f32_e32 v152, v150, v151
	v_add_f32_e32 v163, v163, v152
	v_cvt_pk_f16_f32 v180, v118, v119
	v_cvt_pk_f16_f32 v181, v120, v121
	v_mul_f32_e32 v150, v123, v123
	v_mul_f32_e32 v151, v125, v125
	v_fmac_f32_e32 v150, v122, v122
	v_fmac_f32_e32 v151, v124, v124
	v_add_f32_e32 v152, v150, v151
	v_add_f32_e32 v163, v163, v152
	v_cvt_pk_f16_f32 v182, v122, v123
	v_cvt_pk_f16_f32 v183, v124, v125
	v_mul_f32_e32 v150, v127, v127
	v_mul_f32_e32 v151, v129, v129
	v_fmac_f32_e32 v150, v126, v126
	v_fmac_f32_e32 v151, v128, v128
	v_add_f32_e32 v152, v150, v151
	v_add_f32_e32 v163, v163, v152
	v_cvt_pk_f16_f32 v184, v126, v127
	v_cvt_pk_f16_f32 v185, v128, v129
	global_store_dwordx2 v147, v[178:179], s[10:11]
	global_store_dwordx2 v147, v[180:181], s[10:11] offset:512
	global_store_dwordx2 v147, v[182:183], s[10:11] offset:1024
	global_store_dwordx2 v147, v[184:185], s[10:11] offset:1536
	ds_bpermute_b32 v164, v130, v160
	ds_bpermute_b32 v165, v130, v161
	ds_bpermute_b32 v166, v130, v162
	ds_bpermute_b32 v167, v130, v163
	s_waitcnt lgkmcnt(0)
	v_add_f32_e32 v160, v160, v164
	v_add_f32_e32 v161, v161, v165
	v_add_f32_e32 v162, v162, v166
	v_add_f32_e32 v163, v163, v167
	ds_bpermute_b32 v164, v131, v160
	ds_bpermute_b32 v165, v131, v161
	ds_bpermute_b32 v166, v131, v162
	ds_bpermute_b32 v167, v131, v163
	s_waitcnt lgkmcnt(0)
; __device__ void p0_xconv(const Args& a) {
;     ...
;     for (int row0 = (int)blockIdx.x * 8 + wv; row0 < MROWS; row0 += 4 * nwv) {
;         f32x4 v[4][4];
; #pragma unroll
;         for (int r = 0; r < 4; ++r) {
;             const int row = row0 + r * nwv;
;             if (row < MROWS) {
;                 const float* src = (row < ROWS_PROMPT) ? a.x_prompt + (size_t)row * DM : a.x_sample + (size_t)(row - ROWS_PROMPT) * DM;
; #pragma unroll
;                 for (int i = 0; i < 4; ++i) v[r][i] = __builtin_nontemporal_load((const f32x4*)(src + i * 256 + lane * 4));
;             }
;         }
; #pragma unroll
;         for (int r = 0; r < 4; ++r) {
;             const int row = row0 + r * nwv;
;             if (row < MROWS) {
;                 float ss = 0.f;
; #pragma unroll
;                 for (int i = 0; i < 4; ++i) {
;                     const f32x4 x = v[r][i];
;                     ss += (x[0] * x[0] + x[1] * x[1]) + (x[2] * x[2] + x[3] * x[3]);
;                     f16x4 h; h[0] = (f16)x[0]; h[1] = (f16)x[1]; h[2] = (f16)x[2]; h[3] = (f16)x[3];
;                     *(f16x4*)(XH + (size_t)row * DM + i * 256 + lane * 4) = h;
;                 }
; #pragma unroll
;                 for (int o = 1; o < 64; o <<= 1) ss += __shfl_xor(ss, o);
;                 if (lane < 16) SS[(size_t)row * 16 + lane] = (lane == 0) ? ss : 0.f;
	v_add_f32_e32 v160, v160, v164
	v_add_f32_e32 v161, v161, v165
	v_add_f32_e32 v162, v162, v166
	v_add_f32_e32 v163, v163, v167
	ds_bpermute_b32 v164, v132, v160
	ds_bpermute_b32 v165, v132, v161
	ds_bpermute_b32 v166, v132, v162
	ds_bpermute_b32 v167, v132, v163
	s_waitcnt lgkmcnt(0)
	v_add_f32_e32 v160, v160, v164
	v_add_f32_e32 v161, v161, v165
	v_add_f32_e32 v162, v162, v166
	v_add_f32_e32 v163, v163, v167
	ds_bpermute_b32 v164, v133, v160
	ds_bpermute_b32 v165, v133, v161
	ds_bpermute_b32 v166, v133, v162
	ds_bpermute_b32 v167, v133, v163
	s_waitcnt lgkmcnt(0)
	v_add_f32_e32 v160, v160, v164
	v_add_f32_e32 v161, v161, v165
	v_add_f32_e32 v162, v162, v166
	v_add_f32_e32 v163, v163, v167
	ds_bpermute_b32 v164, v134, v160
	ds_bpermute_b32 v165, v134, v161
	ds_bpermute_b32 v166, v134, v162
	ds_bpermute_b32 v167, v134, v163
	s_waitcnt lgkmcnt(0)
	v_add_f32_e32 v160, v160, v164
	v_add_f32_e32 v161, v161, v165
	v_add_f32_e32 v162, v162, v166
	v_add_f32_e32 v163, v163, v167
	ds_bpermute_b32 v164, v135, v160
	ds_bpermute_b32 v165, v135, v161
	ds_bpermute_b32 v166, v135, v162
	ds_bpermute_b32 v167, v135, v163
	s_waitcnt lgkmcnt(0)
	v_add_f32_e32 v160, v160, v164
	v_add_f32_e32 v161, v161, v165
	v_add_f32_e32 v162, v162, v166
	v_add_f32_e32 v163, v163, v167
	v_cndmask_b32_e64 v164, 0, v160, s[12:13]
	v_cndmask_b32_e64 v165, 0, v161, s[12:13]
	v_cndmask_b32_e64 v166, 0, v162, s[12:13]
	v_cndmask_b32_e64 v167, 0, v163, s[12:13]
	s_mov_b64 exec, 0xffff
	global_store_dword v186, v164, s[6:7]
	global_store_dword v187, v165, s[6:7]
	global_store_dword v188, v166, s[6:7]
	global_store_dword v189, v167, s[6:7]
	s_mov_b64 exec, -1
	s_add_i32 s6, s3, 0x1000
	s_lshl_b32 s6, s6, 12
	s_add_u32 s4, s18, s6
	s_addc_u32 s5, s19, 0
	global_load_dwordx4 v[66:69], v140, s[4:5] nt
	global_load_dwordx4 v[70:73], v140, s[4:5] offset:1024 nt
	global_load_dwordx4 v[74:77], v140, s[4:5] offset:2048 nt
	global_load_dwordx4 v[78:81], v140, s[4:5] offset:3072 nt
	global_load_dwordx4 v[82:85], v141, s[4:5] nt
	global_load_dwordx4 v[86:89], v141, s[4:5] offset:1024 nt
	global_load_dwordx4 v[90:93], v141, s[4:5] offset:2048 nt
	global_load_dwordx4 v[94:97], v141, s[4:5] offset:3072 nt
	global_load_dwordx4 v[98:101], v142, s[4:5] nt
	global_load_dwordx4 v[102:105], v142, s[4:5] offset:1024 nt
	global_load_dwordx4 v[106:109], v142, s[4:5] offset:2048 nt
	global_load_dwordx4 v[110:113], v142, s[4:5] offset:3072 nt
	global_load_dwordx4 v[114:117], v143, s[4:5] nt
	global_load_dwordx4 v[118:121], v143, s[4:5] offset:1024 nt
	global_load_dwordx4 v[122:125], v143, s[4:5] offset:2048 nt
	global_load_dwordx4 v[126:129], v143, s[4:5] offset:3072 nt
	s_waitcnt vmcnt(36)
	s_add_i32 s6, s3, 0x4000
	s_lshl_b32 s7, s6, 11
	s_add_u32 s10, s40, s7
	s_addc_u32 s11, s41, 0
	s_lshl_b32 s7, s6, 6
	s_add_u32 s6, s40, s7
	s_addc_u32 s7, s41, 0
	s_add_u32 s6, s6, 0x1f800000
	s_addc_u32 s7, s7, 0
	v_mul_f32_e32 v150, v3, v3
	v_mul_f32_e32 v151, v5, v5
	v_fmac_f32_e32 v150, v2, v2
	v_fmac_f32_e32 v151, v4, v4
	v_add_f32_e32 v160, v150, v151
	v_cvt_pk_f16_f32 v170, v2, v3
	v_cvt_pk_f16_f32 v171, v4, v5
	v_mul_f32_e32 v150, v7, v7
	v_mul_f32_e32 v151, v9, v9
	v_fmac_f32_e32 v150, v6, v6
	v_fmac_f32_e32 v151, v8, v8
	v_add_f32_e32 v152, v150, v151
	v_add_f32_e32 v160, v160, v152
	v_cvt_pk_f16_f32 v172, v6, v7
	v_cvt_pk_f16_f32 v173, v8, v9
	v_mul_f32_e32 v150, v11, v11
	v_mul_f32_e32 v151, v13, v13
	v_fmac_f32_e32 v150, v10, v10
	v_fmac_f32_e32 v151, v12, v12
	v_add_f32_e32 v152, v150, v151
	v_add_f32_e32 v160, v160, v152
	v_cvt_pk_f16_f32 v174, v10, v11
	v_cvt_pk_f16_f32 v175, v12, v13
	v_mul_f32_e32 v150, v15, v15
	v_mul_f32_e32 v151, v17, v17
	v_fmac_f32_e32 v150, v14, v14
	v_fmac_f32_e32 v151, v16, v16
	v_add_f32_e32 v152, v150, v151
	v_add_f32_e32 v160, v160, v152
	v_cvt_pk_f16_f32 v176, v14, v15
	v_cvt_pk_f16_f32 v177, v16, v17
	global_store_dwordx2 v144, v[170:171], s[10:11]
	global_store_dwordx2 v144, v[172:173], s[10:11] offset:512
	global_store_dwordx2 v144, v[174:175], s[10:11] offset:1024
	global_store_dwordx2 v144, v[176:177], s[10:11] offset:1536
	v_mul_f32_e32 v150, v19, v19
	v_mul_f32_e32 v151, v21, v21
	v_fmac_f32_e32 v150, v18, v18
	v_fmac_f32_e32 v151, v20, v20
	v_add_f32_e32 v161, v150, v151
	v_cvt_pk_f16_f32 v178, v18, v19
	v_cvt_pk_f16_f32 v179, v20, v21
	v_mul_f32_e32 v150, v23, v23
	v_mul_f32_e32 v151, v25, v25
	v_fmac_f32_e32 v150, v22, v22
	v_fmac_f32_e32 v151, v24, v24
	v_add_f32_e32 v152, v150, v151
	v_add_f32_e32 v161, v161, v152
	v_cvt_pk_f16_f32 v180, v22, v23
	v_cvt_pk_f16_f32 v181, v24, v25
	v_mul_f32_e32 v150, v27, v27
	v_mul_f32_e32 v151, v29, v29
	v_fmac_f32_e32 v150, v26, v26
	v_fmac_f32_e32 v151, v28, v28
	v_add_f32_e32 v152, v150, v151
	v_add_f32_e32 v161, v161, v152
	v_cvt_pk_f16_f32 v182, v26, v27
	v_cvt_pk_f16_f32 v183, v28, v29
	v_mul_f32_e32 v150, v31, v31
	v_mul_f32_e32 v151, v33, v33
	v_fmac_f32_e32 v150, v30, v30
	v_fmac_f32_e32 v151, v32, v32
	v_add_f32_e32 v152, v150, v151
	v_add_f32_e32 v161, v161, v152
	v_cvt_pk_f16_f32 v184, v30, v31
	v_cvt_pk_f16_f32 v185, v32, v33
	global_store_dwordx2 v145, v[178:179], s[10:11]
	global_store_dwordx2 v145, v[180:181], s[10:11] offset:512
	global_store_dwordx2 v145, v[182:183], s[10:11] offset:1024
	global_store_dwordx2 v145, v[184:185], s[10:11] offset:1536
	v_mul_f32_e32 v150, v35, v35
	v_mul_f32_e32 v151, v37, v37
	v_fmac_f32_e32 v150, v34, v34
	v_fmac_f32_e32 v151, v36, v36
	v_add_f32_e32 v162, v150, v151
	v_cvt_pk_f16_f32 v170, v34, v35
	v_cvt_pk_f16_f32 v171, v36, v37
	v_mul_f32_e32 v150, v39, v39
	v_mul_f32_e32 v151, v41, v41
	v_fmac_f32_e32 v150, v38, v38
	v_fmac_f32_e32 v151, v40, v40
	v_add_f32_e32 v152, v150, v151
; __device__ void p0_xconv(const Args& a) {
;     ...
;     for (int row0 = (int)blockIdx.x * 8 + wv; row0 < MROWS; row0 += 4 * nwv) {
;         f32x4 v[4][4];
; #pragma unroll
;         for (int r = 0; r < 4; ++r) {
;             const int row = row0 + r * nwv;
;             if (row < MROWS) {
;                 const float* src = (row < ROWS_PROMPT) ? a.x_prompt + (size_t)row * DM : a.x_sample + (size_t)(row - ROWS_PROMPT) * DM;
; #pragma unroll
;                 for (int i = 0; i < 4; ++i) v[r][i] = __builtin_nontemporal_load((const f32x4*)(src + i * 256 + lane * 4));
;             }
;         }
; #pragma unroll
;         for (int r = 0; r < 4; ++r) {
;             const int row = row0 + r * nwv;
;             if (row < MROWS) {
;                 float ss = 0.f;
; #pragma unroll
;                 for (int i = 0; i < 4; ++i) {
;                     const f32x4 x = v[r][i];
;                     ss += (x[0] * x[0] + x[1] * x[1]) + (x[2] * x[2] + x[3] * x[3]);
;                     f16x4 h; h[0] = (f16)x[0]; h[1] = (f16)x[1]; h[2] = (f16)x[2]; h[3] = (f16)x[3];
;                     *(f16x4*)(XH + (size_t)row * DM + i * 256 + lane * 4) = h;
;                 }
; #pragma unroll
;                 for (int o = 1; o < 64; o <<= 1) ss += __shfl_xor(ss, o);
;                 if (lane < 16) SS[(size_t)row * 16 + lane] = (lane == 0) ? ss : 0.f;
	v_add_f32_e32 v162, v162, v152
	v_cvt_pk_f16_f32 v172, v38, v39
	v_cvt_pk_f16_f32 v173, v40, v41
	v_mul_f32_e32 v150, v43, v43
	v_mul_f32_e32 v151, v45, v45
	v_fmac_f32_e32 v150, v42, v42
	v_fmac_f32_e32 v151, v44, v44
	v_add_f32_e32 v152, v150, v151
	v_add_f32_e32 v162, v162, v152
	v_cvt_pk_f16_f32 v174, v42, v43
	v_cvt_pk_f16_f32 v175, v44, v45
	v_mul_f32_e32 v150, v47, v47
	v_mul_f32_e32 v151, v49, v49
	v_fmac_f32_e32 v150, v46, v46
	v_fmac_f32_e32 v151, v48, v48
	v_add_f32_e32 v152, v150, v151
	v_add_f32_e32 v162, v162, v152
	v_cvt_pk_f16_f32 v176, v46, v47
	v_cvt_pk_f16_f32 v177, v48, v49
	global_store_dwordx2 v146, v[170:171], s[10:11]
	global_store_dwordx2 v146, v[172:173], s[10:11] offset:512
	global_store_dwordx2 v146, v[174:175], s[10:11] offset:1024
	global_store_dwordx2 v146, v[176:177], s[10:11] offset:1536
	v_mul_f32_e32 v150, v51, v51
	v_mul_f32_e32 v151, v53, v53
	v_fmac_f32_e32 v150, v50, v50
	v_fmac_f32_e32 v151, v52, v52
	v_add_f32_e32 v163, v150, v151
	v_cvt_pk_f16_f32 v178, v50, v51
	v_cvt_pk_f16_f32 v179, v52, v53
	v_mul_f32_e32 v150, v55, v55
	v_mul_f32_e32 v151, v57, v57
	v_fmac_f32_e32 v150, v54, v54
	v_fmac_f32_e32 v151, v56, v56
	v_add_f32_e32 v152, v150, v151
	v_add_f32_e32 v163, v163, v152
	v_cvt_pk_f16_f32 v180, v54, v55
	v_cvt_pk_f16_f32 v181, v56, v57
	v_mul_f32_e32 v150, v59, v59
	v_mul_f32_e32 v151, v61, v61
	v_fmac_f32_e32 v150, v58, v58
	v_fmac_f32_e32 v151, v60, v60
	v_add_f32_e32 v152, v150, v151
	v_add_f32_e32 v163, v163, v152
	v_cvt_pk_f16_f32 v182, v58, v59
	v_cvt_pk_f16_f32 v183, v60, v61
	v_mul_f32_e32 v150, v63, v63
	v_mul_f32_e32 v151, v65, v65
	v_fmac_f32_e32 v150, v62, v62
	v_fmac_f32_e32 v151, v64, v64
	v_add_f32_e32 v152, v150, v151
	v_add_f32_e32 v163, v163, v152
	v_cvt_pk_f16_f32 v184, v62, v63
	v_cvt_pk_f16_f32 v185, v64, v65
	global_store_dwordx2 v147, v[178:179], s[10:11]
	global_store_dwordx2 v147, v[180:181], s[10:11] offset:512
	global_store_dwordx2 v147, v[182:183], s[10:11] offset:1024
	global_store_dwordx2 v147, v[184:185], s[10:11] offset:1536
	ds_bpermute_b32 v164, v130, v160
	ds_bpermute_b32 v165, v130, v161
	ds_bpermute_b32 v166, v130, v162
	ds_bpermute_b32 v167, v130, v163
	s_waitcnt lgkmcnt(0)
	v_add_f32_e32 v160, v160, v164
	v_add_f32_e32 v161, v161, v165
	v_add_f32_e32 v162, v162, v166
	v_add_f32_e32 v163, v163, v167
	ds_bpermute_b32 v164, v131, v160
	ds_bpermute_b32 v165, v131, v161
	ds_bpermute_b32 v166, v131, v162
	ds_bpermute_b32 v167, v131, v163
	s_waitcnt lgkmcnt(0)
	v_add_f32_e32 v160, v160, v164
	v_add_f32_e32 v161, v161, v165
	v_add_f32_e32 v162, v162, v166
	v_add_f32_e32 v163, v163, v167
	ds_bpermute_b32 v164, v132, v160
	ds_bpermute_b32 v165, v132, v161
	ds_bpermute_b32 v166, v132, v162
	ds_bpermute_b32 v167, v132, v163
	s_waitcnt lgkmcnt(0)
	v_add_f32_e32 v160, v160, v164
	v_add_f32_e32 v161, v161, v165
	v_add_f32_e32 v162, v162, v166
	v_add_f32_e32 v163, v163, v167
	ds_bpermute_b32 v164, v133, v160
	ds_bpermute_b32 v165, v133, v161
	ds_bpermute_b32 v166, v133, v162
	ds_bpermute_b32 v167, v133, v163
	s_waitcnt lgkmcnt(0)
	v_add_f32_e32 v160, v160, v164
	v_add_f32_e32 v161, v161, v165
	v_add_f32_e32 v162, v162, v166
	v_add_f32_e32 v163, v163, v167
	ds_bpermute_b32 v164, v134, v160
	ds_bpermute_b32 v165, v134, v161
	ds_bpermute_b32 v166, v134, v162
	ds_bpermute_b32 v167, v134, v163
	s_waitcnt lgkmcnt(0)
	v_add_f32_e32 v160, v160, v164
	v_add_f32_e32 v161, v161, v165
	v_add_f32_e32 v162, v162, v166
	v_add_f32_e32 v163, v163, v167
	ds_bpermute_b32 v164, v135, v160
	ds_bpermute_b32 v165, v135, v161
	ds_bpermute_b32 v166, v135, v162
	ds_bpermute_b32 v167, v135, v163
	s_waitcnt lgkmcnt(0)
	v_add_f32_e32 v160, v160, v164
	v_add_f32_e32 v161, v161, v165
	v_add_f32_e32 v162, v162, v166
	v_add_f32_e32 v163, v163, v167
	v_cndmask_b32_e64 v164, 0, v160, s[12:13]
	v_cndmask_b32_e64 v165, 0, v161, s[12:13]
	v_cndmask_b32_e64 v166, 0, v162, s[12:13]
	v_cndmask_b32_e64 v167, 0, v163, s[12:13]
	s_mov_b64 exec, 0xffff
	global_store_dword v186, v164, s[6:7]
	global_store_dword v187, v165, s[6:7]
	global_store_dword v188, v166, s[6:7]
	global_store_dword v189, v167, s[6:7]
	s_mov_b64 exec, -1
	s_add_i32 s6, s3, 0x2000
	s_lshl_b32 s6, s6, 12
	s_add_u32 s4, s18, s6
	s_addc_u32 s5, s19, 0
	global_load_dwordx4 v[2:5], v140, s[4:5] nt
	global_load_dwordx4 v[6:9], v140, s[4:5] offset:1024 nt
	global_load_dwordx4 v[10:13], v140, s[4:5] offset:2048 nt
	global_load_dwordx4 v[14:17], v140, s[4:5] offset:3072 nt
	global_load_dwordx4 v[18:21], v141, s[4:5] nt
	global_load_dwordx4 v[22:25], v141, s[4:5] offset:1024 nt
	global_load_dwordx4 v[26:29], v141, s[4:5] offset:2048 nt
	global_load_dwordx4 v[30:33], v141, s[4:5] offset:3072 nt
	global_load_dwordx4 v[34:37], v142, s[4:5] nt
	global_load_dwordx4 v[38:41], v142, s[4:5] offset:1024 nt
	global_load_dwordx4 v[42:45], v142, s[4:5] offset:2048 nt
	global_load_dwordx4 v[46:49], v142, s[4:5] offset:3072 nt
	global_load_dwordx4 v[50:53], v143, s[4:5] nt
	global_load_dwordx4 v[54:57], v143, s[4:5] offset:1024 nt
	global_load_dwordx4 v[58:61], v143, s[4:5] offset:2048 nt
	global_load_dwordx4 v[62:65], v143, s[4:5] offset:3072 nt
	s_waitcnt vmcnt(36)
; __device__ void p0_xconv(const Args& a) {
;     ...
;         for (int r = 0; r < 4; ++r) {
;             const int row = row0 + r * nwv;
;             if (row < MROWS) {
;                 float ss = 0.f;
; #pragma unroll
;                 for (int i = 0; i < 4; ++i) {
;                     const f32x4 x = v[r][i];
;                     ss += (x[0] * x[0] + x[1] * x[1]) + (x[2] * x[2] + x[3] * x[3]);
;                     f16x4 h; h[0] = (f16)x[0]; h[1] = (f16)x[1]; h[2] = (f16)x[2]; h[3] = (f16)x[3];
;                     *(f16x4*)(XH + (size_t)row * DM + i * 256 + lane * 4) = h;
;                 }
; #pragma unroll
;                 for (int o = 1; o < 64; o <<= 1) ss += __shfl_xor(ss, o);
	s_add_i32 s6, s3, 0x5000
	s_lshl_b32 s7, s6, 11
	s_add_u32 s10, s40, s7
	s_addc_u32 s11, s41, 0
	s_lshl_b32 s7, s6, 6
	s_add_u32 s6, s40, s7
	s_addc_u32 s7, s41, 0
	s_add_u32 s6, s6, 0x1f800000
	s_addc_u32 s7, s7, 0
	v_mul_f32_e32 v150, v67, v67
	v_mul_f32_e32 v151, v69, v69
	v_fmac_f32_e32 v150, v66, v66
	v_fmac_f32_e32 v151, v68, v68
	v_add_f32_e32 v160, v150, v151
	v_cvt_pk_f16_f32 v170, v66, v67
	v_cvt_pk_f16_f32 v171, v68, v69
	v_mul_f32_e32 v150, v71, v71
	v_mul_f32_e32 v151, v73, v73
	v_fmac_f32_e32 v150, v70, v70
	v_fmac_f32_e32 v151, v72, v72
	v_add_f32_e32 v152, v150, v151
	v_add_f32_e32 v160, v160, v152
	v_cvt_pk_f16_f32 v172, v70, v71
	v_cvt_pk_f16_f32 v173, v72, v73
	v_mul_f32_e32 v150, v75, v75
	v_mul_f32_e32 v151, v77, v77
	v_fmac_f32_e32 v150, v74, v74
	v_fmac_f32_e32 v151, v76, v76
	v_add_f32_e32 v152, v150, v151
	v_add_f32_e32 v160, v160, v152
	v_cvt_pk_f16_f32 v174, v74, v75
	v_cvt_pk_f16_f32 v175, v76, v77
	v_mul_f32_e32 v150, v79, v79
	v_mul_f32_e32 v151, v81, v81
	v_fmac_f32_e32 v150, v78, v78
	v_fmac_f32_e32 v151, v80, v80
	v_add_f32_e32 v152, v150, v151
	v_add_f32_e32 v160, v160, v152
	v_cvt_pk_f16_f32 v176, v78, v79
	v_cvt_pk_f16_f32 v177, v80, v81
	global_store_dwordx2 v144, v[170:171], s[10:11]
	global_store_dwordx2 v144, v[172:173], s[10:11] offset:512
	global_store_dwordx2 v144, v[174:175], s[10:11] offset:1024
	global_store_dwordx2 v144, v[176:177], s[10:11] offset:1536
	v_mul_f32_e32 v150, v83, v83
	v_mul_f32_e32 v151, v85, v85
	v_fmac_f32_e32 v150, v82, v82
	v_fmac_f32_e32 v151, v84, v84
	v_add_f32_e32 v161, v150, v151
	v_cvt_pk_f16_f32 v178, v82, v83
	v_cvt_pk_f16_f32 v179, v84, v85
	v_mul_f32_e32 v150, v87, v87
	v_mul_f32_e32 v151, v89, v89
	v_fmac_f32_e32 v150, v86, v86
	v_fmac_f32_e32 v151, v88, v88
	v_add_f32_e32 v152, v150, v151
	v_add_f32_e32 v161, v161, v152
	v_cvt_pk_f16_f32 v180, v86, v87
	v_cvt_pk_f16_f32 v181, v88, v89
	v_mul_f32_e32 v150, v91, v91
	v_mul_f32_e32 v151, v93, v93
	v_fmac_f32_e32 v150, v90, v90
	v_fmac_f32_e32 v151, v92, v92
	v_add_f32_e32 v152, v150, v151
	v_add_f32_e32 v161, v161, v152
	v_cvt_pk_f16_f32 v182, v90, v91
	v_cvt_pk_f16_f32 v183, v92, v93
	v_mul_f32_e32 v150, v95, v95
	v_mul_f32_e32 v151, v97, v97
	v_fmac_f32_e32 v150, v94, v94
	v_fmac_f32_e32 v151, v96, v96
	v_add_f32_e32 v152, v150, v151
	v_add_f32_e32 v161, v161, v152
	v_cvt_pk_f16_f32 v184, v94, v95
	v_cvt_pk_f16_f32 v185, v96, v97
	global_store_dwordx2 v145, v[178:179], s[10:11]
	global_store_dwordx2 v145, v[180:181], s[10:11] offset:512
	global_store_dwordx2 v145, v[182:183], s[10:11] offset:1024
	global_store_dwordx2 v145, v[184:185], s[10:11] offset:1536
	v_mul_f32_e32 v150, v99, v99
	v_mul_f32_e32 v151, v101, v101
	v_fmac_f32_e32 v150, v98, v98
	v_fmac_f32_e32 v151, v100, v100
	v_add_f32_e32 v162, v150, v151
	v_cvt_pk_f16_f32 v170, v98, v99
	v_cvt_pk_f16_f32 v171, v100, v101
	v_mul_f32_e32 v150, v103, v103
	v_mul_f32_e32 v151, v105, v105
	v_fmac_f32_e32 v150, v102, v102
	v_fmac_f32_e32 v151, v104, v104
	v_add_f32_e32 v152, v150, v151
	v_add_f32_e32 v162, v162, v152
	v_cvt_pk_f16_f32 v172, v102, v103
	v_cvt_pk_f16_f32 v173, v104, v105
	v_mul_f32_e32 v150, v107, v107
	v_mul_f32_e32 v151, v109, v109
	v_fmac_f32_e32 v150, v106, v106
	v_fmac_f32_e32 v151, v108, v108
	v_add_f32_e32 v152, v150, v151
	v_add_f32_e32 v162, v162, v152
	v_cvt_pk_f16_f32 v174, v106, v107
	v_cvt_pk_f16_f32 v175, v108, v109
	v_mul_f32_e32 v150, v111, v111
	v_mul_f32_e32 v151, v113, v113
	v_fmac_f32_e32 v150, v110, v110
	v_fmac_f32_e32 v151, v112, v112
	v_add_f32_e32 v152, v150, v151
	v_add_f32_e32 v162, v162, v152
	v_cvt_pk_f16_f32 v176, v110, v111
	v_cvt_pk_f16_f32 v177, v112, v113
	global_store_dwordx2 v146, v[170:171], s[10:11]
	global_store_dwordx2 v146, v[172:173], s[10:11] offset:512
	global_store_dwordx2 v146, v[174:175], s[10:11] offset:1024
	global_store_dwordx2 v146, v[176:177], s[10:11] offset:1536
	v_mul_f32_e32 v150, v115, v115
	v_mul_f32_e32 v151, v117, v117
	v_fmac_f32_e32 v150, v114, v114
	v_fmac_f32_e32 v151, v116, v116
	v_add_f32_e32 v163, v150, v151
	v_cvt_pk_f16_f32 v178, v114, v115
	v_cvt_pk_f16_f32 v179, v116, v117
	v_mul_f32_e32 v150, v119, v119
	v_mul_f32_e32 v151, v121, v121
	v_fmac_f32_e32 v150, v118, v118
	v_fmac_f32_e32 v151, v120, v120
	v_add_f32_e32 v152, v150, v151
	v_add_f32_e32 v163, v163, v152
	v_cvt_pk_f16_f32 v180, v118, v119
	v_cvt_pk_f16_f32 v181, v120, v121
	v_mul_f32_e32 v150, v123, v123
	v_mul_f32_e32 v151, v125, v125
	v_fmac_f32_e32 v150, v122, v122
	v_fmac_f32_e32 v151, v124, v124
	v_add_f32_e32 v152, v150, v151
	v_add_f32_e32 v163, v163, v152
	v_cvt_pk_f16_f32 v182, v122, v123
	v_cvt_pk_f16_f32 v183, v124, v125
	v_mul_f32_e32 v150, v127, v127
	v_mul_f32_e32 v151, v129, v129
	v_fmac_f32_e32 v150, v126, v126
	v_fmac_f32_e32 v151, v128, v128
	v_add_f32_e32 v152, v150, v151
	v_add_f32_e32 v163, v163, v152
	v_cvt_pk_f16_f32 v184, v126, v127
	v_cvt_pk_f16_f32 v185, v128, v129
	global_store_dwordx2 v147, v[178:179], s[10:11]
	global_store_dwordx2 v147, v[180:181], s[10:11] offset:512
	global_store_dwordx2 v147, v[182:183], s[10:11] offset:1024
	global_store_dwordx2 v147, v[184:185], s[10:11] offset:1536
	ds_bpermute_b32 v164, v130, v160
	ds_bpermute_b32 v165, v130, v161
	ds_bpermute_b32 v166, v130, v162
	ds_bpermute_b32 v167, v130, v163
	s_waitcnt lgkmcnt(0)
	v_add_f32_e32 v160, v160, v164
	v_add_f32_e32 v161, v161, v165
	v_add_f32_e32 v162, v162, v166
	v_add_f32_e32 v163, v163, v167
	ds_bpermute_b32 v164, v131, v160
	ds_bpermute_b32 v165, v131, v161
	ds_bpermute_b32 v166, v131, v162
	ds_bpermute_b32 v167, v131, v163
	s_waitcnt lgkmcnt(0)
; __device__ void p0_xconv(const Args& a) {
;     ...
;         for (int r = 0; r < 4; ++r) {
;             const int row = row0 + r * nwv;
;             if (row < MROWS) {
;                 const float* src = (row < ROWS_PROMPT) ? a.x_prompt + (size_t)row * DM : a.x_sample + (size_t)(row - ROWS_PROMPT) * DM;
; #pragma unroll
;                 for (int i = 0; i < 4; ++i) v[r][i] = __builtin_nontemporal_load((const f32x4*)(src + i * 256 + lane * 4));
;             }
;         }
; #pragma unroll
;         for (int r = 0; r < 4; ++r) {
;             const int row = row0 + r * nwv;
;             if (row < MROWS) {
;                 float ss = 0.f;
; #pragma unroll
;                 for (int i = 0; i < 4; ++i) {
;                     const f32x4 x = v[r][i];
;                     ss += (x[0] * x[0] + x[1] * x[1]) + (x[2] * x[2] + x[3] * x[3]);
;                     f16x4 h; h[0] = (f16)x[0]; h[1] = (f16)x[1]; h[2] = (f16)x[2]; h[3] = (f16)x[3];
;                     *(f16x4*)(XH + (size_t)row * DM + i * 256 + lane * 4) = h;
;                 }
; #pragma unroll
;                 for (int o = 1; o < 64; o <<= 1) ss += __shfl_xor(ss, o);
;                 if (lane < 16) SS[(size_t)row * 16 + lane] = (lane == 0) ? ss : 0.f;
;             }
	v_add_f32_e32 v160, v160, v164
	v_add_f32_e32 v161, v161, v165
	v_add_f32_e32 v162, v162, v166
	v_add_f32_e32 v163, v163, v167
	ds_bpermute_b32 v164, v132, v160
	ds_bpermute_b32 v165, v132, v161
	ds_bpermute_b32 v166, v132, v162
	ds_bpermute_b32 v167, v132, v163
	s_waitcnt lgkmcnt(0)
	v_add_f32_e32 v160, v160, v164
	v_add_f32_e32 v161, v161, v165
	v_add_f32_e32 v162, v162, v166
	v_add_f32_e32 v163, v163, v167
	ds_bpermute_b32 v164, v133, v160
	ds_bpermute_b32 v165, v133, v161
	ds_bpermute_b32 v166, v133, v162
	ds_bpermute_b32 v167, v133, v163
	s_waitcnt lgkmcnt(0)
	v_add_f32_e32 v160, v160, v164
	v_add_f32_e32 v161, v161, v165
	v_add_f32_e32 v162, v162, v166
	v_add_f32_e32 v163, v163, v167
	ds_bpermute_b32 v164, v134, v160
	ds_bpermute_b32 v165, v134, v161
	ds_bpermute_b32 v166, v134, v162
	ds_bpermute_b32 v167, v134, v163
	s_waitcnt lgkmcnt(0)
	v_add_f32_e32 v160, v160, v164
	v_add_f32_e32 v161, v161, v165
	v_add_f32_e32 v162, v162, v166
	v_add_f32_e32 v163, v163, v167
	ds_bpermute_b32 v164, v135, v160
	ds_bpermute_b32 v165, v135, v161
	ds_bpermute_b32 v166, v135, v162
	ds_bpermute_b32 v167, v135, v163
	s_waitcnt lgkmcnt(0)
	v_add_f32_e32 v160, v160, v164
	v_add_f32_e32 v161, v161, v165
	v_add_f32_e32 v162, v162, v166
	v_add_f32_e32 v163, v163, v167
	v_cndmask_b32_e64 v164, 0, v160, s[12:13]
	v_cndmask_b32_e64 v165, 0, v161, s[12:13]
	v_cndmask_b32_e64 v166, 0, v162, s[12:13]
	v_cndmask_b32_e64 v167, 0, v163, s[12:13]
	s_mov_b64 exec, 0xffff
	global_store_dword v186, v164, s[6:7]
	global_store_dword v187, v165, s[6:7]
	global_store_dword v188, v166, s[6:7]
	global_store_dword v189, v167, s[6:7]
	s_mov_b64 exec, -1
	s_add_i32 s6, s3, 0x3000
	s_lshl_b32 s6, s6, 12
	s_add_u32 s4, s18, s6
	s_addc_u32 s5, s19, 0
	global_load_dwordx4 v[66:69], v140, s[4:5] nt
	global_load_dwordx4 v[70:73], v140, s[4:5] offset:1024 nt
	global_load_dwordx4 v[74:77], v140, s[4:5] offset:2048 nt
	global_load_dwordx4 v[78:81], v140, s[4:5] offset:3072 nt
	global_load_dwordx4 v[82:85], v141, s[4:5] nt
	global_load_dwordx4 v[86:89], v141, s[4:5] offset:1024 nt
	global_load_dwordx4 v[90:93], v141, s[4:5] offset:2048 nt
	global_load_dwordx4 v[94:97], v141, s[4:5] offset:3072 nt
	global_load_dwordx4 v[98:101], v142, s[4:5] nt
	global_load_dwordx4 v[102:105], v142, s[4:5] offset:1024 nt
	global_load_dwordx4 v[106:109], v142, s[4:5] offset:2048 nt
	global_load_dwordx4 v[110:113], v142, s[4:5] offset:3072 nt
	global_load_dwordx4 v[114:117], v143, s[4:5] nt
	global_load_dwordx4 v[118:121], v143, s[4:5] offset:1024 nt
	global_load_dwordx4 v[122:125], v143, s[4:5] offset:2048 nt
	global_load_dwordx4 v[126:129], v143, s[4:5] offset:3072 nt
	s_waitcnt vmcnt(36)
	s_add_i32 s6, s3, 0x6000
	s_lshl_b32 s7, s6, 11
	s_add_u32 s10, s40, s7
	s_addc_u32 s11, s41, 0
	s_lshl_b32 s7, s6, 6
	s_add_u32 s6, s40, s7
	s_addc_u32 s7, s41, 0
	s_add_u32 s6, s6, 0x1f800000
	s_addc_u32 s7, s7, 0
	v_mul_f32_e32 v150, v3, v3
	v_mul_f32_e32 v151, v5, v5
	v_fmac_f32_e32 v150, v2, v2
	v_fmac_f32_e32 v151, v4, v4
	v_add_f32_e32 v160, v150, v151
	v_cvt_pk_f16_f32 v170, v2, v3
	v_cvt_pk_f16_f32 v171, v4, v5
	v_mul_f32_e32 v150, v7, v7
	v_mul_f32_e32 v151, v9, v9
	v_fmac_f32_e32 v150, v6, v6
	v_fmac_f32_e32 v151, v8, v8
	v_add_f32_e32 v152, v150, v151
	v_add_f32_e32 v160, v160, v152
	v_cvt_pk_f16_f32 v172, v6, v7
	v_cvt_pk_f16_f32 v173, v8, v9
	v_mul_f32_e32 v150, v11, v11
	v_mul_f32_e32 v151, v13, v13
	v_fmac_f32_e32 v150, v10, v10
	v_fmac_f32_e32 v151, v12, v12
	v_add_f32_e32 v152, v150, v151
	v_add_f32_e32 v160, v160, v152
	v_cvt_pk_f16_f32 v174, v10, v11
	v_cvt_pk_f16_f32 v175, v12, v13
	v_mul_f32_e32 v150, v15, v15
	v_mul_f32_e32 v151, v17, v17
	v_fmac_f32_e32 v150, v14, v14
	v_fmac_f32_e32 v151, v16, v16
	v_add_f32_e32 v152, v150, v151
	v_add_f32_e32 v160, v160, v152
	v_cvt_pk_f16_f32 v176, v14, v15
	v_cvt_pk_f16_f32 v177, v16, v17
	global_store_dwordx2 v144, v[170:171], s[10:11]
	global_store_dwordx2 v144, v[172:173], s[10:11] offset:512
	global_store_dwordx2 v144, v[174:175], s[10:11] offset:1024
	global_store_dwordx2 v144, v[176:177], s[10:11] offset:1536
	v_mul_f32_e32 v150, v19, v19
	v_mul_f32_e32 v151, v21, v21
	v_fmac_f32_e32 v150, v18, v18
	v_fmac_f32_e32 v151, v20, v20
	v_add_f32_e32 v161, v150, v151
	v_cvt_pk_f16_f32 v178, v18, v19
	v_cvt_pk_f16_f32 v179, v20, v21
	v_mul_f32_e32 v150, v23, v23
	v_mul_f32_e32 v151, v25, v25
	v_fmac_f32_e32 v150, v22, v22
	v_fmac_f32_e32 v151, v24, v24
	v_add_f32_e32 v152, v150, v151
	v_add_f32_e32 v161, v161, v152
	v_cvt_pk_f16_f32 v180, v22, v23
	v_cvt_pk_f16_f32 v181, v24, v25
	v_mul_f32_e32 v150, v27, v27
	v_mul_f32_e32 v151, v29, v29
	v_fmac_f32_e32 v150, v26, v26
	v_fmac_f32_e32 v151, v28, v28
	v_add_f32_e32 v152, v150, v151
	v_add_f32_e32 v161, v161, v152
	v_cvt_pk_f16_f32 v182, v26, v27
	v_cvt_pk_f16_f32 v183, v28, v29
	v_mul_f32_e32 v150, v31, v31
	v_mul_f32_e32 v151, v33, v33
	v_fmac_f32_e32 v150, v30, v30
	v_fmac_f32_e32 v151, v32, v32
	v_add_f32_e32 v152, v150, v151
	v_add_f32_e32 v161, v161, v152
	v_cvt_pk_f16_f32 v184, v30, v31
	v_cvt_pk_f16_f32 v185, v32, v33
	global_store_dwordx2 v145, v[178:179], s[10:11]
	global_store_dwordx2 v145, v[180:181], s[10:11] offset:512
	global_store_dwordx2 v145, v[182:183], s[10:11] offset:1024
	global_store_dwordx2 v145, v[184:185], s[10:11] offset:1536
	v_mul_f32_e32 v150, v35, v35
	v_mul_f32_e32 v151, v37, v37
	v_fmac_f32_e32 v150, v34, v34
	v_fmac_f32_e32 v151, v36, v36
	v_add_f32_e32 v162, v150, v151
	v_cvt_pk_f16_f32 v170, v34, v35
	v_cvt_pk_f16_f32 v171, v36, v37
	v_mul_f32_e32 v150, v39, v39
	v_mul_f32_e32 v151, v41, v41
	v_fmac_f32_e32 v150, v38, v38
	v_fmac_f32_e32 v151, v40, v40
	v_add_f32_e32 v152, v150, v151
; __device__ void p0_xconv(const Args& a) {
;     ...
;         for (int r = 0; r < 4; ++r) {
;             const int row = row0 + r * nwv;
;             if (row < MROWS) {
;                 const float* src = (row < ROWS_PROMPT) ? a.x_prompt + (size_t)row * DM : a.x_sample + (size_t)(row - ROWS_PROMPT) * DM;
; #pragma unroll
;                 for (int i = 0; i < 4; ++i) v[r][i] = __builtin_nontemporal_load((const f32x4*)(src + i * 256 + lane * 4));
;             }
;         }
; #pragma unroll
;         for (int r = 0; r < 4; ++r) {
;             const int row = row0 + r * nwv;
;             if (row < MROWS) {
;                 float ss = 0.f;
; #pragma unroll
;                 for (int i = 0; i < 4; ++i) {
;                     const f32x4 x = v[r][i];
;                     ss += (x[0] * x[0] + x[1] * x[1]) + (x[2] * x[2] + x[3] * x[3]);
;                     f16x4 h; h[0] = (f16)x[0]; h[1] = (f16)x[1]; h[2] = (f16)x[2]; h[3] = (f16)x[3];
;                     *(f16x4*)(XH + (size_t)row * DM + i * 256 + lane * 4) = h;
;                 }
; #pragma unroll
;                 for (int o = 1; o < 64; o <<= 1) ss += __shfl_xor(ss, o);
;                 if (lane < 16) SS[(size_t)row * 16 + lane] = (lane == 0) ? ss : 0.f;
;             }
	v_add_f32_e32 v162, v162, v152
	v_cvt_pk_f16_f32 v172, v38, v39
	v_cvt_pk_f16_f32 v173, v40, v41
	v_mul_f32_e32 v150, v43, v43
	v_mul_f32_e32 v151, v45, v45
	v_fmac_f32_e32 v150, v42, v42
	v_fmac_f32_e32 v151, v44, v44
	v_add_f32_e32 v152, v150, v151
	v_add_f32_e32 v162, v162, v152
	v_cvt_pk_f16_f32 v174, v42, v43
	v_cvt_pk_f16_f32 v175, v44, v45
	v_mul_f32_e32 v150, v47, v47
	v_mul_f32_e32 v151, v49, v49
	v_fmac_f32_e32 v150, v46, v46
	v_fmac_f32_e32 v151, v48, v48
	v_add_f32_e32 v152, v150, v151
	v_add_f32_e32 v162, v162, v152
	v_cvt_pk_f16_f32 v176, v46, v47
	v_cvt_pk_f16_f32 v177, v48, v49
	global_store_dwordx2 v146, v[170:171], s[10:11]
	global_store_dwordx2 v146, v[172:173], s[10:11] offset:512
	global_store_dwordx2 v146, v[174:175], s[10:11] offset:1024
	global_store_dwordx2 v146, v[176:177], s[10:11] offset:1536
	v_mul_f32_e32 v150, v51, v51
	v_mul_f32_e32 v151, v53, v53
	v_fmac_f32_e32 v150, v50, v50
	v_fmac_f32_e32 v151, v52, v52
	v_add_f32_e32 v163, v150, v151
	v_cvt_pk_f16_f32 v178, v50, v51
	v_cvt_pk_f16_f32 v179, v52, v53
	v_mul_f32_e32 v150, v55, v55
	v_mul_f32_e32 v151, v57, v57
	v_fmac_f32_e32 v150, v54, v54
	v_fmac_f32_e32 v151, v56, v56
	v_add_f32_e32 v152, v150, v151
	v_add_f32_e32 v163, v163, v152
	v_cvt_pk_f16_f32 v180, v54, v55
	v_cvt_pk_f16_f32 v181, v56, v57
	v_mul_f32_e32 v150, v59, v59
	v_mul_f32_e32 v151, v61, v61
	v_fmac_f32_e32 v150, v58, v58
	v_fmac_f32_e32 v151, v60, v60
	v_add_f32_e32 v152, v150, v151
	v_add_f32_e32 v163, v163, v152
	v_cvt_pk_f16_f32 v182, v58, v59
	v_cvt_pk_f16_f32 v183, v60, v61
	v_mul_f32_e32 v150, v63, v63
	v_mul_f32_e32 v151, v65, v65
	v_fmac_f32_e32 v150, v62, v62
	v_fmac_f32_e32 v151, v64, v64
	v_add_f32_e32 v152, v150, v151
	v_add_f32_e32 v163, v163, v152
	v_cvt_pk_f16_f32 v184, v62, v63
	v_cvt_pk_f16_f32 v185, v64, v65
	global_store_dwordx2 v147, v[178:179], s[10:11]
	global_store_dwordx2 v147, v[180:181], s[10:11] offset:512
	global_store_dwordx2 v147, v[182:183], s[10:11] offset:1024
	global_store_dwordx2 v147, v[184:185], s[10:11] offset:1536
	ds_bpermute_b32 v164, v130, v160
	ds_bpermute_b32 v165, v130, v161
	ds_bpermute_b32 v166, v130, v162
	ds_bpermute_b32 v167, v130, v163
	s_waitcnt lgkmcnt(0)
	v_add_f32_e32 v160, v160, v164
	v_add_f32_e32 v161, v161, v165
	v_add_f32_e32 v162, v162, v166
	v_add_f32_e32 v163, v163, v167
	ds_bpermute_b32 v164, v131, v160
	ds_bpermute_b32 v165, v131, v161
	ds_bpermute_b32 v166, v131, v162
	ds_bpermute_b32 v167, v131, v163
	s_waitcnt lgkmcnt(0)
	v_add_f32_e32 v160, v160, v164
	v_add_f32_e32 v161, v161, v165
	v_add_f32_e32 v162, v162, v166
	v_add_f32_e32 v163, v163, v167
	ds_bpermute_b32 v164, v132, v160
	ds_bpermute_b32 v165, v132, v161
	ds_bpermute_b32 v166, v132, v162
	ds_bpermute_b32 v167, v132, v163
	s_waitcnt lgkmcnt(0)
	v_add_f32_e32 v160, v160, v164
	v_add_f32_e32 v161, v161, v165
	v_add_f32_e32 v162, v162, v166
	v_add_f32_e32 v163, v163, v167
	ds_bpermute_b32 v164, v133, v160
	ds_bpermute_b32 v165, v133, v161
	ds_bpermute_b32 v166, v133, v162
	ds_bpermute_b32 v167, v133, v163
	s_waitcnt lgkmcnt(0)
	v_add_f32_e32 v160, v160, v164
	v_add_f32_e32 v161, v161, v165
	v_add_f32_e32 v162, v162, v166
	v_add_f32_e32 v163, v163, v167
	ds_bpermute_b32 v164, v134, v160
	ds_bpermute_b32 v165, v134, v161
	ds_bpermute_b32 v166, v134, v162
	ds_bpermute_b32 v167, v134, v163
	s_waitcnt lgkmcnt(0)
	v_add_f32_e32 v160, v160, v164
	v_add_f32_e32 v161, v161, v165
	v_add_f32_e32 v162, v162, v166
	v_add_f32_e32 v163, v163, v167
	ds_bpermute_b32 v164, v135, v160
	ds_bpermute_b32 v165, v135, v161
	ds_bpermute_b32 v166, v135, v162
	ds_bpermute_b32 v167, v135, v163
	s_waitcnt lgkmcnt(0)
	v_add_f32_e32 v160, v160, v164
	v_add_f32_e32 v161, v161, v165
	v_add_f32_e32 v162, v162, v166
	v_add_f32_e32 v163, v163, v167
	v_cndmask_b32_e64 v164, 0, v160, s[12:13]
	v_cndmask_b32_e64 v165, 0, v161, s[12:13]
	v_cndmask_b32_e64 v166, 0, v162, s[12:13]
	v_cndmask_b32_e64 v167, 0, v163, s[12:13]
	s_mov_b64 exec, 0xffff
	global_store_dword v186, v164, s[6:7]
	global_store_dword v187, v165, s[6:7]
	global_store_dword v188, v166, s[6:7]
	global_store_dword v189, v167, s[6:7]
	s_mov_b64 exec, -1
	s_add_i32 s6, s3, 0x4000
	s_lshl_b32 s6, s6, 12
	s_add_u32 s4, s18, s6
	s_addc_u32 s5, s19, 0
	global_load_dwordx4 v[2:5], v140, s[4:5] nt
	global_load_dwordx4 v[6:9], v140, s[4:5] offset:1024 nt
	global_load_dwordx4 v[10:13], v140, s[4:5] offset:2048 nt
	global_load_dwordx4 v[14:17], v140, s[4:5] offset:3072 nt
	global_load_dwordx4 v[18:21], v141, s[4:5] nt
	global_load_dwordx4 v[22:25], v141, s[4:5] offset:1024 nt
	global_load_dwordx4 v[26:29], v141, s[4:5] offset:2048 nt
	global_load_dwordx4 v[30:33], v141, s[4:5] offset:3072 nt
	global_load_dwordx4 v[34:37], v142, s[4:5] nt
	global_load_dwordx4 v[38:41], v142, s[4:5] offset:1024 nt
	global_load_dwordx4 v[42:45], v142, s[4:5] offset:2048 nt
	global_load_dwordx4 v[46:49], v142, s[4:5] offset:3072 nt
	global_load_dwordx4 v[50:53], v143, s[4:5] nt
	global_load_dwordx4 v[54:57], v143, s[4:5] offset:1024 nt
	global_load_dwordx4 v[58:61], v143, s[4:5] offset:2048 nt
	global_load_dwordx4 v[62:65], v143, s[4:5] offset:3072 nt
	s_waitcnt vmcnt(36)
; __device__ void p0_xconv(const Args& a) {
;     ...
;         for (int r = 0; r < 4; ++r) {
;             const int row = row0 + r * nwv;
;             if (row < MROWS) {
;                 float ss = 0.f;
; #pragma unroll
;                 for (int i = 0; i < 4; ++i) {
;                     const f32x4 x = v[r][i];
;                     ss += (x[0] * x[0] + x[1] * x[1]) + (x[2] * x[2] + x[3] * x[3]);
;                     f16x4 h; h[0] = (f16)x[0]; h[1] = (f16)x[1]; h[2] = (f16)x[2]; h[3] = (f16)x[3];
;                     *(f16x4*)(XH + (size_t)row * DM + i * 256 + lane * 4) = h;
;                 }
; #pragma unroll
;                 for (int o = 1; o < 64; o <<= 1) ss += __shfl_xor(ss, o);
	s_add_i32 s6, s3, 0x7000
	s_lshl_b32 s7, s6, 11
	s_add_u32 s10, s40, s7
	s_addc_u32 s11, s41, 0
	s_lshl_b32 s7, s6, 6
	s_add_u32 s6, s40, s7
	s_addc_u32 s7, s41, 0
	s_add_u32 s6, s6, 0x1f800000
	s_addc_u32 s7, s7, 0
	v_mul_f32_e32 v150, v67, v67
	v_mul_f32_e32 v151, v69, v69
	v_fmac_f32_e32 v150, v66, v66
	v_fmac_f32_e32 v151, v68, v68
	v_add_f32_e32 v160, v150, v151
	v_cvt_pk_f16_f32 v170, v66, v67
	v_cvt_pk_f16_f32 v171, v68, v69
	v_mul_f32_e32 v150, v71, v71
	v_mul_f32_e32 v151, v73, v73
	v_fmac_f32_e32 v150, v70, v70
	v_fmac_f32_e32 v151, v72, v72
	v_add_f32_e32 v152, v150, v151
	v_add_f32_e32 v160, v160, v152
	v_cvt_pk_f16_f32 v172, v70, v71
	v_cvt_pk_f16_f32 v173, v72, v73
	v_mul_f32_e32 v150, v75, v75
	v_mul_f32_e32 v151, v77, v77
	v_fmac_f32_e32 v150, v74, v74
	v_fmac_f32_e32 v151, v76, v76
	v_add_f32_e32 v152, v150, v151
	v_add_f32_e32 v160, v160, v152
	v_cvt_pk_f16_f32 v174, v74, v75
	v_cvt_pk_f16_f32 v175, v76, v77
	v_mul_f32_e32 v150, v79, v79
	v_mul_f32_e32 v151, v81, v81
	v_fmac_f32_e32 v150, v78, v78
	v_fmac_f32_e32 v151, v80, v80
	v_add_f32_e32 v152, v150, v151
	v_add_f32_e32 v160, v160, v152
	v_cvt_pk_f16_f32 v176, v78, v79
	v_cvt_pk_f16_f32 v177, v80, v81
	global_store_dwordx2 v144, v[170:171], s[10:11]
	global_store_dwordx2 v144, v[172:173], s[10:11] offset:512
	global_store_dwordx2 v144, v[174:175], s[10:11] offset:1024
	global_store_dwordx2 v144, v[176:177], s[10:11] offset:1536
	v_mul_f32_e32 v150, v83, v83
	v_mul_f32_e32 v151, v85, v85
	v_fmac_f32_e32 v150, v82, v82
	v_fmac_f32_e32 v151, v84, v84
	v_add_f32_e32 v161, v150, v151
	v_cvt_pk_f16_f32 v178, v82, v83
	v_cvt_pk_f16_f32 v179, v84, v85
	v_mul_f32_e32 v150, v87, v87
	v_mul_f32_e32 v151, v89, v89
	v_fmac_f32_e32 v150, v86, v86
	v_fmac_f32_e32 v151, v88, v88
	v_add_f32_e32 v152, v150, v151
	v_add_f32_e32 v161, v161, v152
	v_cvt_pk_f16_f32 v180, v86, v87
	v_cvt_pk_f16_f32 v181, v88, v89
	v_mul_f32_e32 v150, v91, v91
	v_mul_f32_e32 v151, v93, v93
	v_fmac_f32_e32 v150, v90, v90
	v_fmac_f32_e32 v151, v92, v92
	v_add_f32_e32 v152, v150, v151
	v_add_f32_e32 v161, v161, v152
	v_cvt_pk_f16_f32 v182, v90, v91
	v_cvt_pk_f16_f32 v183, v92, v93
	v_mul_f32_e32 v150, v95, v95
	v_mul_f32_e32 v151, v97, v97
	v_fmac_f32_e32 v150, v94, v94
	v_fmac_f32_e32 v151, v96, v96
	v_add_f32_e32 v152, v150, v151
	v_add_f32_e32 v161, v161, v152
	v_cvt_pk_f16_f32 v184, v94, v95
	v_cvt_pk_f16_f32 v185, v96, v97
	global_store_dwordx2 v145, v[178:179], s[10:11]
	global_store_dwordx2 v145, v[180:181], s[10:11] offset:512
	global_store_dwordx2 v145, v[182:183], s[10:11] offset:1024
	global_store_dwordx2 v145, v[184:185], s[10:11] offset:1536
	v_mul_f32_e32 v150, v99, v99
	v_mul_f32_e32 v151, v101, v101
	v_fmac_f32_e32 v150, v98, v98
	v_fmac_f32_e32 v151, v100, v100
	v_add_f32_e32 v162, v150, v151
	v_cvt_pk_f16_f32 v170, v98, v99
	v_cvt_pk_f16_f32 v171, v100, v101
	v_mul_f32_e32 v150, v103, v103
	v_mul_f32_e32 v151, v105, v105
	v_fmac_f32_e32 v150, v102, v102
	v_fmac_f32_e32 v151, v104, v104
	v_add_f32_e32 v152, v150, v151
	v_add_f32_e32 v162, v162, v152
	v_cvt_pk_f16_f32 v172, v102, v103
	v_cvt_pk_f16_f32 v173, v104, v105
	v_mul_f32_e32 v150, v107, v107
	v_mul_f32_e32 v151, v109, v109
	v_fmac_f32_e32 v150, v106, v106
	v_fmac_f32_e32 v151, v108, v108
	v_add_f32_e32 v152, v150, v151
	v_add_f32_e32 v162, v162, v152
	v_cvt_pk_f16_f32 v174, v106, v107
	v_cvt_pk_f16_f32 v175, v108, v109
	v_mul_f32_e32 v150, v111, v111
	v_mul_f32_e32 v151, v113, v113
	v_fmac_f32_e32 v150, v110, v110
	v_fmac_f32_e32 v151, v112, v112
	v_add_f32_e32 v152, v150, v151
	v_add_f32_e32 v162, v162, v152
	v_cvt_pk_f16_f32 v176, v110, v111
	v_cvt_pk_f16_f32 v177, v112, v113
	global_store_dwordx2 v146, v[170:171], s[10:11]
	global_store_dwordx2 v146, v[172:173], s[10:11] offset:512
	global_store_dwordx2 v146, v[174:175], s[10:11] offset:1024
	global_store_dwordx2 v146, v[176:177], s[10:11] offset:1536
	v_mul_f32_e32 v150, v115, v115
	v_mul_f32_e32 v151, v117, v117
	v_fmac_f32_e32 v150, v114, v114
	v_fmac_f32_e32 v151, v116, v116
	v_add_f32_e32 v163, v150, v151
	v_cvt_pk_f16_f32 v178, v114, v115
	v_cvt_pk_f16_f32 v179, v116, v117
	v_mul_f32_e32 v150, v119, v119
	v_mul_f32_e32 v151, v121, v121
	v_fmac_f32_e32 v150, v118, v118
	v_fmac_f32_e32 v151, v120, v120
	v_add_f32_e32 v152, v150, v151
	v_add_f32_e32 v163, v163, v152
	v_cvt_pk_f16_f32 v180, v118, v119
	v_cvt_pk_f16_f32 v181, v120, v121
	v_mul_f32_e32 v150, v123, v123
	v_mul_f32_e32 v151, v125, v125
	v_fmac_f32_e32 v150, v122, v122
	v_fmac_f32_e32 v151, v124, v124
	v_add_f32_e32 v152, v150, v151
	v_add_f32_e32 v163, v163, v152
	v_cvt_pk_f16_f32 v182, v122, v123
	v_cvt_pk_f16_f32 v183, v124, v125
	v_mul_f32_e32 v150, v127, v127
	v_mul_f32_e32 v151, v129, v129
	v_fmac_f32_e32 v150, v126, v126
	v_fmac_f32_e32 v151, v128, v128
	v_add_f32_e32 v152, v150, v151
	v_add_f32_e32 v163, v163, v152
	v_cvt_pk_f16_f32 v184, v126, v127
	v_cvt_pk_f16_f32 v185, v128, v129
	global_store_dwordx2 v147, v[178:179], s[10:11]
	global_store_dwordx2 v147, v[180:181], s[10:11] offset:512
	global_store_dwordx2 v147, v[182:183], s[10:11] offset:1024
	global_store_dwordx2 v147, v[184:185], s[10:11] offset:1536
	ds_bpermute_b32 v164, v130, v160
	ds_bpermute_b32 v165, v130, v161
	ds_bpermute_b32 v166, v130, v162
	ds_bpermute_b32 v167, v130, v163
	s_waitcnt lgkmcnt(0)
	v_add_f32_e32 v160, v160, v164
	v_add_f32_e32 v161, v161, v165
	v_add_f32_e32 v162, v162, v166
	v_add_f32_e32 v163, v163, v167
	ds_bpermute_b32 v164, v131, v160
	ds_bpermute_b32 v165, v131, v161
	ds_bpermute_b32 v166, v131, v162
	ds_bpermute_b32 v167, v131, v163
	s_waitcnt lgkmcnt(0)
; __device__ void p0_xconv(const Args& a) {
;     ...
;         for (int r = 0; r < 4; ++r) {
;             const int row = row0 + r * nwv;
;             if (row < MROWS) {
;                 const float* src = (row < ROWS_PROMPT) ? a.x_prompt + (size_t)row * DM : a.x_sample + (size_t)(row - ROWS_PROMPT) * DM;
; #pragma unroll
;                 for (int i = 0; i < 4; ++i) v[r][i] = __builtin_nontemporal_load((const f32x4*)(src + i * 256 + lane * 4));
;             }
	v_add_f32_e32 v160, v160, v164
	v_add_f32_e32 v161, v161, v165
	v_add_f32_e32 v162, v162, v166
	v_add_f32_e32 v163, v163, v167
	ds_bpermute_b32 v164, v132, v160
	ds_bpermute_b32 v165, v132, v161
	ds_bpermute_b32 v166, v132, v162
	ds_bpermute_b32 v167, v132, v163
	s_waitcnt lgkmcnt(0)
	v_add_f32_e32 v160, v160, v164
	v_add_f32_e32 v161, v161, v165
	v_add_f32_e32 v162, v162, v166
	v_add_f32_e32 v163, v163, v167
	ds_bpermute_b32 v164, v133, v160
	ds_bpermute_b32 v165, v133, v161
	ds_bpermute_b32 v166, v133, v162
	ds_bpermute_b32 v167, v133, v163
	s_waitcnt lgkmcnt(0)
	v_add_f32_e32 v160, v160, v164
	v_add_f32_e32 v161, v161, v165
	v_add_f32_e32 v162, v162, v166
	v_add_f32_e32 v163, v163, v167
	ds_bpermute_b32 v164, v134, v160
	ds_bpermute_b32 v165, v134, v161
	ds_bpermute_b32 v166, v134, v162
	ds_bpermute_b32 v167, v134, v163
	s_waitcnt lgkmcnt(0)
	v_add_f32_e32 v160, v160, v164
	v_add_f32_e32 v161, v161, v165
	v_add_f32_e32 v162, v162, v166
	v_add_f32_e32 v163, v163, v167
	ds_bpermute_b32 v164, v135, v160
	ds_bpermute_b32 v165, v135, v161
	ds_bpermute_b32 v166, v135, v162
	ds_bpermute_b32 v167, v135, v163
	s_waitcnt lgkmcnt(0)
	v_add_f32_e32 v160, v160, v164
	v_add_f32_e32 v161, v161, v165
	v_add_f32_e32 v162, v162, v166
	v_add_f32_e32 v163, v163, v167
	v_cndmask_b32_e64 v164, 0, v160, s[12:13]
	v_cndmask_b32_e64 v165, 0, v161, s[12:13]
	v_cndmask_b32_e64 v166, 0, v162, s[12:13]
	v_cndmask_b32_e64 v167, 0, v163, s[12:13]
	s_mov_b64 exec, 0xffff
	global_store_dword v186, v164, s[6:7]
	global_store_dword v187, v165, s[6:7]
	global_store_dword v188, v166, s[6:7]
	global_store_dword v189, v167, s[6:7]
	s_mov_b64 exec, -1
	s_add_i32 s6, s9, 0x5000
	s_lshl_b32 s6, s6, 12
	s_add_u32 s4, s18, s6
	s_addc_u32 s5, s19, 0
	global_load_dwordx4 v[66:69], v190, s[4:5] nt
	global_load_dwordx4 v[70:73], v190, s[4:5] offset:1024 nt
	global_load_dwordx4 v[74:77], v190, s[4:5] offset:2048 nt
	global_load_dwordx4 v[78:81], v190, s[4:5] offset:3072 nt
	global_load_dwordx4 v[82:85], v191, s[4:5] nt
	global_load_dwordx4 v[86:89], v191, s[4:5] offset:1024 nt
	global_load_dwordx4 v[90:93], v191, s[4:5] offset:2048 nt
	global_load_dwordx4 v[94:97], v191, s[4:5] offset:3072 nt
	global_load_dwordx4 v[98:101], v192, s[4:5] nt
	global_load_dwordx4 v[102:105], v192, s[4:5] offset:1024 nt
	global_load_dwordx4 v[106:109], v192, s[4:5] offset:2048 nt
	global_load_dwordx4 v[110:113], v192, s[4:5] offset:3072 nt
	global_load_dwordx4 v[114:117], v193, s[4:5] nt
	global_load_dwordx4 v[118:121], v193, s[4:5] offset:1024 nt
	global_load_dwordx4 v[122:125], v193, s[4:5] offset:2048 nt
	global_load_dwordx4 v[126:129], v193, s[4:5] offset:3072 nt
	s_waitcnt vmcnt(36)
	s_add_i32 s6, s3, 0x8000
	s_lshl_b32 s7, s6, 11
	s_add_u32 s10, s40, s7
	s_addc_u32 s11, s41, 0
	s_lshl_b32 s7, s6, 6
	s_add_u32 s6, s40, s7
	s_addc_u32 s7, s41, 0
	s_add_u32 s6, s6, 0x1f800000
	s_addc_u32 s7, s7, 0
	v_mul_f32_e32 v150, v3, v3
	v_mul_f32_e32 v151, v5, v5
	v_fmac_f32_e32 v150, v2, v2
	v_fmac_f32_e32 v151, v4, v4
	v_add_f32_e32 v160, v150, v151
	v_cvt_pk_f16_f32 v170, v2, v3
	v_cvt_pk_f16_f32 v171, v4, v5
	v_mul_f32_e32 v150, v7, v7
	v_mul_f32_e32 v151, v9, v9
	v_fmac_f32_e32 v150, v6, v6
	v_fmac_f32_e32 v151, v8, v8
	v_add_f32_e32 v152, v150, v151
	v_add_f32_e32 v160, v160, v152
	v_cvt_pk_f16_f32 v172, v6, v7
	v_cvt_pk_f16_f32 v173, v8, v9
	v_mul_f32_e32 v150, v11, v11
	v_mul_f32_e32 v151, v13, v13
	v_fmac_f32_e32 v150, v10, v10
	v_fmac_f32_e32 v151, v12, v12
	v_add_f32_e32 v152, v150, v151
	v_add_f32_e32 v160, v160, v152
	v_cvt_pk_f16_f32 v174, v10, v11
	v_cvt_pk_f16_f32 v175, v12, v13
	v_mul_f32_e32 v150, v15, v15
	v_mul_f32_e32 v151, v17, v17
	v_fmac_f32_e32 v150, v14, v14
	v_fmac_f32_e32 v151, v16, v16
	v_add_f32_e32 v152, v150, v151
	v_add_f32_e32 v160, v160, v152
	v_cvt_pk_f16_f32 v176, v14, v15
	v_cvt_pk_f16_f32 v177, v16, v17
	global_store_dwordx2 v144, v[170:171], s[10:11]
	global_store_dwordx2 v144, v[172:173], s[10:11] offset:512
	global_store_dwordx2 v144, v[174:175], s[10:11] offset:1024
	global_store_dwordx2 v144, v[176:177], s[10:11] offset:1536
	v_mul_f32_e32 v150, v19, v19
	v_mul_f32_e32 v151, v21, v21
	v_fmac_f32_e32 v150, v18, v18
	v_fmac_f32_e32 v151, v20, v20
	v_add_f32_e32 v161, v150, v151
	v_cvt_pk_f16_f32 v178, v18, v19
	v_cvt_pk_f16_f32 v179, v20, v21
	v_mul_f32_e32 v150, v23, v23
	v_mul_f32_e32 v151, v25, v25
	v_fmac_f32_e32 v150, v22, v22
	v_fmac_f32_e32 v151, v24, v24
	v_add_f32_e32 v152, v150, v151
	v_add_f32_e32 v161, v161, v152
	v_cvt_pk_f16_f32 v180, v22, v23
	v_cvt_pk_f16_f32 v181, v24, v25
	v_mul_f32_e32 v150, v27, v27
	v_mul_f32_e32 v151, v29, v29
	v_fmac_f32_e32 v150, v26, v26
	v_fmac_f32_e32 v151, v28, v28
	v_add_f32_e32 v152, v150, v151
	v_add_f32_e32 v161, v161, v152
	v_cvt_pk_f16_f32 v182, v26, v27
	v_cvt_pk_f16_f32 v183, v28, v29
	v_mul_f32_e32 v150, v31, v31
	v_mul_f32_e32 v151, v33, v33
	v_fmac_f32_e32 v150, v30, v30
	v_fmac_f32_e32 v151, v32, v32
	v_add_f32_e32 v152, v150, v151
	v_add_f32_e32 v161, v161, v152
	v_cvt_pk_f16_f32 v184, v30, v31
	v_cvt_pk_f16_f32 v185, v32, v33
	global_store_dwordx2 v145, v[178:179], s[10:11]
	global_store_dwordx2 v145, v[180:181], s[10:11] offset:512
	global_store_dwordx2 v145, v[182:183], s[10:11] offset:1024
	global_store_dwordx2 v145, v[184:185], s[10:11] offset:1536
	v_mul_f32_e32 v150, v35, v35
	v_mul_f32_e32 v151, v37, v37
	v_fmac_f32_e32 v150, v34, v34
	v_fmac_f32_e32 v151, v36, v36
	v_add_f32_e32 v162, v150, v151
	v_cvt_pk_f16_f32 v170, v34, v35
	v_cvt_pk_f16_f32 v171, v36, v37
	v_mul_f32_e32 v150, v39, v39
	v_mul_f32_e32 v151, v41, v41
	v_fmac_f32_e32 v150, v38, v38
	v_fmac_f32_e32 v151, v40, v40
	v_add_f32_e32 v152, v150, v151
; __device__ void p0_xconv(const Args& a) {
;     ...
;         for (int r = 0; r < 4; ++r) {
;             const int row = row0 + r * nwv;
;             if (row < MROWS) {
;                 const float* src = (row < ROWS_PROMPT) ? a.x_prompt + (size_t)row * DM : a.x_sample + (size_t)(row - ROWS_PROMPT) * DM;
; #pragma unroll
;                 for (int i = 0; i < 4; ++i) v[r][i] = __builtin_nontemporal_load((const f32x4*)(src + i * 256 + lane * 4));
;             }
;         }
; #pragma unroll
;         for (int r = 0; r < 4; ++r) {
;             const int row = row0 + r * nwv;
;             if (row < MROWS) {
;                 float ss = 0.f;
; #pragma unroll
;                 for (int i = 0; i < 4; ++i) {
;                     const f32x4 x = v[r][i];
;                     ss += (x[0] * x[0] + x[1] * x[1]) + (x[2] * x[2] + x[3] * x[3]);
;                     f16x4 h; h[0] = (f16)x[0]; h[1] = (f16)x[1]; h[2] = (f16)x[2]; h[3] = (f16)x[3];
;                     *(f16x4*)(XH + (size_t)row * DM + i * 256 + lane * 4) = h;
;                 }
; #pragma unroll
;                 for (int o = 1; o < 64; o <<= 1) ss += __shfl_xor(ss, o);
;                 if (lane < 16) SS[(size_t)row * 16 + lane] = (lane == 0) ? ss : 0.f;
;             }
	v_add_f32_e32 v162, v162, v152
	v_cvt_pk_f16_f32 v172, v38, v39
	v_cvt_pk_f16_f32 v173, v40, v41
	v_mul_f32_e32 v150, v43, v43
	v_mul_f32_e32 v151, v45, v45
	v_fmac_f32_e32 v150, v42, v42
	v_fmac_f32_e32 v151, v44, v44
	v_add_f32_e32 v152, v150, v151
	v_add_f32_e32 v162, v162, v152
	v_cvt_pk_f16_f32 v174, v42, v43
	v_cvt_pk_f16_f32 v175, v44, v45
	v_mul_f32_e32 v150, v47, v47
	v_mul_f32_e32 v151, v49, v49
	v_fmac_f32_e32 v150, v46, v46
	v_fmac_f32_e32 v151, v48, v48
	v_add_f32_e32 v152, v150, v151
	v_add_f32_e32 v162, v162, v152
	v_cvt_pk_f16_f32 v176, v46, v47
	v_cvt_pk_f16_f32 v177, v48, v49
	global_store_dwordx2 v146, v[170:171], s[10:11]
	global_store_dwordx2 v146, v[172:173], s[10:11] offset:512
	global_store_dwordx2 v146, v[174:175], s[10:11] offset:1024
	global_store_dwordx2 v146, v[176:177], s[10:11] offset:1536
	v_mul_f32_e32 v150, v51, v51
	v_mul_f32_e32 v151, v53, v53
	v_fmac_f32_e32 v150, v50, v50
	v_fmac_f32_e32 v151, v52, v52
	v_add_f32_e32 v163, v150, v151
	v_cvt_pk_f16_f32 v178, v50, v51
	v_cvt_pk_f16_f32 v179, v52, v53
	v_mul_f32_e32 v150, v55, v55
	v_mul_f32_e32 v151, v57, v57
	v_fmac_f32_e32 v150, v54, v54
	v_fmac_f32_e32 v151, v56, v56
	v_add_f32_e32 v152, v150, v151
	v_add_f32_e32 v163, v163, v152
	v_cvt_pk_f16_f32 v180, v54, v55
	v_cvt_pk_f16_f32 v181, v56, v57
	v_mul_f32_e32 v150, v59, v59
	v_mul_f32_e32 v151, v61, v61
	v_fmac_f32_e32 v150, v58, v58
	v_fmac_f32_e32 v151, v60, v60
	v_add_f32_e32 v152, v150, v151
	v_add_f32_e32 v163, v163, v152
	v_cvt_pk_f16_f32 v182, v58, v59
	v_cvt_pk_f16_f32 v183, v60, v61
	v_mul_f32_e32 v150, v63, v63
	v_mul_f32_e32 v151, v65, v65
	v_fmac_f32_e32 v150, v62, v62
	v_fmac_f32_e32 v151, v64, v64
	v_add_f32_e32 v152, v150, v151
	v_add_f32_e32 v163, v163, v152
	v_cvt_pk_f16_f32 v184, v62, v63
	v_cvt_pk_f16_f32 v185, v64, v65
	global_store_dwordx2 v147, v[178:179], s[10:11]
	global_store_dwordx2 v147, v[180:181], s[10:11] offset:512
	global_store_dwordx2 v147, v[182:183], s[10:11] offset:1024
	global_store_dwordx2 v147, v[184:185], s[10:11] offset:1536
	ds_bpermute_b32 v164, v130, v160
	ds_bpermute_b32 v165, v130, v161
	ds_bpermute_b32 v166, v130, v162
	ds_bpermute_b32 v167, v130, v163
	s_waitcnt lgkmcnt(0)
	v_add_f32_e32 v160, v160, v164
	v_add_f32_e32 v161, v161, v165
	v_add_f32_e32 v162, v162, v166
	v_add_f32_e32 v163, v163, v167
	ds_bpermute_b32 v164, v131, v160
	ds_bpermute_b32 v165, v131, v161
	ds_bpermute_b32 v166, v131, v162
	ds_bpermute_b32 v167, v131, v163
	s_waitcnt lgkmcnt(0)
	v_add_f32_e32 v160, v160, v164
	v_add_f32_e32 v161, v161, v165
	v_add_f32_e32 v162, v162, v166
	v_add_f32_e32 v163, v163, v167
	ds_bpermute_b32 v164, v132, v160
	ds_bpermute_b32 v165, v132, v161
	ds_bpermute_b32 v166, v132, v162
	ds_bpermute_b32 v167, v132, v163
	s_waitcnt lgkmcnt(0)
	v_add_f32_e32 v160, v160, v164
	v_add_f32_e32 v161, v161, v165
	v_add_f32_e32 v162, v162, v166
	v_add_f32_e32 v163, v163, v167
	ds_bpermute_b32 v164, v133, v160
	ds_bpermute_b32 v165, v133, v161
	ds_bpermute_b32 v166, v133, v162
	ds_bpermute_b32 v167, v133, v163
	s_waitcnt lgkmcnt(0)
	v_add_f32_e32 v160, v160, v164
	v_add_f32_e32 v161, v161, v165
	v_add_f32_e32 v162, v162, v166
	v_add_f32_e32 v163, v163, v167
	ds_bpermute_b32 v164, v134, v160
	ds_bpermute_b32 v165, v134, v161
	ds_bpermute_b32 v166, v134, v162
	ds_bpermute_b32 v167, v134, v163
	s_waitcnt lgkmcnt(0)
	v_add_f32_e32 v160, v160, v164
	v_add_f32_e32 v161, v161, v165
	v_add_f32_e32 v162, v162, v166
	v_add_f32_e32 v163, v163, v167
	ds_bpermute_b32 v164, v135, v160
	ds_bpermute_b32 v165, v135, v161
	ds_bpermute_b32 v166, v135, v162
	ds_bpermute_b32 v167, v135, v163
	s_waitcnt lgkmcnt(0)
	v_add_f32_e32 v160, v160, v164
	v_add_f32_e32 v161, v161, v165
	v_add_f32_e32 v162, v162, v166
	v_add_f32_e32 v163, v163, v167
	v_cndmask_b32_e64 v164, 0, v160, s[12:13]
	v_cndmask_b32_e64 v165, 0, v161, s[12:13]
	v_cndmask_b32_e64 v166, 0, v162, s[12:13]
	v_cndmask_b32_e64 v167, 0, v163, s[12:13]
	s_mov_b64 exec, 0xffff
	global_store_dword v186, v164, s[6:7]
	global_store_dword v187, v165, s[6:7]
	global_store_dword v188, v166, s[6:7]
	global_store_dword v189, v167, s[6:7]
	s_mov_b64 exec, -1
	s_add_i32 s6, s9, 0x5800
	s_lshl_b32 s6, s6, 12
	s_add_u32 s4, s18, s6
	s_addc_u32 s5, s19, 0
	global_load_dwordx4 v[2:5], v190, s[4:5] nt
	global_load_dwordx4 v[6:9], v190, s[4:5] offset:1024 nt
	global_load_dwordx4 v[10:13], v190, s[4:5] offset:2048 nt
	global_load_dwordx4 v[14:17], v190, s[4:5] offset:3072 nt
	global_load_dwordx4 v[18:21], v191, s[4:5] nt
	global_load_dwordx4 v[22:25], v191, s[4:5] offset:1024 nt
	global_load_dwordx4 v[26:29], v191, s[4:5] offset:2048 nt
	global_load_dwordx4 v[30:33], v191, s[4:5] offset:3072 nt
	global_load_dwordx4 v[34:37], v192, s[4:5] nt
	global_load_dwordx4 v[38:41], v192, s[4:5] offset:1024 nt
	global_load_dwordx4 v[42:45], v192, s[4:5] offset:2048 nt
	global_load_dwordx4 v[46:49], v192, s[4:5] offset:3072 nt
	global_load_dwordx4 v[50:53], v193, s[4:5] nt
	global_load_dwordx4 v[54:57], v193, s[4:5] offset:1024 nt
	global_load_dwordx4 v[58:61], v193, s[4:5] offset:2048 nt
	global_load_dwordx4 v[62:65], v193, s[4:5] offset:3072 nt
	s_waitcnt vmcnt(36)
; __device__ void p0_xconv(const Args& a) {
;     ...
;         for (int r = 0; r < 4; ++r) {
;             const int row = row0 + r * nwv;
;             if (row < MROWS) {
;                 float ss = 0.f;
; #pragma unroll
;                 for (int i = 0; i < 4; ++i) {
;                     const f32x4 x = v[r][i];
;                     ss += (x[0] * x[0] + x[1] * x[1]) + (x[2] * x[2] + x[3] * x[3]);
;                     f16x4 h; h[0] = (f16)x[0]; h[1] = (f16)x[1]; h[2] = (f16)x[2]; h[3] = (f16)x[3];
;                     *(f16x4*)(XH + (size_t)row * DM + i * 256 + lane * 4) = h;
;                 }
; #pragma unroll
;                 for (int o = 1; o < 64; o <<= 1) ss += __shfl_xor(ss, o);
	s_add_i32 s6, s9, 0x9000
	s_lshl_b32 s7, s6, 11
	s_add_u32 s10, s40, s7
	s_addc_u32 s11, s41, 0
	s_lshl_b32 s7, s6, 6
	s_add_u32 s6, s40, s7
	s_addc_u32 s7, s41, 0
	s_add_u32 s6, s6, 0x1f800000
	s_addc_u32 s7, s7, 0
	v_mul_f32_e32 v150, v67, v67
	v_mul_f32_e32 v151, v69, v69
	v_fmac_f32_e32 v150, v66, v66
	v_fmac_f32_e32 v151, v68, v68
	v_add_f32_e32 v160, v150, v151
	v_cvt_pk_f16_f32 v170, v66, v67
	v_cvt_pk_f16_f32 v171, v68, v69
	v_mul_f32_e32 v150, v71, v71
	v_mul_f32_e32 v151, v73, v73
	v_fmac_f32_e32 v150, v70, v70
	v_fmac_f32_e32 v151, v72, v72
	v_add_f32_e32 v152, v150, v151
	v_add_f32_e32 v160, v160, v152
	v_cvt_pk_f16_f32 v172, v70, v71
	v_cvt_pk_f16_f32 v173, v72, v73
	v_mul_f32_e32 v150, v75, v75
	v_mul_f32_e32 v151, v77, v77
	v_fmac_f32_e32 v150, v74, v74
	v_fmac_f32_e32 v151, v76, v76
	v_add_f32_e32 v152, v150, v151
	v_add_f32_e32 v160, v160, v152
	v_cvt_pk_f16_f32 v174, v74, v75
	v_cvt_pk_f16_f32 v175, v76, v77
	v_mul_f32_e32 v150, v79, v79
	v_mul_f32_e32 v151, v81, v81
	v_fmac_f32_e32 v150, v78, v78
	v_fmac_f32_e32 v151, v80, v80
	v_add_f32_e32 v152, v150, v151
	v_add_f32_e32 v160, v160, v152
	v_cvt_pk_f16_f32 v176, v78, v79
	v_cvt_pk_f16_f32 v177, v80, v81
	global_store_dwordx2 v194, v[170:171], s[10:11]
	global_store_dwordx2 v194, v[172:173], s[10:11] offset:512
	global_store_dwordx2 v194, v[174:175], s[10:11] offset:1024
	global_store_dwordx2 v194, v[176:177], s[10:11] offset:1536
	v_mul_f32_e32 v150, v83, v83
	v_mul_f32_e32 v151, v85, v85
	v_fmac_f32_e32 v150, v82, v82
	v_fmac_f32_e32 v151, v84, v84
	v_add_f32_e32 v161, v150, v151
	v_cvt_pk_f16_f32 v178, v82, v83
	v_cvt_pk_f16_f32 v179, v84, v85
	v_mul_f32_e32 v150, v87, v87
	v_mul_f32_e32 v151, v89, v89
	v_fmac_f32_e32 v150, v86, v86
	v_fmac_f32_e32 v151, v88, v88
	v_add_f32_e32 v152, v150, v151
	v_add_f32_e32 v161, v161, v152
	v_cvt_pk_f16_f32 v180, v86, v87
	v_cvt_pk_f16_f32 v181, v88, v89
	v_mul_f32_e32 v150, v91, v91
	v_mul_f32_e32 v151, v93, v93
	v_fmac_f32_e32 v150, v90, v90
	v_fmac_f32_e32 v151, v92, v92
	v_add_f32_e32 v152, v150, v151
	v_add_f32_e32 v161, v161, v152
	v_cvt_pk_f16_f32 v182, v90, v91
	v_cvt_pk_f16_f32 v183, v92, v93
	v_mul_f32_e32 v150, v95, v95
	v_mul_f32_e32 v151, v97, v97
	v_fmac_f32_e32 v150, v94, v94
	v_fmac_f32_e32 v151, v96, v96
	v_add_f32_e32 v152, v150, v151
	v_add_f32_e32 v161, v161, v152
	v_cvt_pk_f16_f32 v184, v94, v95
	v_cvt_pk_f16_f32 v185, v96, v97
	global_store_dwordx2 v195, v[178:179], s[10:11]
	global_store_dwordx2 v195, v[180:181], s[10:11] offset:512
	global_store_dwordx2 v195, v[182:183], s[10:11] offset:1024
	global_store_dwordx2 v195, v[184:185], s[10:11] offset:1536
	v_mul_f32_e32 v150, v99, v99
	v_mul_f32_e32 v151, v101, v101
	v_fmac_f32_e32 v150, v98, v98
	v_fmac_f32_e32 v151, v100, v100
	v_add_f32_e32 v162, v150, v151
	v_cvt_pk_f16_f32 v170, v98, v99
	v_cvt_pk_f16_f32 v171, v100, v101
	v_mul_f32_e32 v150, v103, v103
	v_mul_f32_e32 v151, v105, v105
	v_fmac_f32_e32 v150, v102, v102
	v_fmac_f32_e32 v151, v104, v104
	v_add_f32_e32 v152, v150, v151
	v_add_f32_e32 v162, v162, v152
	v_cvt_pk_f16_f32 v172, v102, v103
	v_cvt_pk_f16_f32 v173, v104, v105
	v_mul_f32_e32 v150, v107, v107
	v_mul_f32_e32 v151, v109, v109
	v_fmac_f32_e32 v150, v106, v106
	v_fmac_f32_e32 v151, v108, v108
	v_add_f32_e32 v152, v150, v151
	v_add_f32_e32 v162, v162, v152
	v_cvt_pk_f16_f32 v174, v106, v107
	v_cvt_pk_f16_f32 v175, v108, v109
	v_mul_f32_e32 v150, v111, v111
	v_mul_f32_e32 v151, v113, v113
	v_fmac_f32_e32 v150, v110, v110
	v_fmac_f32_e32 v151, v112, v112
	v_add_f32_e32 v152, v150, v151
	v_add_f32_e32 v162, v162, v152
	v_cvt_pk_f16_f32 v176, v110, v111
	v_cvt_pk_f16_f32 v177, v112, v113
	global_store_dwordx2 v196, v[170:171], s[10:11]
	global_store_dwordx2 v196, v[172:173], s[10:11] offset:512
	global_store_dwordx2 v196, v[174:175], s[10:11] offset:1024
	global_store_dwordx2 v196, v[176:177], s[10:11] offset:1536
	v_mul_f32_e32 v150, v115, v115
	v_mul_f32_e32 v151, v117, v117
	v_fmac_f32_e32 v150, v114, v114
	v_fmac_f32_e32 v151, v116, v116
	v_add_f32_e32 v163, v150, v151
	v_cvt_pk_f16_f32 v178, v114, v115
	v_cvt_pk_f16_f32 v179, v116, v117
	v_mul_f32_e32 v150, v119, v119
	v_mul_f32_e32 v151, v121, v121
	v_fmac_f32_e32 v150, v118, v118
	v_fmac_f32_e32 v151, v120, v120
	v_add_f32_e32 v152, v150, v151
	v_add_f32_e32 v163, v163, v152
	v_cvt_pk_f16_f32 v180, v118, v119
	v_cvt_pk_f16_f32 v181, v120, v121
	v_mul_f32_e32 v150, v123, v123
	v_mul_f32_e32 v151, v125, v125
	v_fmac_f32_e32 v150, v122, v122
	v_fmac_f32_e32 v151, v124, v124
	v_add_f32_e32 v152, v150, v151
	v_add_f32_e32 v163, v163, v152
	v_cvt_pk_f16_f32 v182, v122, v123
	v_cvt_pk_f16_f32 v183, v124, v125
	v_mul_f32_e32 v150, v127, v127
	v_mul_f32_e32 v151, v129, v129
	v_fmac_f32_e32 v150, v126, v126
	v_fmac_f32_e32 v151, v128, v128
	v_add_f32_e32 v152, v150, v151
	v_add_f32_e32 v163, v163, v152
	v_cvt_pk_f16_f32 v184, v126, v127
	v_cvt_pk_f16_f32 v185, v128, v129
	global_store_dwordx2 v197, v[178:179], s[10:11]
	global_store_dwordx2 v197, v[180:181], s[10:11] offset:512
	global_store_dwordx2 v197, v[182:183], s[10:11] offset:1024
	global_store_dwordx2 v197, v[184:185], s[10:11] offset:1536
	ds_bpermute_b32 v164, v130, v160
	ds_bpermute_b32 v165, v130, v161
	ds_bpermute_b32 v166, v130, v162
	ds_bpermute_b32 v167, v130, v163
	s_waitcnt lgkmcnt(0)
	v_add_f32_e32 v160, v160, v164
	v_add_f32_e32 v161, v161, v165
	v_add_f32_e32 v162, v162, v166
	v_add_f32_e32 v163, v163, v167
	ds_bpermute_b32 v164, v131, v160
	ds_bpermute_b32 v165, v131, v161
	ds_bpermute_b32 v166, v131, v162
	ds_bpermute_b32 v167, v131, v163
	s_waitcnt lgkmcnt(0)
; __device__ void p0_xconv(const Args& a) {
;     ...
;         for (int r = 0; r < 4; ++r) {
;             const int row = row0 + r * nwv;
;             if (row < MROWS) {
;                 float ss = 0.f;
; #pragma unroll
;                 for (int i = 0; i < 4; ++i) {
;                     const f32x4 x = v[r][i];
;                     ss += (x[0] * x[0] + x[1] * x[1]) + (x[2] * x[2] + x[3] * x[3]);
;                     f16x4 h; h[0] = (f16)x[0]; h[1] = (f16)x[1]; h[2] = (f16)x[2]; h[3] = (f16)x[3];
;                     *(f16x4*)(XH + (size_t)row * DM + i * 256 + lane * 4) = h;
;                 }
; #pragma unroll
;                 for (int o = 1; o < 64; o <<= 1) ss += __shfl_xor(ss, o);
;                 if (lane < 16) SS[(size_t)row * 16 + lane] = (lane == 0) ? ss : 0.f;
;             }
	v_add_f32_e32 v160, v160, v164
	v_add_f32_e32 v161, v161, v165
	v_add_f32_e32 v162, v162, v166
	v_add_f32_e32 v163, v163, v167
	ds_bpermute_b32 v164, v132, v160
	ds_bpermute_b32 v165, v132, v161
	ds_bpermute_b32 v166, v132, v162
	ds_bpermute_b32 v167, v132, v163
	s_waitcnt lgkmcnt(0)
	v_add_f32_e32 v160, v160, v164
	v_add_f32_e32 v161, v161, v165
	v_add_f32_e32 v162, v162, v166
	v_add_f32_e32 v163, v163, v167
	ds_bpermute_b32 v164, v133, v160
	ds_bpermute_b32 v165, v133, v161
	ds_bpermute_b32 v166, v133, v162
	ds_bpermute_b32 v167, v133, v163
	s_waitcnt lgkmcnt(0)
	v_add_f32_e32 v160, v160, v164
	v_add_f32_e32 v161, v161, v165
	v_add_f32_e32 v162, v162, v166
	v_add_f32_e32 v163, v163, v167
	ds_bpermute_b32 v164, v134, v160
	ds_bpermute_b32 v165, v134, v161
	ds_bpermute_b32 v166, v134, v162
	ds_bpermute_b32 v167, v134, v163
	s_waitcnt lgkmcnt(0)
	v_add_f32_e32 v160, v160, v164
	v_add_f32_e32 v161, v161, v165
	v_add_f32_e32 v162, v162, v166
	v_add_f32_e32 v163, v163, v167
	ds_bpermute_b32 v164, v135, v160
	ds_bpermute_b32 v165, v135, v161
	ds_bpermute_b32 v166, v135, v162
	ds_bpermute_b32 v167, v135, v163
	s_waitcnt lgkmcnt(0)
	v_add_f32_e32 v160, v160, v164
	v_add_f32_e32 v161, v161, v165
	v_add_f32_e32 v162, v162, v166
	v_add_f32_e32 v163, v163, v167
	v_cndmask_b32_e64 v164, 0, v160, s[12:13]
	v_cndmask_b32_e64 v165, 0, v161, s[12:13]
	v_cndmask_b32_e64 v166, 0, v162, s[12:13]
	v_cndmask_b32_e64 v167, 0, v163, s[12:13]
	s_mov_b64 exec, 0xffff
	global_store_dword v198, v164, s[6:7]
	global_store_dword v199, v165, s[6:7]
	global_store_dword v200, v166, s[6:7]
	global_store_dword v201, v167, s[6:7]
	s_mov_b64 exec, -1
	s_waitcnt vmcnt(20)
	s_add_i32 s6, s9, 0x9800
	s_lshl_b32 s7, s6, 11
	s_add_u32 s10, s40, s7
	s_addc_u32 s11, s41, 0
	s_lshl_b32 s7, s6, 6
	s_add_u32 s6, s40, s7
	s_addc_u32 s7, s41, 0
	s_add_u32 s6, s6, 0x1f800000
	s_addc_u32 s7, s7, 0
	v_mul_f32_e32 v150, v3, v3
	v_mul_f32_e32 v151, v5, v5
	v_fmac_f32_e32 v150, v2, v2
	v_fmac_f32_e32 v151, v4, v4
	v_add_f32_e32 v160, v150, v151
	v_cvt_pk_f16_f32 v170, v2, v3
	v_cvt_pk_f16_f32 v171, v4, v5
	v_mul_f32_e32 v150, v7, v7
	v_mul_f32_e32 v151, v9, v9
	v_fmac_f32_e32 v150, v6, v6
	v_fmac_f32_e32 v151, v8, v8
	v_add_f32_e32 v152, v150, v151
	v_add_f32_e32 v160, v160, v152
	v_cvt_pk_f16_f32 v172, v6, v7
	v_cvt_pk_f16_f32 v173, v8, v9
	v_mul_f32_e32 v150, v11, v11
	v_mul_f32_e32 v151, v13, v13
	v_fmac_f32_e32 v150, v10, v10
	v_fmac_f32_e32 v151, v12, v12
	v_add_f32_e32 v152, v150, v151
	v_add_f32_e32 v160, v160, v152
	v_cvt_pk_f16_f32 v174, v10, v11
	v_cvt_pk_f16_f32 v175, v12, v13
	v_mul_f32_e32 v150, v15, v15
	v_mul_f32_e32 v151, v17, v17
	v_fmac_f32_e32 v150, v14, v14
	v_fmac_f32_e32 v151, v16, v16
	v_add_f32_e32 v152, v150, v151
	v_add_f32_e32 v160, v160, v152
	v_cvt_pk_f16_f32 v176, v14, v15
	v_cvt_pk_f16_f32 v177, v16, v17
	global_store_dwordx2 v194, v[170:171], s[10:11]
	global_store_dwordx2 v194, v[172:173], s[10:11] offset:512
	global_store_dwordx2 v194, v[174:175], s[10:11] offset:1024
	global_store_dwordx2 v194, v[176:177], s[10:11] offset:1536
	v_mul_f32_e32 v150, v19, v19
	v_mul_f32_e32 v151, v21, v21
	v_fmac_f32_e32 v150, v18, v18
	v_fmac_f32_e32 v151, v20, v20
	v_add_f32_e32 v161, v150, v151
	v_cvt_pk_f16_f32 v178, v18, v19
	v_cvt_pk_f16_f32 v179, v20, v21
	v_mul_f32_e32 v150, v23, v23
	v_mul_f32_e32 v151, v25, v25
	v_fmac_f32_e32 v150, v22, v22
	v_fmac_f32_e32 v151, v24, v24
	v_add_f32_e32 v152, v150, v151
	v_add_f32_e32 v161, v161, v152
	v_cvt_pk_f16_f32 v180, v22, v23
	v_cvt_pk_f16_f32 v181, v24, v25
	v_mul_f32_e32 v150, v27, v27
	v_mul_f32_e32 v151, v29, v29
	v_fmac_f32_e32 v150, v26, v26
	v_fmac_f32_e32 v151, v28, v28
	v_add_f32_e32 v152, v150, v151
	v_add_f32_e32 v161, v161, v152
	v_cvt_pk_f16_f32 v182, v26, v27
	v_cvt_pk_f16_f32 v183, v28, v29
	v_mul_f32_e32 v150, v31, v31
	v_mul_f32_e32 v151, v33, v33
	v_fmac_f32_e32 v150, v30, v30
	v_fmac_f32_e32 v151, v32, v32
	v_add_f32_e32 v152, v150, v151
	v_add_f32_e32 v161, v161, v152
	v_cvt_pk_f16_f32 v184, v30, v31
	v_cvt_pk_f16_f32 v185, v32, v33
	global_store_dwordx2 v195, v[178:179], s[10:11]
	global_store_dwordx2 v195, v[180:181], s[10:11] offset:512
	global_store_dwordx2 v195, v[182:183], s[10:11] offset:1024
	global_store_dwordx2 v195, v[184:185], s[10:11] offset:1536
	v_mul_f32_e32 v150, v35, v35
	v_mul_f32_e32 v151, v37, v37
	v_fmac_f32_e32 v150, v34, v34
	v_fmac_f32_e32 v151, v36, v36
	v_add_f32_e32 v162, v150, v151
	v_cvt_pk_f16_f32 v170, v34, v35
	v_cvt_pk_f16_f32 v171, v36, v37
	v_mul_f32_e32 v150, v39, v39
	v_mul_f32_e32 v151, v41, v41
	v_fmac_f32_e32 v150, v38, v38
	v_fmac_f32_e32 v151, v40, v40
	v_add_f32_e32 v152, v150, v151
	v_add_f32_e32 v162, v162, v152
	v_cvt_pk_f16_f32 v172, v38, v39
	v_cvt_pk_f16_f32 v173, v40, v41
	v_mul_f32_e32 v150, v43, v43
	v_mul_f32_e32 v151, v45, v45
	v_fmac_f32_e32 v150, v42, v42
	v_fmac_f32_e32 v151, v44, v44
	v_add_f32_e32 v152, v150, v151
	v_add_f32_e32 v162, v162, v152
	v_cvt_pk_f16_f32 v174, v42, v43
	v_cvt_pk_f16_f32 v175, v44, v45
	v_mul_f32_e32 v150, v47, v47
	v_mul_f32_e32 v151, v49, v49
	v_fmac_f32_e32 v150, v46, v46
	v_fmac_f32_e32 v151, v48, v48
	v_add_f32_e32 v152, v150, v151
	v_add_f32_e32 v162, v162, v152
	v_cvt_pk_f16_f32 v176, v46, v47
	v_cvt_pk_f16_f32 v177, v48, v49
	global_store_dwordx2 v196, v[170:171], s[10:11]
	global_store_dwordx2 v196, v[172:173], s[10:11] offset:512
	global_store_dwordx2 v196, v[174:175], s[10:11] offset:1024
	global_store_dwordx2 v196, v[176:177], s[10:11] offset:1536
	v_mul_f32_e32 v150, v51, v51
	v_mul_f32_e32 v151, v53, v53
	v_fmac_f32_e32 v150, v50, v50
	v_fmac_f32_e32 v151, v52, v52
	v_add_f32_e32 v163, v150, v151
	v_cvt_pk_f16_f32 v178, v50, v51
	v_cvt_pk_f16_f32 v179, v52, v53
	v_mul_f32_e32 v150, v55, v55
	v_mul_f32_e32 v151, v57, v57
	v_fmac_f32_e32 v150, v54, v54
	v_fmac_f32_e32 v151, v56, v56
	v_add_f32_e32 v152, v150, v151
	v_add_f32_e32 v163, v163, v152
	v_cvt_pk_f16_f32 v180, v54, v55
	v_cvt_pk_f16_f32 v181, v56, v57
	v_mul_f32_e32 v150, v59, v59
	v_mul_f32_e32 v151, v61, v61
	v_fmac_f32_e32 v150, v58, v58
	v_fmac_f32_e32 v151, v60, v60
	v_add_f32_e32 v152, v150, v151
	v_add_f32_e32 v163, v163, v152
	v_cvt_pk_f16_f32 v182, v58, v59
	v_cvt_pk_f16_f32 v183, v60, v61
	v_mul_f32_e32 v150, v63, v63
	v_mul_f32_e32 v151, v65, v65
	v_fmac_f32_e32 v150, v62, v62
	v_fmac_f32_e32 v151, v64, v64
	v_add_f32_e32 v152, v150, v151
	v_add_f32_e32 v163, v163, v152
	v_cvt_pk_f16_f32 v184, v62, v63
	v_cvt_pk_f16_f32 v185, v64, v65
	global_store_dwordx2 v197, v[178:179], s[10:11]
	global_store_dwordx2 v197, v[180:181], s[10:11] offset:512
	global_store_dwordx2 v197, v[182:183], s[10:11] offset:1024
	global_store_dwordx2 v197, v[184:185], s[10:11] offset:1536
	ds_bpermute_b32 v164, v130, v160
	ds_bpermute_b32 v165, v130, v161
	ds_bpermute_b32 v166, v130, v162
	ds_bpermute_b32 v167, v130, v163
	s_waitcnt lgkmcnt(0)
; __device__ void p0_xconv(const Args& a) {
;     ...
;         for (int r = 0; r < 4; ++r) {
;             const int row = row0 + r * nwv;
;             if (row < MROWS) {
;                 const float* src = (row < ROWS_PROMPT) ? a.x_prompt + (size_t)row * DM : a.x_sample + (size_t)(row - ROWS_PROMPT) * DM;
; #pragma unroll
;                 for (int i = 0; i < 4; ++i) v[r][i] = __builtin_nontemporal_load((const f32x4*)(src + i * 256 + lane * 4));
;             }
;     ...
;         for (int r = 0; r < 4; ++r) {
;             const int row = row0 + r * nwv;
;             if (row < MROWS) {
;                 float ss = 0.f;
; #pragma unroll
;                 for (int i = 0; i < 4; ++i) {
;                     const f32x4 x = v[r][i];
;                     ss += (x[0] * x[0] + x[1] * x[1]) + (x[2] * x[2] + x[3] * x[3]);
;                     f16x4 h; h[0] = (f16)x[0]; h[1] = (f16)x[1]; h[2] = (f16)x[2]; h[3] = (f16)x[3];
;                     *(f16x4*)(XH + (size_t)row * DM + i * 256 + lane * 4) = h;
;                 }
; #pragma unroll
;                 for (int o = 1; o < 64; o <<= 1) ss += __shfl_xor(ss, o);
;                 if (lane < 16) SS[(size_t)row * 16 + lane] = (lane == 0) ? ss : 0.f;
;             }
	v_add_f32_e32 v160, v160, v164
	v_add_f32_e32 v161, v161, v165
	v_add_f32_e32 v162, v162, v166
	v_add_f32_e32 v163, v163, v167
	ds_bpermute_b32 v164, v131, v160
	ds_bpermute_b32 v165, v131, v161
	ds_bpermute_b32 v166, v131, v162
	ds_bpermute_b32 v167, v131, v163
	s_waitcnt lgkmcnt(0)
	v_add_f32_e32 v160, v160, v164
	v_add_f32_e32 v161, v161, v165
	v_add_f32_e32 v162, v162, v166
	v_add_f32_e32 v163, v163, v167
	ds_bpermute_b32 v164, v132, v160
	ds_bpermute_b32 v165, v132, v161
	ds_bpermute_b32 v166, v132, v162
	ds_bpermute_b32 v167, v132, v163
	s_waitcnt lgkmcnt(0)
	v_add_f32_e32 v160, v160, v164
	v_add_f32_e32 v161, v161, v165
	v_add_f32_e32 v162, v162, v166
	v_add_f32_e32 v163, v163, v167
	ds_bpermute_b32 v164, v133, v160
	ds_bpermute_b32 v165, v133, v161
	ds_bpermute_b32 v166, v133, v162
	ds_bpermute_b32 v167, v133, v163
	s_waitcnt lgkmcnt(0)
	v_add_f32_e32 v160, v160, v164
	v_add_f32_e32 v161, v161, v165
	v_add_f32_e32 v162, v162, v166
	v_add_f32_e32 v163, v163, v167
	ds_bpermute_b32 v164, v134, v160
	ds_bpermute_b32 v165, v134, v161
	ds_bpermute_b32 v166, v134, v162
	ds_bpermute_b32 v167, v134, v163
	s_waitcnt lgkmcnt(0)
	v_add_f32_e32 v160, v160, v164
	v_add_f32_e32 v161, v161, v165
	v_add_f32_e32 v162, v162, v166
	v_add_f32_e32 v163, v163, v167
	ds_bpermute_b32 v164, v135, v160
	ds_bpermute_b32 v165, v135, v161
	ds_bpermute_b32 v166, v135, v162
	ds_bpermute_b32 v167, v135, v163
	s_waitcnt lgkmcnt(0)
	v_add_f32_e32 v160, v160, v164
	v_add_f32_e32 v161, v161, v165
	v_add_f32_e32 v162, v162, v166
	v_add_f32_e32 v163, v163, v167
	v_cndmask_b32_e64 v164, 0, v160, s[12:13]
	v_cndmask_b32_e64 v165, 0, v161, s[12:13]
	v_cndmask_b32_e64 v166, 0, v162, s[12:13]
	v_cndmask_b32_e64 v167, 0, v163, s[12:13]
	s_mov_b64 exec, 0xffff
	global_store_dword v198, v164, s[6:7]
	global_store_dword v199, v165, s[6:7]
	global_store_dword v200, v166, s[6:7]
	global_store_dword v201, v167, s[6:7]
	s_mov_b64 exec, -1
	s_branch .LBB0_37
.Lws_xlo:
	s_add_i32 s6, s3, 0x0
	s_lshl_b32 s6, s6, 12
	s_add_u32 s4, s16, s6
	s_addc_u32 s5, s17, 0
	global_load_dwordx4 v[2:5], v140, s[4:5] nt
	global_load_dwordx4 v[6:9], v140, s[4:5] offset:1024 nt
	global_load_dwordx4 v[10:13], v140, s[4:5] offset:2048 nt
	global_load_dwordx4 v[14:17], v140, s[4:5] offset:3072 nt
	global_load_dwordx4 v[18:21], v141, s[4:5] nt
	global_load_dwordx4 v[22:25], v141, s[4:5] offset:1024 nt
	global_load_dwordx4 v[26:29], v141, s[4:5] offset:2048 nt
	global_load_dwordx4 v[30:33], v141, s[4:5] offset:3072 nt
	global_load_dwordx4 v[34:37], v142, s[4:5] nt
	global_load_dwordx4 v[38:41], v142, s[4:5] offset:1024 nt
	global_load_dwordx4 v[42:45], v142, s[4:5] offset:2048 nt
	global_load_dwordx4 v[46:49], v142, s[4:5] offset:3072 nt
	global_load_dwordx4 v[50:53], v143, s[4:5] nt
	global_load_dwordx4 v[54:57], v143, s[4:5] offset:1024 nt
	global_load_dwordx4 v[58:61], v143, s[4:5] offset:2048 nt
	global_load_dwordx4 v[62:65], v143, s[4:5] offset:3072 nt
	s_add_i32 s6, s3, 0x1000
	s_lshl_b32 s6, s6, 12
	s_add_u32 s4, s16, s6
	s_addc_u32 s5, s17, 0
	global_load_dwordx4 v[66:69], v140, s[4:5] nt
	global_load_dwordx4 v[70:73], v140, s[4:5] offset:1024 nt
	global_load_dwordx4 v[74:77], v140, s[4:5] offset:2048 nt
	global_load_dwordx4 v[78:81], v140, s[4:5] offset:3072 nt
	global_load_dwordx4 v[82:85], v141, s[4:5] nt
	global_load_dwordx4 v[86:89], v141, s[4:5] offset:1024 nt
	global_load_dwordx4 v[90:93], v141, s[4:5] offset:2048 nt
	global_load_dwordx4 v[94:97], v141, s[4:5] offset:3072 nt
	global_load_dwordx4 v[98:101], v142, s[4:5] nt
	global_load_dwordx4 v[102:105], v142, s[4:5] offset:1024 nt
	global_load_dwordx4 v[106:109], v142, s[4:5] offset:2048 nt
	global_load_dwordx4 v[110:113], v142, s[4:5] offset:3072 nt
	global_load_dwordx4 v[114:117], v143, s[4:5] nt
	global_load_dwordx4 v[118:121], v143, s[4:5] offset:1024 nt
	global_load_dwordx4 v[122:125], v143, s[4:5] offset:2048 nt
	global_load_dwordx4 v[126:129], v143, s[4:5] offset:3072 nt
	s_waitcnt vmcnt(16)
	s_add_i32 s6, s3, 0x0
	s_lshl_b32 s7, s6, 11
	s_add_u32 s10, s40, s7
	s_addc_u32 s11, s41, 0
	s_lshl_b32 s7, s6, 6
	s_add_u32 s6, s40, s7
	s_addc_u32 s7, s41, 0
	s_add_u32 s6, s6, 0x1f800000
	s_addc_u32 s7, s7, 0
	v_mul_f32_e32 v150, v3, v3
	v_mul_f32_e32 v151, v5, v5
	v_fmac_f32_e32 v150, v2, v2
	v_fmac_f32_e32 v151, v4, v4
	v_add_f32_e32 v160, v150, v151
	v_cvt_pk_f16_f32 v170, v2, v3
	v_cvt_pk_f16_f32 v171, v4, v5
	v_mul_f32_e32 v150, v7, v7
	v_mul_f32_e32 v151, v9, v9
	v_fmac_f32_e32 v150, v6, v6
	v_fmac_f32_e32 v151, v8, v8
	v_add_f32_e32 v152, v150, v151
	v_add_f32_e32 v160, v160, v152
	v_cvt_pk_f16_f32 v172, v6, v7
	v_cvt_pk_f16_f32 v173, v8, v9
	v_mul_f32_e32 v150, v11, v11
	v_mul_f32_e32 v151, v13, v13
	v_fmac_f32_e32 v150, v10, v10
	v_fmac_f32_e32 v151, v12, v12
	v_add_f32_e32 v152, v150, v151
	v_add_f32_e32 v160, v160, v152
	v_cvt_pk_f16_f32 v174, v10, v11
	v_cvt_pk_f16_f32 v175, v12, v13
	v_mul_f32_e32 v150, v15, v15
	v_mul_f32_e32 v151, v17, v17
	v_fmac_f32_e32 v150, v14, v14
	v_fmac_f32_e32 v151, v16, v16
	v_add_f32_e32 v152, v150, v151
	v_add_f32_e32 v160, v160, v152
	v_cvt_pk_f16_f32 v176, v14, v15
	v_cvt_pk_f16_f32 v177, v16, v17
	global_store_dwordx2 v144, v[170:171], s[10:11]
	global_store_dwordx2 v144, v[172:173], s[10:11] offset:512
	global_store_dwordx2 v144, v[174:175], s[10:11] offset:1024
	global_store_dwordx2 v144, v[176:177], s[10:11] offset:1536
	v_mul_f32_e32 v150, v19, v19
	v_mul_f32_e32 v151, v21, v21
	v_fmac_f32_e32 v150, v18, v18
	v_fmac_f32_e32 v151, v20, v20
	v_add_f32_e32 v161, v150, v151
	v_cvt_pk_f16_f32 v178, v18, v19
	v_cvt_pk_f16_f32 v179, v20, v21
	v_mul_f32_e32 v150, v23, v23
	v_mul_f32_e32 v151, v25, v25
; __device__ void p0_xconv(const Args& a) {
;     ...
;         for (int r = 0; r < 4; ++r) {
;             const int row = row0 + r * nwv;
;             if (row < MROWS) {
;                 float ss = 0.f;
; #pragma unroll
;                 for (int i = 0; i < 4; ++i) {
;                     const f32x4 x = v[r][i];
;                     ss += (x[0] * x[0] + x[1] * x[1]) + (x[2] * x[2] + x[3] * x[3]);
;                     f16x4 h; h[0] = (f16)x[0]; h[1] = (f16)x[1]; h[2] = (f16)x[2]; h[3] = (f16)x[3];
;                     *(f16x4*)(XH + (size_t)row * DM + i * 256 + lane * 4) = h;
;                 }
; #pragma unroll
;                 for (int o = 1; o < 64; o <<= 1) ss += __shfl_xor(ss, o);
	v_fmac_f32_e32 v150, v22, v22
	v_fmac_f32_e32 v151, v24, v24
	v_add_f32_e32 v152, v150, v151
	v_add_f32_e32 v161, v161, v152
	v_cvt_pk_f16_f32 v180, v22, v23
	v_cvt_pk_f16_f32 v181, v24, v25
	v_mul_f32_e32 v150, v27, v27
	v_mul_f32_e32 v151, v29, v29
	v_fmac_f32_e32 v150, v26, v26
	v_fmac_f32_e32 v151, v28, v28
	v_add_f32_e32 v152, v150, v151
	v_add_f32_e32 v161, v161, v152
	v_cvt_pk_f16_f32 v182, v26, v27
	v_cvt_pk_f16_f32 v183, v28, v29
	v_mul_f32_e32 v150, v31, v31
	v_mul_f32_e32 v151, v33, v33
	v_fmac_f32_e32 v150, v30, v30
	v_fmac_f32_e32 v151, v32, v32
	v_add_f32_e32 v152, v150, v151
	v_add_f32_e32 v161, v161, v152
	v_cvt_pk_f16_f32 v184, v30, v31
	v_cvt_pk_f16_f32 v185, v32, v33
	global_store_dwordx2 v145, v[178:179], s[10:11]
	global_store_dwordx2 v145, v[180:181], s[10:11] offset:512
	global_store_dwordx2 v145, v[182:183], s[10:11] offset:1024
	global_store_dwordx2 v145, v[184:185], s[10:11] offset:1536
	v_mul_f32_e32 v150, v35, v35
	v_mul_f32_e32 v151, v37, v37
	v_fmac_f32_e32 v150, v34, v34
	v_fmac_f32_e32 v151, v36, v36
	v_add_f32_e32 v162, v150, v151
	v_cvt_pk_f16_f32 v170, v34, v35
	v_cvt_pk_f16_f32 v171, v36, v37
	v_mul_f32_e32 v150, v39, v39
	v_mul_f32_e32 v151, v41, v41
	v_fmac_f32_e32 v150, v38, v38
	v_fmac_f32_e32 v151, v40, v40
	v_add_f32_e32 v152, v150, v151
	v_add_f32_e32 v162, v162, v152
	v_cvt_pk_f16_f32 v172, v38, v39
	v_cvt_pk_f16_f32 v173, v40, v41
	v_mul_f32_e32 v150, v43, v43
	v_mul_f32_e32 v151, v45, v45
	v_fmac_f32_e32 v150, v42, v42
	v_fmac_f32_e32 v151, v44, v44
	v_add_f32_e32 v152, v150, v151
	v_add_f32_e32 v162, v162, v152
	v_cvt_pk_f16_f32 v174, v42, v43
	v_cvt_pk_f16_f32 v175, v44, v45
	v_mul_f32_e32 v150, v47, v47
	v_mul_f32_e32 v151, v49, v49
	v_fmac_f32_e32 v150, v46, v46
	v_fmac_f32_e32 v151, v48, v48
	v_add_f32_e32 v152, v150, v151
	v_add_f32_e32 v162, v162, v152
	v_cvt_pk_f16_f32 v176, v46, v47
	v_cvt_pk_f16_f32 v177, v48, v49
	global_store_dwordx2 v146, v[170:171], s[10:11]
	global_store_dwordx2 v146, v[172:173], s[10:11] offset:512
	global_store_dwordx2 v146, v[174:175], s[10:11] offset:1024
	global_store_dwordx2 v146, v[176:177], s[10:11] offset:1536
	v_mul_f32_e32 v150, v51, v51
	v_mul_f32_e32 v151, v53, v53
	v_fmac_f32_e32 v150, v50, v50
	v_fmac_f32_e32 v151, v52, v52
	v_add_f32_e32 v163, v150, v151
	v_cvt_pk_f16_f32 v178, v50, v51
	v_cvt_pk_f16_f32 v179, v52, v53
	v_mul_f32_e32 v150, v55, v55
	v_mul_f32_e32 v151, v57, v57
	v_fmac_f32_e32 v150, v54, v54
	v_fmac_f32_e32 v151, v56, v56
	v_add_f32_e32 v152, v150, v151
	v_add_f32_e32 v163, v163, v152
	v_cvt_pk_f16_f32 v180, v54, v55
	v_cvt_pk_f16_f32 v181, v56, v57
	v_mul_f32_e32 v150, v59, v59
	v_mul_f32_e32 v151, v61, v61
	v_fmac_f32_e32 v150, v58, v58
	v_fmac_f32_e32 v151, v60, v60
	v_add_f32_e32 v152, v150, v151
	v_add_f32_e32 v163, v163, v152
	v_cvt_pk_f16_f32 v182, v58, v59
	v_cvt_pk_f16_f32 v183, v60, v61
	v_mul_f32_e32 v150, v63, v63
	v_mul_f32_e32 v151, v65, v65
	v_fmac_f32_e32 v150, v62, v62
	v_fmac_f32_e32 v151, v64, v64
	v_add_f32_e32 v152, v150, v151
	v_add_f32_e32 v163, v163, v152
	v_cvt_pk_f16_f32 v184, v62, v63
	v_cvt_pk_f16_f32 v185, v64, v65
	global_store_dwordx2 v147, v[178:179], s[10:11]
	global_store_dwordx2 v147, v[180:181], s[10:11] offset:512
	global_store_dwordx2 v147, v[182:183], s[10:11] offset:1024
	global_store_dwordx2 v147, v[184:185], s[10:11] offset:1536
	ds_bpermute_b32 v164, v130, v160
	ds_bpermute_b32 v165, v130, v161
	ds_bpermute_b32 v166, v130, v162
	ds_bpermute_b32 v167, v130, v163
	s_waitcnt lgkmcnt(0)
	v_add_f32_e32 v160, v160, v164
	v_add_f32_e32 v161, v161, v165
	v_add_f32_e32 v162, v162, v166
	v_add_f32_e32 v163, v163, v167
	ds_bpermute_b32 v164, v131, v160
	ds_bpermute_b32 v165, v131, v161
	ds_bpermute_b32 v166, v131, v162
	ds_bpermute_b32 v167, v131, v163
	s_waitcnt lgkmcnt(0)
	v_add_f32_e32 v160, v160, v164
	v_add_f32_e32 v161, v161, v165
	v_add_f32_e32 v162, v162, v166
	v_add_f32_e32 v163, v163, v167
	ds_bpermute_b32 v164, v132, v160
	ds_bpermute_b32 v165, v132, v161
	ds_bpermute_b32 v166, v132, v162
	ds_bpermute_b32 v167, v132, v163
	s_waitcnt lgkmcnt(0)
	v_add_f32_e32 v160, v160, v164
	v_add_f32_e32 v161, v161, v165
	v_add_f32_e32 v162, v162, v166
	v_add_f32_e32 v163, v163, v167
	ds_bpermute_b32 v164, v133, v160
	ds_bpermute_b32 v165, v133, v161
	ds_bpermute_b32 v166, v133, v162
	ds_bpermute_b32 v167, v133, v163
	s_waitcnt lgkmcnt(0)
	v_add_f32_e32 v160, v160, v164
	v_add_f32_e32 v161, v161, v165
	v_add_f32_e32 v162, v162, v166
	v_add_f32_e32 v163, v163, v167
	ds_bpermute_b32 v164, v134, v160
	ds_bpermute_b32 v165, v134, v161
	ds_bpermute_b32 v166, v134, v162
	ds_bpermute_b32 v167, v134, v163
	s_waitcnt lgkmcnt(0)
	v_add_f32_e32 v160, v160, v164
	v_add_f32_e32 v161, v161, v165
	v_add_f32_e32 v162, v162, v166
	v_add_f32_e32 v163, v163, v167
	ds_bpermute_b32 v164, v135, v160
	ds_bpermute_b32 v165, v135, v161
	ds_bpermute_b32 v166, v135, v162
	ds_bpermute_b32 v167, v135, v163
	s_waitcnt lgkmcnt(0)
; __device__ void p0_xconv(const Args& a) {
;     ...
;         for (int r = 0; r < 4; ++r) {
;             const int row = row0 + r * nwv;
;             if (row < MROWS) {
;                 const float* src = (row < ROWS_PROMPT) ? a.x_prompt + (size_t)row * DM : a.x_sample + (size_t)(row - ROWS_PROMPT) * DM;
; #pragma unroll
;                 for (int i = 0; i < 4; ++i) v[r][i] = __builtin_nontemporal_load((const f32x4*)(src + i * 256 + lane * 4));
;             }
;         }
; #pragma unroll
;         for (int r = 0; r < 4; ++r) {
;             const int row = row0 + r * nwv;
;             if (row < MROWS) {
;                 float ss = 0.f;
; #pragma unroll
;                 for (int i = 0; i < 4; ++i) {
;                     const f32x4 x = v[r][i];
;                     ss += (x[0] * x[0] + x[1] * x[1]) + (x[2] * x[2] + x[3] * x[3]);
;                     f16x4 h; h[0] = (f16)x[0]; h[1] = (f16)x[1]; h[2] = (f16)x[2]; h[3] = (f16)x[3];
;                     *(f16x4*)(XH + (size_t)row * DM + i * 256 + lane * 4) = h;
;                 }
; #pragma unroll
;                 for (int o = 1; o < 64; o <<= 1) ss += __shfl_xor(ss, o);
;                 if (lane < 16) SS[(size_t)row * 16 + lane] = (lane == 0) ? ss : 0.f;
;             }
	v_add_f32_e32 v160, v160, v164
	v_add_f32_e32 v161, v161, v165
	v_add_f32_e32 v162, v162, v166
	v_add_f32_e32 v163, v163, v167
	v_cndmask_b32_e64 v164, 0, v160, s[12:13]
	v_cndmask_b32_e64 v165, 0, v161, s[12:13]
	v_cndmask_b32_e64 v166, 0, v162, s[12:13]
	v_cndmask_b32_e64 v167, 0, v163, s[12:13]
	s_mov_b64 exec, 0xffff
	global_store_dword v186, v164, s[6:7]
	global_store_dword v187, v165, s[6:7]
	global_store_dword v188, v166, s[6:7]
	global_store_dword v189, v167, s[6:7]
	s_mov_b64 exec, -1
	s_add_i32 s6, s3, 0x2000
	s_lshl_b32 s6, s6, 12
	s_add_u32 s4, s16, s6
	s_addc_u32 s5, s17, 0
	global_load_dwordx4 v[2:5], v140, s[4:5] nt
	global_load_dwordx4 v[6:9], v140, s[4:5] offset:1024 nt
	global_load_dwordx4 v[10:13], v140, s[4:5] offset:2048 nt
	global_load_dwordx4 v[14:17], v140, s[4:5] offset:3072 nt
	global_load_dwordx4 v[18:21], v141, s[4:5] nt
	global_load_dwordx4 v[22:25], v141, s[4:5] offset:1024 nt
	global_load_dwordx4 v[26:29], v141, s[4:5] offset:2048 nt
	global_load_dwordx4 v[30:33], v141, s[4:5] offset:3072 nt
	global_load_dwordx4 v[34:37], v142, s[4:5] nt
	global_load_dwordx4 v[38:41], v142, s[4:5] offset:1024 nt
	global_load_dwordx4 v[42:45], v142, s[4:5] offset:2048 nt
	global_load_dwordx4 v[46:49], v142, s[4:5] offset:3072 nt
	global_load_dwordx4 v[50:53], v143, s[4:5] nt
	global_load_dwordx4 v[54:57], v143, s[4:5] offset:1024 nt
	global_load_dwordx4 v[58:61], v143, s[4:5] offset:2048 nt
	global_load_dwordx4 v[62:65], v143, s[4:5] offset:3072 nt
	s_waitcnt vmcnt(36)
	s_add_i32 s6, s3, 0x1000
	s_lshl_b32 s7, s6, 11
	s_add_u32 s10, s40, s7
	s_addc_u32 s11, s41, 0
	s_lshl_b32 s7, s6, 6
	s_add_u32 s6, s40, s7
	s_addc_u32 s7, s41, 0
	s_add_u32 s6, s6, 0x1f800000
	s_addc_u32 s7, s7, 0
	v_mul_f32_e32 v150, v67, v67
	v_mul_f32_e32 v151, v69, v69
	v_fmac_f32_e32 v150, v66, v66
	v_fmac_f32_e32 v151, v68, v68
	v_add_f32_e32 v160, v150, v151
	v_cvt_pk_f16_f32 v170, v66, v67
	v_cvt_pk_f16_f32 v171, v68, v69
	v_mul_f32_e32 v150, v71, v71
	v_mul_f32_e32 v151, v73, v73
	v_fmac_f32_e32 v150, v70, v70
	v_fmac_f32_e32 v151, v72, v72
	v_add_f32_e32 v152, v150, v151
	v_add_f32_e32 v160, v160, v152
	v_cvt_pk_f16_f32 v172, v70, v71
	v_cvt_pk_f16_f32 v173, v72, v73
	v_mul_f32_e32 v150, v75, v75
	v_mul_f32_e32 v151, v77, v77
	v_fmac_f32_e32 v150, v74, v74
	v_fmac_f32_e32 v151, v76, v76
	v_add_f32_e32 v152, v150, v151
	v_add_f32_e32 v160, v160, v152
	v_cvt_pk_f16_f32 v174, v74, v75
	v_cvt_pk_f16_f32 v175, v76, v77
	v_mul_f32_e32 v150, v79, v79
	v_mul_f32_e32 v151, v81, v81
	v_fmac_f32_e32 v150, v78, v78
	v_fmac_f32_e32 v151, v80, v80
	v_add_f32_e32 v152, v150, v151
	v_add_f32_e32 v160, v160, v152
	v_cvt_pk_f16_f32 v176, v78, v79
	v_cvt_pk_f16_f32 v177, v80, v81
	global_store_dwordx2 v144, v[170:171], s[10:11]
	global_store_dwordx2 v144, v[172:173], s[10:11] offset:512
	global_store_dwordx2 v144, v[174:175], s[10:11] offset:1024
	global_store_dwordx2 v144, v[176:177], s[10:11] offset:1536
	v_mul_f32_e32 v150, v83, v83
	v_mul_f32_e32 v151, v85, v85
	v_fmac_f32_e32 v150, v82, v82
	v_fmac_f32_e32 v151, v84, v84
	v_add_f32_e32 v161, v150, v151
	v_cvt_pk_f16_f32 v178, v82, v83
	v_cvt_pk_f16_f32 v179, v84, v85
	v_mul_f32_e32 v150, v87, v87
	v_mul_f32_e32 v151, v89, v89
	v_fmac_f32_e32 v150, v86, v86
	v_fmac_f32_e32 v151, v88, v88
	v_add_f32_e32 v152, v150, v151
	v_add_f32_e32 v161, v161, v152
	v_cvt_pk_f16_f32 v180, v86, v87
	v_cvt_pk_f16_f32 v181, v88, v89
	v_mul_f32_e32 v150, v91, v91
	v_mul_f32_e32 v151, v93, v93
	v_fmac_f32_e32 v150, v90, v90
	v_fmac_f32_e32 v151, v92, v92
	v_add_f32_e32 v152, v150, v151
	v_add_f32_e32 v161, v161, v152
	v_cvt_pk_f16_f32 v182, v90, v91
	v_cvt_pk_f16_f32 v183, v92, v93
	v_mul_f32_e32 v150, v95, v95
	v_mul_f32_e32 v151, v97, v97
	v_fmac_f32_e32 v150, v94, v94
	v_fmac_f32_e32 v151, v96, v96
	v_add_f32_e32 v152, v150, v151
	v_add_f32_e32 v161, v161, v152
	v_cvt_pk_f16_f32 v184, v94, v95
	v_cvt_pk_f16_f32 v185, v96, v97
	global_store_dwordx2 v145, v[178:179], s[10:11]
	global_store_dwordx2 v145, v[180:181], s[10:11] offset:512
	global_store_dwordx2 v145, v[182:183], s[10:11] offset:1024
	global_store_dwordx2 v145, v[184:185], s[10:11] offset:1536
	v_mul_f32_e32 v150, v99, v99
	v_mul_f32_e32 v151, v101, v101
	v_fmac_f32_e32 v150, v98, v98
	v_fmac_f32_e32 v151, v100, v100
	v_add_f32_e32 v162, v150, v151
	v_cvt_pk_f16_f32 v170, v98, v99
	v_cvt_pk_f16_f32 v171, v100, v101
	v_mul_f32_e32 v150, v103, v103
	v_mul_f32_e32 v151, v105, v105
	v_fmac_f32_e32 v150, v102, v102
	v_fmac_f32_e32 v151, v104, v104
	v_add_f32_e32 v152, v150, v151
	v_add_f32_e32 v162, v162, v152
	v_cvt_pk_f16_f32 v172, v102, v103
	v_cvt_pk_f16_f32 v173, v104, v105
	v_mul_f32_e32 v150, v107, v107
	v_mul_f32_e32 v151, v109, v109
	v_fmac_f32_e32 v150, v106, v106
	v_fmac_f32_e32 v151, v108, v108
	v_add_f32_e32 v152, v150, v151
	v_add_f32_e32 v162, v162, v152
	v_cvt_pk_f16_f32 v174, v106, v107
	v_cvt_pk_f16_f32 v175, v108, v109
	v_mul_f32_e32 v150, v111, v111
	v_mul_f32_e32 v151, v113, v113
	v_fmac_f32_e32 v150, v110, v110
	v_fmac_f32_e32 v151, v112, v112
	v_add_f32_e32 v152, v150, v151
	v_add_f32_e32 v162, v162, v152
	v_cvt_pk_f16_f32 v176, v110, v111
	v_cvt_pk_f16_f32 v177, v112, v113
	global_store_dwordx2 v146, v[170:171], s[10:11]
	global_store_dwordx2 v146, v[172:173], s[10:11] offset:512
	global_store_dwordx2 v146, v[174:175], s[10:11] offset:1024
	global_store_dwordx2 v146, v[176:177], s[10:11] offset:1536
	v_mul_f32_e32 v150, v115, v115
	v_mul_f32_e32 v151, v117, v117
	v_fmac_f32_e32 v150, v114, v114
	v_fmac_f32_e32 v151, v116, v116
	v_add_f32_e32 v163, v150, v151
	v_cvt_pk_f16_f32 v178, v114, v115
	v_cvt_pk_f16_f32 v179, v116, v117
	v_mul_f32_e32 v150, v119, v119
	v_mul_f32_e32 v151, v121, v121
	v_fmac_f32_e32 v150, v118, v118
	v_fmac_f32_e32 v151, v120, v120
	v_add_f32_e32 v152, v150, v151
	v_add_f32_e32 v163, v163, v152
	v_cvt_pk_f16_f32 v180, v118, v119
	v_cvt_pk_f16_f32 v181, v120, v121
	v_mul_f32_e32 v150, v123, v123
	v_mul_f32_e32 v151, v125, v125
	v_fmac_f32_e32 v150, v122, v122
	v_fmac_f32_e32 v151, v124, v124
	v_add_f32_e32 v152, v150, v151
	v_add_f32_e32 v163, v163, v152
	v_cvt_pk_f16_f32 v182, v122, v123
	v_cvt_pk_f16_f32 v183, v124, v125
	v_mul_f32_e32 v150, v127, v127
	v_mul_f32_e32 v151, v129, v129
	v_fmac_f32_e32 v150, v126, v126
	v_fmac_f32_e32 v151, v128, v128
	v_add_f32_e32 v152, v150, v151
	v_add_f32_e32 v163, v163, v152
	v_cvt_pk_f16_f32 v184, v126, v127
	v_cvt_pk_f16_f32 v185, v128, v129
	global_store_dwordx2 v147, v[178:179], s[10:11]
	global_store_dwordx2 v147, v[180:181], s[10:11] offset:512
	global_store_dwordx2 v147, v[182:183], s[10:11] offset:1024
	global_store_dwordx2 v147, v[184:185], s[10:11] offset:1536
	ds_bpermute_b32 v164, v130, v160
	ds_bpermute_b32 v165, v130, v161
	ds_bpermute_b32 v166, v130, v162
	ds_bpermute_b32 v167, v130, v163
	s_waitcnt lgkmcnt(0)
; __device__ void p0_xconv(const Args& a) {
;     ...
;         for (int r = 0; r < 4; ++r) {
;             const int row = row0 + r * nwv;
;             if (row < MROWS) {
;                 const float* src = (row < ROWS_PROMPT) ? a.x_prompt + (size_t)row * DM : a.x_sample + (size_t)(row - ROWS_PROMPT) * DM;
; #pragma unroll
;                 for (int i = 0; i < 4; ++i) v[r][i] = __builtin_nontemporal_load((const f32x4*)(src + i * 256 + lane * 4));
;             }
;         }
; #pragma unroll
;         for (int r = 0; r < 4; ++r) {
;             const int row = row0 + r * nwv;
;             if (row < MROWS) {
;                 float ss = 0.f;
; #pragma unroll
;                 for (int i = 0; i < 4; ++i) {
;                     const f32x4 x = v[r][i];
;                     ss += (x[0] * x[0] + x[1] * x[1]) + (x[2] * x[2] + x[3] * x[3]);
;                     f16x4 h; h[0] = (f16)x[0]; h[1] = (f16)x[1]; h[2] = (f16)x[2]; h[3] = (f16)x[3];
;                     *(f16x4*)(XH + (size_t)row * DM + i * 256 + lane * 4) = h;
;                 }
; #pragma unroll
;                 for (int o = 1; o < 64; o <<= 1) ss += __shfl_xor(ss, o);
;                 if (lane < 16) SS[(size_t)row * 16 + lane] = (lane == 0) ? ss : 0.f;
;             }
	v_add_f32_e32 v160, v160, v164
	v_add_f32_e32 v161, v161, v165
	v_add_f32_e32 v162, v162, v166
	v_add_f32_e32 v163, v163, v167
	ds_bpermute_b32 v164, v131, v160
	ds_bpermute_b32 v165, v131, v161
	ds_bpermute_b32 v166, v131, v162
	ds_bpermute_b32 v167, v131, v163
	s_waitcnt lgkmcnt(0)
	v_add_f32_e32 v160, v160, v164
	v_add_f32_e32 v161, v161, v165
	v_add_f32_e32 v162, v162, v166
	v_add_f32_e32 v163, v163, v167
	ds_bpermute_b32 v164, v132, v160
	ds_bpermute_b32 v165, v132, v161
	ds_bpermute_b32 v166, v132, v162
	ds_bpermute_b32 v167, v132, v163
	s_waitcnt lgkmcnt(0)
	v_add_f32_e32 v160, v160, v164
	v_add_f32_e32 v161, v161, v165
	v_add_f32_e32 v162, v162, v166
	v_add_f32_e32 v163, v163, v167
	ds_bpermute_b32 v164, v133, v160
	ds_bpermute_b32 v165, v133, v161
	ds_bpermute_b32 v166, v133, v162
	ds_bpermute_b32 v167, v133, v163
	s_waitcnt lgkmcnt(0)
	v_add_f32_e32 v160, v160, v164
	v_add_f32_e32 v161, v161, v165
	v_add_f32_e32 v162, v162, v166
	v_add_f32_e32 v163, v163, v167
	ds_bpermute_b32 v164, v134, v160
	ds_bpermute_b32 v165, v134, v161
	ds_bpermute_b32 v166, v134, v162
	ds_bpermute_b32 v167, v134, v163
	s_waitcnt lgkmcnt(0)
	v_add_f32_e32 v160, v160, v164
	v_add_f32_e32 v161, v161, v165
	v_add_f32_e32 v162, v162, v166
	v_add_f32_e32 v163, v163, v167
	ds_bpermute_b32 v164, v135, v160
	ds_bpermute_b32 v165, v135, v161
	ds_bpermute_b32 v166, v135, v162
	ds_bpermute_b32 v167, v135, v163
	s_waitcnt lgkmcnt(0)
	v_add_f32_e32 v160, v160, v164
	v_add_f32_e32 v161, v161, v165
	v_add_f32_e32 v162, v162, v166
	v_add_f32_e32 v163, v163, v167
	v_cndmask_b32_e64 v164, 0, v160, s[12:13]
	v_cndmask_b32_e64 v165, 0, v161, s[12:13]
	v_cndmask_b32_e64 v166, 0, v162, s[12:13]
	v_cndmask_b32_e64 v167, 0, v163, s[12:13]
	s_mov_b64 exec, 0xffff
	global_store_dword v186, v164, s[6:7]
	global_store_dword v187, v165, s[6:7]
	global_store_dword v188, v166, s[6:7]
	global_store_dword v189, v167, s[6:7]
	s_mov_b64 exec, -1
	s_add_i32 s6, s3, 0x3000
	s_lshl_b32 s6, s6, 12
	s_add_u32 s4, s16, s6
	s_addc_u32 s5, s17, 0
	global_load_dwordx4 v[66:69], v140, s[4:5] nt
	global_load_dwordx4 v[70:73], v140, s[4:5] offset:1024 nt
	global_load_dwordx4 v[74:77], v140, s[4:5] offset:2048 nt
	global_load_dwordx4 v[78:81], v140, s[4:5] offset:3072 nt
	global_load_dwordx4 v[82:85], v141, s[4:5] nt
	global_load_dwordx4 v[86:89], v141, s[4:5] offset:1024 nt
	global_load_dwordx4 v[90:93], v141, s[4:5] offset:2048 nt
	global_load_dwordx4 v[94:97], v141, s[4:5] offset:3072 nt
	global_load_dwordx4 v[98:101], v142, s[4:5] nt
	global_load_dwordx4 v[102:105], v142, s[4:5] offset:1024 nt
	global_load_dwordx4 v[106:109], v142, s[4:5] offset:2048 nt
	global_load_dwordx4 v[110:113], v142, s[4:5] offset:3072 nt
	global_load_dwordx4 v[114:117], v143, s[4:5] nt
	global_load_dwordx4 v[118:121], v143, s[4:5] offset:1024 nt
	global_load_dwordx4 v[122:125], v143, s[4:5] offset:2048 nt
	global_load_dwordx4 v[126:129], v143, s[4:5] offset:3072 nt
	s_waitcnt vmcnt(36)
	s_add_i32 s6, s3, 0x2000
	s_lshl_b32 s7, s6, 11
	s_add_u32 s10, s40, s7
	s_addc_u32 s11, s41, 0
	s_lshl_b32 s7, s6, 6
	s_add_u32 s6, s40, s7
	s_addc_u32 s7, s41, 0
	s_add_u32 s6, s6, 0x1f800000
	s_addc_u32 s7, s7, 0
	v_mul_f32_e32 v150, v3, v3
	v_mul_f32_e32 v151, v5, v5
	v_fmac_f32_e32 v150, v2, v2
	v_fmac_f32_e32 v151, v4, v4
	v_add_f32_e32 v160, v150, v151
	v_cvt_pk_f16_f32 v170, v2, v3
	v_cvt_pk_f16_f32 v171, v4, v5
	v_mul_f32_e32 v150, v7, v7
	v_mul_f32_e32 v151, v9, v9
	v_fmac_f32_e32 v150, v6, v6
	v_fmac_f32_e32 v151, v8, v8
	v_add_f32_e32 v152, v150, v151
	v_add_f32_e32 v160, v160, v152
	v_cvt_pk_f16_f32 v172, v6, v7
	v_cvt_pk_f16_f32 v173, v8, v9
	v_mul_f32_e32 v150, v11, v11
	v_mul_f32_e32 v151, v13, v13
	v_fmac_f32_e32 v150, v10, v10
	v_fmac_f32_e32 v151, v12, v12
	v_add_f32_e32 v152, v150, v151
	v_add_f32_e32 v160, v160, v152
	v_cvt_pk_f16_f32 v174, v10, v11
	v_cvt_pk_f16_f32 v175, v12, v13
	v_mul_f32_e32 v150, v15, v15
	v_mul_f32_e32 v151, v17, v17
	v_fmac_f32_e32 v150, v14, v14
	v_fmac_f32_e32 v151, v16, v16
	v_add_f32_e32 v152, v150, v151
	v_add_f32_e32 v160, v160, v152
	v_cvt_pk_f16_f32 v176, v14, v15
	v_cvt_pk_f16_f32 v177, v16, v17
	global_store_dwordx2 v144, v[170:171], s[10:11]
	global_store_dwordx2 v144, v[172:173], s[10:11] offset:512
	global_store_dwordx2 v144, v[174:175], s[10:11] offset:1024
	global_store_dwordx2 v144, v[176:177], s[10:11] offset:1536
	v_mul_f32_e32 v150, v19, v19
	v_mul_f32_e32 v151, v21, v21
	v_fmac_f32_e32 v150, v18, v18
	v_fmac_f32_e32 v151, v20, v20
	v_add_f32_e32 v161, v150, v151
	v_cvt_pk_f16_f32 v178, v18, v19
	v_cvt_pk_f16_f32 v179, v20, v21
	v_mul_f32_e32 v150, v23, v23
	v_mul_f32_e32 v151, v25, v25
	v_fmac_f32_e32 v150, v22, v22
	v_fmac_f32_e32 v151, v24, v24
	v_add_f32_e32 v152, v150, v151
	v_add_f32_e32 v161, v161, v152
	v_cvt_pk_f16_f32 v180, v22, v23
	v_cvt_pk_f16_f32 v181, v24, v25
	v_mul_f32_e32 v150, v27, v27
	v_mul_f32_e32 v151, v29, v29
	v_fmac_f32_e32 v150, v26, v26
	v_fmac_f32_e32 v151, v28, v28
	v_add_f32_e32 v152, v150, v151
	v_add_f32_e32 v161, v161, v152
	v_cvt_pk_f16_f32 v182, v26, v27
	v_cvt_pk_f16_f32 v183, v28, v29
	v_mul_f32_e32 v150, v31, v31
	v_mul_f32_e32 v151, v33, v33
	v_fmac_f32_e32 v150, v30, v30
	v_fmac_f32_e32 v151, v32, v32
	v_add_f32_e32 v152, v150, v151
	v_add_f32_e32 v161, v161, v152
	v_cvt_pk_f16_f32 v184, v30, v31
	v_cvt_pk_f16_f32 v185, v32, v33
	global_store_dwordx2 v145, v[178:179], s[10:11]
	global_store_dwordx2 v145, v[180:181], s[10:11] offset:512
	global_store_dwordx2 v145, v[182:183], s[10:11] offset:1024
	global_store_dwordx2 v145, v[184:185], s[10:11] offset:1536
	v_mul_f32_e32 v150, v35, v35
	v_mul_f32_e32 v151, v37, v37
	v_fmac_f32_e32 v150, v34, v34
; __device__ void p0_xconv(const Args& a) {
;     ...
;         for (int r = 0; r < 4; ++r) {
;             const int row = row0 + r * nwv;
;             if (row < MROWS) {
;                 const float* src = (row < ROWS_PROMPT) ? a.x_prompt + (size_t)row * DM : a.x_sample + (size_t)(row - ROWS_PROMPT) * DM;
; #pragma unroll
;                 for (int i = 0; i < 4; ++i) v[r][i] = __builtin_nontemporal_load((const f32x4*)(src + i * 256 + lane * 4));
;             }
;         }
; #pragma unroll
;         for (int r = 0; r < 4; ++r) {
;             const int row = row0 + r * nwv;
;             if (row < MROWS) {
;                 float ss = 0.f;
; #pragma unroll
;                 for (int i = 0; i < 4; ++i) {
;                     const f32x4 x = v[r][i];
;                     ss += (x[0] * x[0] + x[1] * x[1]) + (x[2] * x[2] + x[3] * x[3]);
;                     f16x4 h; h[0] = (f16)x[0]; h[1] = (f16)x[1]; h[2] = (f16)x[2]; h[3] = (f16)x[3];
;                     *(f16x4*)(XH + (size_t)row * DM + i * 256 + lane * 4) = h;
;                 }
; #pragma unroll
;                 for (int o = 1; o < 64; o <<= 1) ss += __shfl_xor(ss, o);
;                 if (lane < 16) SS[(size_t)row * 16 + lane] = (lane == 0) ? ss : 0.f;
;             }
	v_fmac_f32_e32 v151, v36, v36
	v_add_f32_e32 v162, v150, v151
	v_cvt_pk_f16_f32 v170, v34, v35
	v_cvt_pk_f16_f32 v171, v36, v37
	v_mul_f32_e32 v150, v39, v39
	v_mul_f32_e32 v151, v41, v41
	v_fmac_f32_e32 v150, v38, v38
	v_fmac_f32_e32 v151, v40, v40
	v_add_f32_e32 v152, v150, v151
	v_add_f32_e32 v162, v162, v152
	v_cvt_pk_f16_f32 v172, v38, v39
	v_cvt_pk_f16_f32 v173, v40, v41
	v_mul_f32_e32 v150, v43, v43
	v_mul_f32_e32 v151, v45, v45
	v_fmac_f32_e32 v150, v42, v42
	v_fmac_f32_e32 v151, v44, v44
	v_add_f32_e32 v152, v150, v151
	v_add_f32_e32 v162, v162, v152
	v_cvt_pk_f16_f32 v174, v42, v43
	v_cvt_pk_f16_f32 v175, v44, v45
	v_mul_f32_e32 v150, v47, v47
	v_mul_f32_e32 v151, v49, v49
	v_fmac_f32_e32 v150, v46, v46
	v_fmac_f32_e32 v151, v48, v48
	v_add_f32_e32 v152, v150, v151
	v_add_f32_e32 v162, v162, v152
	v_cvt_pk_f16_f32 v176, v46, v47
	v_cvt_pk_f16_f32 v177, v48, v49
	global_store_dwordx2 v146, v[170:171], s[10:11]
	global_store_dwordx2 v146, v[172:173], s[10:11] offset:512
	global_store_dwordx2 v146, v[174:175], s[10:11] offset:1024
	global_store_dwordx2 v146, v[176:177], s[10:11] offset:1536
	v_mul_f32_e32 v150, v51, v51
	v_mul_f32_e32 v151, v53, v53
	v_fmac_f32_e32 v150, v50, v50
	v_fmac_f32_e32 v151, v52, v52
	v_add_f32_e32 v163, v150, v151
	v_cvt_pk_f16_f32 v178, v50, v51
	v_cvt_pk_f16_f32 v179, v52, v53
	v_mul_f32_e32 v150, v55, v55
	v_mul_f32_e32 v151, v57, v57
	v_fmac_f32_e32 v150, v54, v54
	v_fmac_f32_e32 v151, v56, v56
	v_add_f32_e32 v152, v150, v151
	v_add_f32_e32 v163, v163, v152
	v_cvt_pk_f16_f32 v180, v54, v55
	v_cvt_pk_f16_f32 v181, v56, v57
	v_mul_f32_e32 v150, v59, v59
	v_mul_f32_e32 v151, v61, v61
	v_fmac_f32_e32 v150, v58, v58
	v_fmac_f32_e32 v151, v60, v60
	v_add_f32_e32 v152, v150, v151
	v_add_f32_e32 v163, v163, v152
	v_cvt_pk_f16_f32 v182, v58, v59
	v_cvt_pk_f16_f32 v183, v60, v61
	v_mul_f32_e32 v150, v63, v63
	v_mul_f32_e32 v151, v65, v65
	v_fmac_f32_e32 v150, v62, v62
	v_fmac_f32_e32 v151, v64, v64
	v_add_f32_e32 v152, v150, v151
	v_add_f32_e32 v163, v163, v152
	v_cvt_pk_f16_f32 v184, v62, v63
	v_cvt_pk_f16_f32 v185, v64, v65
	global_store_dwordx2 v147, v[178:179], s[10:11]
	global_store_dwordx2 v147, v[180:181], s[10:11] offset:512
	global_store_dwordx2 v147, v[182:183], s[10:11] offset:1024
	global_store_dwordx2 v147, v[184:185], s[10:11] offset:1536
	ds_bpermute_b32 v164, v130, v160
	ds_bpermute_b32 v165, v130, v161
	ds_bpermute_b32 v166, v130, v162
	ds_bpermute_b32 v167, v130, v163
	s_waitcnt lgkmcnt(0)
	v_add_f32_e32 v160, v160, v164
	v_add_f32_e32 v161, v161, v165
	v_add_f32_e32 v162, v162, v166
	v_add_f32_e32 v163, v163, v167
	ds_bpermute_b32 v164, v131, v160
	ds_bpermute_b32 v165, v131, v161
	ds_bpermute_b32 v166, v131, v162
	ds_bpermute_b32 v167, v131, v163
	s_waitcnt lgkmcnt(0)
	v_add_f32_e32 v160, v160, v164
	v_add_f32_e32 v161, v161, v165
	v_add_f32_e32 v162, v162, v166
	v_add_f32_e32 v163, v163, v167
	ds_bpermute_b32 v164, v132, v160
	ds_bpermute_b32 v165, v132, v161
	ds_bpermute_b32 v166, v132, v162
	ds_bpermute_b32 v167, v132, v163
	s_waitcnt lgkmcnt(0)
	v_add_f32_e32 v160, v160, v164
	v_add_f32_e32 v161, v161, v165
	v_add_f32_e32 v162, v162, v166
	v_add_f32_e32 v163, v163, v167
	ds_bpermute_b32 v164, v133, v160
	ds_bpermute_b32 v165, v133, v161
	ds_bpermute_b32 v166, v133, v162
	ds_bpermute_b32 v167, v133, v163
	s_waitcnt lgkmcnt(0)
	v_add_f32_e32 v160, v160, v164
	v_add_f32_e32 v161, v161, v165
	v_add_f32_e32 v162, v162, v166
	v_add_f32_e32 v163, v163, v167
	ds_bpermute_b32 v164, v134, v160
	ds_bpermute_b32 v165, v134, v161
	ds_bpermute_b32 v166, v134, v162
	ds_bpermute_b32 v167, v134, v163
	s_waitcnt lgkmcnt(0)
	v_add_f32_e32 v160, v160, v164
	v_add_f32_e32 v161, v161, v165
	v_add_f32_e32 v162, v162, v166
	v_add_f32_e32 v163, v163, v167
	ds_bpermute_b32 v164, v135, v160
	ds_bpermute_b32 v165, v135, v161
	ds_bpermute_b32 v166, v135, v162
	ds_bpermute_b32 v167, v135, v163
	s_waitcnt lgkmcnt(0)
	v_add_f32_e32 v160, v160, v164
	v_add_f32_e32 v161, v161, v165
	v_add_f32_e32 v162, v162, v166
	v_add_f32_e32 v163, v163, v167
	v_cndmask_b32_e64 v164, 0, v160, s[12:13]
	v_cndmask_b32_e64 v165, 0, v161, s[12:13]
	v_cndmask_b32_e64 v166, 0, v162, s[12:13]
	v_cndmask_b32_e64 v167, 0, v163, s[12:13]
	s_mov_b64 exec, 0xffff
	global_store_dword v186, v164, s[6:7]
	global_store_dword v187, v165, s[6:7]
	global_store_dword v188, v166, s[6:7]
	global_store_dword v189, v167, s[6:7]
	s_mov_b64 exec, -1
	s_add_i32 s6, s3, 0x0
	s_lshl_b32 s6, s6, 12
	s_add_u32 s4, s18, s6
	s_addc_u32 s5, s19, 0
	global_load_dwordx4 v[2:5], v140, s[4:5] nt
	global_load_dwordx4 v[6:9], v140, s[4:5] offset:1024 nt
	global_load_dwordx4 v[10:13], v140, s[4:5] offset:2048 nt
	global_load_dwordx4 v[14:17], v140, s[4:5] offset:3072 nt
	global_load_dwordx4 v[18:21], v141, s[4:5] nt
	global_load_dwordx4 v[22:25], v141, s[4:5] offset:1024 nt
	global_load_dwordx4 v[26:29], v141, s[4:5] offset:2048 nt
	global_load_dwordx4 v[30:33], v141, s[4:5] offset:3072 nt
	global_load_dwordx4 v[34:37], v142, s[4:5] nt
	global_load_dwordx4 v[38:41], v142, s[4:5] offset:1024 nt
	global_load_dwordx4 v[42:45], v142, s[4:5] offset:2048 nt
	global_load_dwordx4 v[46:49], v142, s[4:5] offset:3072 nt
	global_load_dwordx4 v[50:53], v143, s[4:5] nt
	global_load_dwordx4 v[54:57], v143, s[4:5] offset:1024 nt
	global_load_dwordx4 v[58:61], v143, s[4:5] offset:2048 nt
	global_load_dwordx4 v[62:65], v143, s[4:5] offset:3072 nt
	s_waitcnt vmcnt(36)
; __device__ void p0_xconv(const Args& a) {
;     ...
;         for (int r = 0; r < 4; ++r) {
;             const int row = row0 + r * nwv;
;             if (row < MROWS) {
;                 float ss = 0.f;
; #pragma unroll
;                 for (int i = 0; i < 4; ++i) {
;                     const f32x4 x = v[r][i];
;                     ss += (x[0] * x[0] + x[1] * x[1]) + (x[2] * x[2] + x[3] * x[3]);
;                     f16x4 h; h[0] = (f16)x[0]; h[1] = (f16)x[1]; h[2] = (f16)x[2]; h[3] = (f16)x[3];
;                     *(f16x4*)(XH + (size_t)row * DM + i * 256 + lane * 4) = h;
;                 }
; #pragma unroll
;                 for (int o = 1; o < 64; o <<= 1) ss += __shfl_xor(ss, o);
	s_add_i32 s6, s3, 0x3000
	s_lshl_b32 s7, s6, 11
	s_add_u32 s10, s40, s7
	s_addc_u32 s11, s41, 0
	s_lshl_b32 s7, s6, 6
	s_add_u32 s6, s40, s7
	s_addc_u32 s7, s41, 0
	s_add_u32 s6, s6, 0x1f800000
	s_addc_u32 s7, s7, 0
	v_mul_f32_e32 v150, v67, v67
	v_mul_f32_e32 v151, v69, v69
	v_fmac_f32_e32 v150, v66, v66
	v_fmac_f32_e32 v151, v68, v68
	v_add_f32_e32 v160, v150, v151
	v_cvt_pk_f16_f32 v170, v66, v67
	v_cvt_pk_f16_f32 v171, v68, v69
	v_mul_f32_e32 v150, v71, v71
	v_mul_f32_e32 v151, v73, v73
	v_fmac_f32_e32 v150, v70, v70
	v_fmac_f32_e32 v151, v72, v72
	v_add_f32_e32 v152, v150, v151
	v_add_f32_e32 v160, v160, v152
	v_cvt_pk_f16_f32 v172, v70, v71
	v_cvt_pk_f16_f32 v173, v72, v73
	v_mul_f32_e32 v150, v75, v75
	v_mul_f32_e32 v151, v77, v77
	v_fmac_f32_e32 v150, v74, v74
	v_fmac_f32_e32 v151, v76, v76
	v_add_f32_e32 v152, v150, v151
	v_add_f32_e32 v160, v160, v152
	v_cvt_pk_f16_f32 v174, v74, v75
	v_cvt_pk_f16_f32 v175, v76, v77
	v_mul_f32_e32 v150, v79, v79
	v_mul_f32_e32 v151, v81, v81
	v_fmac_f32_e32 v150, v78, v78
	v_fmac_f32_e32 v151, v80, v80
	v_add_f32_e32 v152, v150, v151
	v_add_f32_e32 v160, v160, v152
	v_cvt_pk_f16_f32 v176, v78, v79
	v_cvt_pk_f16_f32 v177, v80, v81
	global_store_dwordx2 v144, v[170:171], s[10:11]
	global_store_dwordx2 v144, v[172:173], s[10:11] offset:512
	global_store_dwordx2 v144, v[174:175], s[10:11] offset:1024
	global_store_dwordx2 v144, v[176:177], s[10:11] offset:1536
	v_mul_f32_e32 v150, v83, v83
	v_mul_f32_e32 v151, v85, v85
	v_fmac_f32_e32 v150, v82, v82
	v_fmac_f32_e32 v151, v84, v84
	v_add_f32_e32 v161, v150, v151
	v_cvt_pk_f16_f32 v178, v82, v83
	v_cvt_pk_f16_f32 v179, v84, v85
	v_mul_f32_e32 v150, v87, v87
	v_mul_f32_e32 v151, v89, v89
	v_fmac_f32_e32 v150, v86, v86
	v_fmac_f32_e32 v151, v88, v88
	v_add_f32_e32 v152, v150, v151
	v_add_f32_e32 v161, v161, v152
	v_cvt_pk_f16_f32 v180, v86, v87
	v_cvt_pk_f16_f32 v181, v88, v89
	v_mul_f32_e32 v150, v91, v91
	v_mul_f32_e32 v151, v93, v93
	v_fmac_f32_e32 v150, v90, v90
	v_fmac_f32_e32 v151, v92, v92
	v_add_f32_e32 v152, v150, v151
	v_add_f32_e32 v161, v161, v152
	v_cvt_pk_f16_f32 v182, v90, v91
	v_cvt_pk_f16_f32 v183, v92, v93
	v_mul_f32_e32 v150, v95, v95
	v_mul_f32_e32 v151, v97, v97
	v_fmac_f32_e32 v150, v94, v94
	v_fmac_f32_e32 v151, v96, v96
	v_add_f32_e32 v152, v150, v151
	v_add_f32_e32 v161, v161, v152
	v_cvt_pk_f16_f32 v184, v94, v95
	v_cvt_pk_f16_f32 v185, v96, v97
	global_store_dwordx2 v145, v[178:179], s[10:11]
	global_store_dwordx2 v145, v[180:181], s[10:11] offset:512
	global_store_dwordx2 v145, v[182:183], s[10:11] offset:1024
	global_store_dwordx2 v145, v[184:185], s[10:11] offset:1536
	v_mul_f32_e32 v150, v99, v99
	v_mul_f32_e32 v151, v101, v101
	v_fmac_f32_e32 v150, v98, v98
	v_fmac_f32_e32 v151, v100, v100
	v_add_f32_e32 v162, v150, v151
	v_cvt_pk_f16_f32 v170, v98, v99
	v_cvt_pk_f16_f32 v171, v100, v101
	v_mul_f32_e32 v150, v103, v103
	v_mul_f32_e32 v151, v105, v105
	v_fmac_f32_e32 v150, v102, v102
	v_fmac_f32_e32 v151, v104, v104
	v_add_f32_e32 v152, v150, v151
	v_add_f32_e32 v162, v162, v152
	v_cvt_pk_f16_f32 v172, v102, v103
	v_cvt_pk_f16_f32 v173, v104, v105
	v_mul_f32_e32 v150, v107, v107
	v_mul_f32_e32 v151, v109, v109
	v_fmac_f32_e32 v150, v106, v106
	v_fmac_f32_e32 v151, v108, v108
	v_add_f32_e32 v152, v150, v151
	v_add_f32_e32 v162, v162, v152
	v_cvt_pk_f16_f32 v174, v106, v107
	v_cvt_pk_f16_f32 v175, v108, v109
	v_mul_f32_e32 v150, v111, v111
	v_mul_f32_e32 v151, v113, v113
	v_fmac_f32_e32 v150, v110, v110
	v_fmac_f32_e32 v151, v112, v112
	v_add_f32_e32 v152, v150, v151
	v_add_f32_e32 v162, v162, v152
	v_cvt_pk_f16_f32 v176, v110, v111
	v_cvt_pk_f16_f32 v177, v112, v113
	global_store_dwordx2 v146, v[170:171], s[10:11]
	global_store_dwordx2 v146, v[172:173], s[10:11] offset:512
	global_store_dwordx2 v146, v[174:175], s[10:11] offset:1024
	global_store_dwordx2 v146, v[176:177], s[10:11] offset:1536
	v_mul_f32_e32 v150, v115, v115
	v_mul_f32_e32 v151, v117, v117
	v_fmac_f32_e32 v150, v114, v114
	v_fmac_f32_e32 v151, v116, v116
	v_add_f32_e32 v163, v150, v151
	v_cvt_pk_f16_f32 v178, v114, v115
	v_cvt_pk_f16_f32 v179, v116, v117
	v_mul_f32_e32 v150, v119, v119
	v_mul_f32_e32 v151, v121, v121
	v_fmac_f32_e32 v150, v118, v118
	v_fmac_f32_e32 v151, v120, v120
	v_add_f32_e32 v152, v150, v151
	v_add_f32_e32 v163, v163, v152
	v_cvt_pk_f16_f32 v180, v118, v119
	v_cvt_pk_f16_f32 v181, v120, v121
	v_mul_f32_e32 v150, v123, v123
	v_mul_f32_e32 v151, v125, v125
	v_fmac_f32_e32 v150, v122, v122
	v_fmac_f32_e32 v151, v124, v124
	v_add_f32_e32 v152, v150, v151
	v_add_f32_e32 v163, v163, v152
	v_cvt_pk_f16_f32 v182, v122, v123
	v_cvt_pk_f16_f32 v183, v124, v125
	v_mul_f32_e32 v150, v127, v127
	v_mul_f32_e32 v151, v129, v129
	v_fmac_f32_e32 v150, v126, v126
	v_fmac_f32_e32 v151, v128, v128
	v_add_f32_e32 v152, v150, v151
	v_add_f32_e32 v163, v163, v152
	v_cvt_pk_f16_f32 v184, v126, v127
	v_cvt_pk_f16_f32 v185, v128, v129
	global_store_dwordx2 v147, v[178:179], s[10:11]
	global_store_dwordx2 v147, v[180:181], s[10:11] offset:512
	global_store_dwordx2 v147, v[182:183], s[10:11] offset:1024
	global_store_dwordx2 v147, v[184:185], s[10:11] offset:1536
	ds_bpermute_b32 v164, v130, v160
	ds_bpermute_b32 v165, v130, v161
	ds_bpermute_b32 v166, v130, v162
	ds_bpermute_b32 v167, v130, v163
	s_waitcnt lgkmcnt(0)
	v_add_f32_e32 v160, v160, v164
	v_add_f32_e32 v161, v161, v165
	v_add_f32_e32 v162, v162, v166
	v_add_f32_e32 v163, v163, v167
	ds_bpermute_b32 v164, v131, v160
	ds_bpermute_b32 v165, v131, v161
	ds_bpermute_b32 v166, v131, v162
	ds_bpermute_b32 v167, v131, v163
	s_waitcnt lgkmcnt(0)
; __device__ void p0_xconv(const Args& a) {
;     ...
;         for (int r = 0; r < 4; ++r) {
;             const int row = row0 + r * nwv;
;             if (row < MROWS) {
;                 const float* src = (row < ROWS_PROMPT) ? a.x_prompt + (size_t)row * DM : a.x_sample + (size_t)(row - ROWS_PROMPT) * DM;
; #pragma unroll
;                 for (int i = 0; i < 4; ++i) v[r][i] = __builtin_nontemporal_load((const f32x4*)(src + i * 256 + lane * 4));
;             }
;         }
; #pragma unroll
;         for (int r = 0; r < 4; ++r) {
;             const int row = row0 + r * nwv;
;             if (row < MROWS) {
;                 float ss = 0.f;
; #pragma unroll
;                 for (int i = 0; i < 4; ++i) {
;                     const f32x4 x = v[r][i];
;                     ss += (x[0] * x[0] + x[1] * x[1]) + (x[2] * x[2] + x[3] * x[3]);
;                     f16x4 h; h[0] = (f16)x[0]; h[1] = (f16)x[1]; h[2] = (f16)x[2]; h[3] = (f16)x[3];
;                     *(f16x4*)(XH + (size_t)row * DM + i * 256 + lane * 4) = h;
;                 }
; #pragma unroll
;                 for (int o = 1; o < 64; o <<= 1) ss += __shfl_xor(ss, o);
;                 if (lane < 16) SS[(size_t)row * 16 + lane] = (lane == 0) ? ss : 0.f;
;             }
	v_add_f32_e32 v160, v160, v164
	v_add_f32_e32 v161, v161, v165
	v_add_f32_e32 v162, v162, v166
	v_add_f32_e32 v163, v163, v167
	ds_bpermute_b32 v164, v132, v160
	ds_bpermute_b32 v165, v132, v161
	ds_bpermute_b32 v166, v132, v162
	ds_bpermute_b32 v167, v132, v163
	s_waitcnt lgkmcnt(0)
	v_add_f32_e32 v160, v160, v164
	v_add_f32_e32 v161, v161, v165
	v_add_f32_e32 v162, v162, v166
	v_add_f32_e32 v163, v163, v167
	ds_bpermute_b32 v164, v133, v160
	ds_bpermute_b32 v165, v133, v161
	ds_bpermute_b32 v166, v133, v162
	ds_bpermute_b32 v167, v133, v163
	s_waitcnt lgkmcnt(0)
	v_add_f32_e32 v160, v160, v164
	v_add_f32_e32 v161, v161, v165
	v_add_f32_e32 v162, v162, v166
	v_add_f32_e32 v163, v163, v167
	ds_bpermute_b32 v164, v134, v160
	ds_bpermute_b32 v165, v134, v161
	ds_bpermute_b32 v166, v134, v162
	ds_bpermute_b32 v167, v134, v163
	s_waitcnt lgkmcnt(0)
	v_add_f32_e32 v160, v160, v164
	v_add_f32_e32 v161, v161, v165
	v_add_f32_e32 v162, v162, v166
	v_add_f32_e32 v163, v163, v167
	ds_bpermute_b32 v164, v135, v160
	ds_bpermute_b32 v165, v135, v161
	ds_bpermute_b32 v166, v135, v162
	ds_bpermute_b32 v167, v135, v163
	s_waitcnt lgkmcnt(0)
	v_add_f32_e32 v160, v160, v164
	v_add_f32_e32 v161, v161, v165
	v_add_f32_e32 v162, v162, v166
	v_add_f32_e32 v163, v163, v167
	v_cndmask_b32_e64 v164, 0, v160, s[12:13]
	v_cndmask_b32_e64 v165, 0, v161, s[12:13]
	v_cndmask_b32_e64 v166, 0, v162, s[12:13]
	v_cndmask_b32_e64 v167, 0, v163, s[12:13]
	s_mov_b64 exec, 0xffff
	global_store_dword v186, v164, s[6:7]
	global_store_dword v187, v165, s[6:7]
	global_store_dword v188, v166, s[6:7]
	global_store_dword v189, v167, s[6:7]
	s_mov_b64 exec, -1
	s_add_i32 s6, s3, 0x1000
	s_lshl_b32 s6, s6, 12
	s_add_u32 s4, s18, s6
	s_addc_u32 s5, s19, 0
	global_load_dwordx4 v[66:69], v140, s[4:5] nt
	global_load_dwordx4 v[70:73], v140, s[4:5] offset:1024 nt
	global_load_dwordx4 v[74:77], v140, s[4:5] offset:2048 nt
	global_load_dwordx4 v[78:81], v140, s[4:5] offset:3072 nt
	global_load_dwordx4 v[82:85], v141, s[4:5] nt
	global_load_dwordx4 v[86:89], v141, s[4:5] offset:1024 nt
	global_load_dwordx4 v[90:93], v141, s[4:5] offset:2048 nt
	global_load_dwordx4 v[94:97], v141, s[4:5] offset:3072 nt
	global_load_dwordx4 v[98:101], v142, s[4:5] nt
	global_load_dwordx4 v[102:105], v142, s[4:5] offset:1024 nt
	global_load_dwordx4 v[106:109], v142, s[4:5] offset:2048 nt
	global_load_dwordx4 v[110:113], v142, s[4:5] offset:3072 nt
	global_load_dwordx4 v[114:117], v143, s[4:5] nt
	global_load_dwordx4 v[118:121], v143, s[4:5] offset:1024 nt
	global_load_dwordx4 v[122:125], v143, s[4:5] offset:2048 nt
	global_load_dwordx4 v[126:129], v143, s[4:5] offset:3072 nt
	s_waitcnt vmcnt(36)
	s_add_i32 s6, s3, 0x4000
	s_lshl_b32 s7, s6, 11
	s_add_u32 s10, s40, s7
	s_addc_u32 s11, s41, 0
	s_lshl_b32 s7, s6, 6
	s_add_u32 s6, s40, s7
	s_addc_u32 s7, s41, 0
	s_add_u32 s6, s6, 0x1f800000
	s_addc_u32 s7, s7, 0
	v_mul_f32_e32 v150, v3, v3
	v_mul_f32_e32 v151, v5, v5
	v_fmac_f32_e32 v150, v2, v2
	v_fmac_f32_e32 v151, v4, v4
	v_add_f32_e32 v160, v150, v151
	v_cvt_pk_f16_f32 v170, v2, v3
	v_cvt_pk_f16_f32 v171, v4, v5
	v_mul_f32_e32 v150, v7, v7
	v_mul_f32_e32 v151, v9, v9
	v_fmac_f32_e32 v150, v6, v6
	v_fmac_f32_e32 v151, v8, v8
	v_add_f32_e32 v152, v150, v151
	v_add_f32_e32 v160, v160, v152
	v_cvt_pk_f16_f32 v172, v6, v7
	v_cvt_pk_f16_f32 v173, v8, v9
	v_mul_f32_e32 v150, v11, v11
	v_mul_f32_e32 v151, v13, v13
	v_fmac_f32_e32 v150, v10, v10
	v_fmac_f32_e32 v151, v12, v12
	v_add_f32_e32 v152, v150, v151
	v_add_f32_e32 v160, v160, v152
	v_cvt_pk_f16_f32 v174, v10, v11
	v_cvt_pk_f16_f32 v175, v12, v13
	v_mul_f32_e32 v150, v15, v15
	v_mul_f32_e32 v151, v17, v17
	v_fmac_f32_e32 v150, v14, v14
	v_fmac_f32_e32 v151, v16, v16
	v_add_f32_e32 v152, v150, v151
	v_add_f32_e32 v160, v160, v152
	v_cvt_pk_f16_f32 v176, v14, v15
	v_cvt_pk_f16_f32 v177, v16, v17
	global_store_dwordx2 v144, v[170:171], s[10:11]
	global_store_dwordx2 v144, v[172:173], s[10:11] offset:512
	global_store_dwordx2 v144, v[174:175], s[10:11] offset:1024
	global_store_dwordx2 v144, v[176:177], s[10:11] offset:1536
	v_mul_f32_e32 v150, v19, v19
	v_mul_f32_e32 v151, v21, v21
	v_fmac_f32_e32 v150, v18, v18
	v_fmac_f32_e32 v151, v20, v20
	v_add_f32_e32 v161, v150, v151
	v_cvt_pk_f16_f32 v178, v18, v19
	v_cvt_pk_f16_f32 v179, v20, v21
	v_mul_f32_e32 v150, v23, v23
	v_mul_f32_e32 v151, v25, v25
	v_fmac_f32_e32 v150, v22, v22
	v_fmac_f32_e32 v151, v24, v24
	v_add_f32_e32 v152, v150, v151
	v_add_f32_e32 v161, v161, v152
	v_cvt_pk_f16_f32 v180, v22, v23
	v_cvt_pk_f16_f32 v181, v24, v25
	v_mul_f32_e32 v150, v27, v27
	v_mul_f32_e32 v151, v29, v29
	v_fmac_f32_e32 v150, v26, v26
	v_fmac_f32_e32 v151, v28, v28
	v_add_f32_e32 v152, v150, v151
	v_add_f32_e32 v161, v161, v152
	v_cvt_pk_f16_f32 v182, v26, v27
	v_cvt_pk_f16_f32 v183, v28, v29
	v_mul_f32_e32 v150, v31, v31
	v_mul_f32_e32 v151, v33, v33
	v_fmac_f32_e32 v150, v30, v30
	v_fmac_f32_e32 v151, v32, v32
	v_add_f32_e32 v152, v150, v151
	v_add_f32_e32 v161, v161, v152
	v_cvt_pk_f16_f32 v184, v30, v31
	v_cvt_pk_f16_f32 v185, v32, v33
	global_store_dwordx2 v145, v[178:179], s[10:11]
	global_store_dwordx2 v145, v[180:181], s[10:11] offset:512
	global_store_dwordx2 v145, v[182:183], s[10:11] offset:1024
	global_store_dwordx2 v145, v[184:185], s[10:11] offset:1536
	v_mul_f32_e32 v150, v35, v35
	v_mul_f32_e32 v151, v37, v37
	v_fmac_f32_e32 v150, v34, v34
	v_fmac_f32_e32 v151, v36, v36
	v_add_f32_e32 v162, v150, v151
	v_cvt_pk_f16_f32 v170, v34, v35
	v_cvt_pk_f16_f32 v171, v36, v37
	v_mul_f32_e32 v150, v39, v39
	v_mul_f32_e32 v151, v41, v41
	v_fmac_f32_e32 v150, v38, v38
	v_fmac_f32_e32 v151, v40, v40
	v_add_f32_e32 v152, v150, v151
; __device__ void p0_xconv(const Args& a) {
;     ...
;         for (int r = 0; r < 4; ++r) {
;             const int row = row0 + r * nwv;
;             if (row < MROWS) {
;                 const float* src = (row < ROWS_PROMPT) ? a.x_prompt + (size_t)row * DM : a.x_sample + (size_t)(row - ROWS_PROMPT) * DM;
; #pragma unroll
;                 for (int i = 0; i < 4; ++i) v[r][i] = __builtin_nontemporal_load((const f32x4*)(src + i * 256 + lane * 4));
;             }
;         }
; #pragma unroll
;         for (int r = 0; r < 4; ++r) {
;             const int row = row0 + r * nwv;
;             if (row < MROWS) {
;                 float ss = 0.f;
; #pragma unroll
;                 for (int i = 0; i < 4; ++i) {
;                     const f32x4 x = v[r][i];
;                     ss += (x[0] * x[0] + x[1] * x[1]) + (x[2] * x[2] + x[3] * x[3]);
;                     f16x4 h; h[0] = (f16)x[0]; h[1] = (f16)x[1]; h[2] = (f16)x[2]; h[3] = (f16)x[3];
;                     *(f16x4*)(XH + (size_t)row * DM + i * 256 + lane * 4) = h;
;                 }
; #pragma unroll
;                 for (int o = 1; o < 64; o <<= 1) ss += __shfl_xor(ss, o);
;                 if (lane < 16) SS[(size_t)row * 16 + lane] = (lane == 0) ? ss : 0.f;
;             }
	v_add_f32_e32 v162, v162, v152
	v_cvt_pk_f16_f32 v172, v38, v39
	v_cvt_pk_f16_f32 v173, v40, v41
	v_mul_f32_e32 v150, v43, v43
	v_mul_f32_e32 v151, v45, v45
	v_fmac_f32_e32 v150, v42, v42
	v_fmac_f32_e32 v151, v44, v44
	v_add_f32_e32 v152, v150, v151
	v_add_f32_e32 v162, v162, v152
	v_cvt_pk_f16_f32 v174, v42, v43
	v_cvt_pk_f16_f32 v175, v44, v45
	v_mul_f32_e32 v150, v47, v47
	v_mul_f32_e32 v151, v49, v49
	v_fmac_f32_e32 v150, v46, v46
	v_fmac_f32_e32 v151, v48, v48
	v_add_f32_e32 v152, v150, v151
	v_add_f32_e32 v162, v162, v152
	v_cvt_pk_f16_f32 v176, v46, v47
	v_cvt_pk_f16_f32 v177, v48, v49
	global_store_dwordx2 v146, v[170:171], s[10:11]
	global_store_dwordx2 v146, v[172:173], s[10:11] offset:512
	global_store_dwordx2 v146, v[174:175], s[10:11] offset:1024
	global_store_dwordx2 v146, v[176:177], s[10:11] offset:1536
	v_mul_f32_e32 v150, v51, v51
	v_mul_f32_e32 v151, v53, v53
	v_fmac_f32_e32 v150, v50, v50
	v_fmac_f32_e32 v151, v52, v52
	v_add_f32_e32 v163, v150, v151
	v_cvt_pk_f16_f32 v178, v50, v51
	v_cvt_pk_f16_f32 v179, v52, v53
	v_mul_f32_e32 v150, v55, v55
	v_mul_f32_e32 v151, v57, v57
	v_fmac_f32_e32 v150, v54, v54
	v_fmac_f32_e32 v151, v56, v56
	v_add_f32_e32 v152, v150, v151
	v_add_f32_e32 v163, v163, v152
	v_cvt_pk_f16_f32 v180, v54, v55
	v_cvt_pk_f16_f32 v181, v56, v57
	v_mul_f32_e32 v150, v59, v59
	v_mul_f32_e32 v151, v61, v61
	v_fmac_f32_e32 v150, v58, v58
	v_fmac_f32_e32 v151, v60, v60
	v_add_f32_e32 v152, v150, v151
	v_add_f32_e32 v163, v163, v152
	v_cvt_pk_f16_f32 v182, v58, v59
	v_cvt_pk_f16_f32 v183, v60, v61
	v_mul_f32_e32 v150, v63, v63
	v_mul_f32_e32 v151, v65, v65
	v_fmac_f32_e32 v150, v62, v62
	v_fmac_f32_e32 v151, v64, v64
	v_add_f32_e32 v152, v150, v151
	v_add_f32_e32 v163, v163, v152
	v_cvt_pk_f16_f32 v184, v62, v63
	v_cvt_pk_f16_f32 v185, v64, v65
	global_store_dwordx2 v147, v[178:179], s[10:11]
	global_store_dwordx2 v147, v[180:181], s[10:11] offset:512
	global_store_dwordx2 v147, v[182:183], s[10:11] offset:1024
	global_store_dwordx2 v147, v[184:185], s[10:11] offset:1536
	ds_bpermute_b32 v164, v130, v160
	ds_bpermute_b32 v165, v130, v161
	ds_bpermute_b32 v166, v130, v162
	ds_bpermute_b32 v167, v130, v163
	s_waitcnt lgkmcnt(0)
	v_add_f32_e32 v160, v160, v164
	v_add_f32_e32 v161, v161, v165
	v_add_f32_e32 v162, v162, v166
	v_add_f32_e32 v163, v163, v167
	ds_bpermute_b32 v164, v131, v160
	ds_bpermute_b32 v165, v131, v161
	ds_bpermute_b32 v166, v131, v162
	ds_bpermute_b32 v167, v131, v163
	s_waitcnt lgkmcnt(0)
	v_add_f32_e32 v160, v160, v164
	v_add_f32_e32 v161, v161, v165
	v_add_f32_e32 v162, v162, v166
	v_add_f32_e32 v163, v163, v167
	ds_bpermute_b32 v164, v132, v160
	ds_bpermute_b32 v165, v132, v161
	ds_bpermute_b32 v166, v132, v162
	ds_bpermute_b32 v167, v132, v163
	s_waitcnt lgkmcnt(0)
	v_add_f32_e32 v160, v160, v164
	v_add_f32_e32 v161, v161, v165
	v_add_f32_e32 v162, v162, v166
	v_add_f32_e32 v163, v163, v167
	ds_bpermute_b32 v164, v133, v160
	ds_bpermute_b32 v165, v133, v161
	ds_bpermute_b32 v166, v133, v162
	ds_bpermute_b32 v167, v133, v163
	s_waitcnt lgkmcnt(0)
	v_add_f32_e32 v160, v160, v164
	v_add_f32_e32 v161, v161, v165
	v_add_f32_e32 v162, v162, v166
	v_add_f32_e32 v163, v163, v167
	ds_bpermute_b32 v164, v134, v160
	ds_bpermute_b32 v165, v134, v161
	ds_bpermute_b32 v166, v134, v162
	ds_bpermute_b32 v167, v134, v163
	s_waitcnt lgkmcnt(0)
	v_add_f32_e32 v160, v160, v164
	v_add_f32_e32 v161, v161, v165
	v_add_f32_e32 v162, v162, v166
	v_add_f32_e32 v163, v163, v167
	ds_bpermute_b32 v164, v135, v160
	ds_bpermute_b32 v165, v135, v161
	ds_bpermute_b32 v166, v135, v162
	ds_bpermute_b32 v167, v135, v163
	s_waitcnt lgkmcnt(0)
	v_add_f32_e32 v160, v160, v164
	v_add_f32_e32 v161, v161, v165
	v_add_f32_e32 v162, v162, v166
	v_add_f32_e32 v163, v163, v167
	v_cndmask_b32_e64 v164, 0, v160, s[12:13]
	v_cndmask_b32_e64 v165, 0, v161, s[12:13]
	v_cndmask_b32_e64 v166, 0, v162, s[12:13]
	v_cndmask_b32_e64 v167, 0, v163, s[12:13]
	s_mov_b64 exec, 0xffff
	global_store_dword v186, v164, s[6:7]
	global_store_dword v187, v165, s[6:7]
	global_store_dword v188, v166, s[6:7]
	global_store_dword v189, v167, s[6:7]
	s_mov_b64 exec, -1
	s_add_i32 s6, s3, 0x2000
	s_lshl_b32 s6, s6, 12
	s_add_u32 s4, s18, s6
	s_addc_u32 s5, s19, 0
	global_load_dwordx4 v[2:5], v140, s[4:5] nt
	global_load_dwordx4 v[6:9], v140, s[4:5] offset:1024 nt
	global_load_dwordx4 v[10:13], v140, s[4:5] offset:2048 nt
	global_load_dwordx4 v[14:17], v140, s[4:5] offset:3072 nt
	global_load_dwordx4 v[18:21], v141, s[4:5] nt
	global_load_dwordx4 v[22:25], v141, s[4:5] offset:1024 nt
	global_load_dwordx4 v[26:29], v141, s[4:5] offset:2048 nt
	global_load_dwordx4 v[30:33], v141, s[4:5] offset:3072 nt
	global_load_dwordx4 v[34:37], v142, s[4:5] nt
	global_load_dwordx4 v[38:41], v142, s[4:5] offset:1024 nt
	global_load_dwordx4 v[42:45], v142, s[4:5] offset:2048 nt
	global_load_dwordx4 v[46:49], v142, s[4:5] offset:3072 nt
	global_load_dwordx4 v[50:53], v143, s[4:5] nt
	global_load_dwordx4 v[54:57], v143, s[4:5] offset:1024 nt
	global_load_dwordx4 v[58:61], v143, s[4:5] offset:2048 nt
	global_load_dwordx4 v[62:65], v143, s[4:5] offset:3072 nt
	s_waitcnt vmcnt(36)
; __device__ void p0_xconv(const Args& a) {
;     ...
;         for (int r = 0; r < 4; ++r) {
;             const int row = row0 + r * nwv;
;             if (row < MROWS) {
;                 float ss = 0.f;
; #pragma unroll
;                 for (int i = 0; i < 4; ++i) {
;                     const f32x4 x = v[r][i];
;                     ss += (x[0] * x[0] + x[1] * x[1]) + (x[2] * x[2] + x[3] * x[3]);
;                     f16x4 h; h[0] = (f16)x[0]; h[1] = (f16)x[1]; h[2] = (f16)x[2]; h[3] = (f16)x[3];
;                     *(f16x4*)(XH + (size_t)row * DM + i * 256 + lane * 4) = h;
;                 }
; #pragma unroll
;                 for (int o = 1; o < 64; o <<= 1) ss += __shfl_xor(ss, o);
	s_add_i32 s6, s3, 0x5000
	s_lshl_b32 s7, s6, 11
	s_add_u32 s10, s40, s7
	s_addc_u32 s11, s41, 0
	s_lshl_b32 s7, s6, 6
	s_add_u32 s6, s40, s7
	s_addc_u32 s7, s41, 0
	s_add_u32 s6, s6, 0x1f800000
	s_addc_u32 s7, s7, 0
	v_mul_f32_e32 v150, v67, v67
	v_mul_f32_e32 v151, v69, v69
	v_fmac_f32_e32 v150, v66, v66
	v_fmac_f32_e32 v151, v68, v68
	v_add_f32_e32 v160, v150, v151
	v_cvt_pk_f16_f32 v170, v66, v67
	v_cvt_pk_f16_f32 v171, v68, v69
	v_mul_f32_e32 v150, v71, v71
	v_mul_f32_e32 v151, v73, v73
	v_fmac_f32_e32 v150, v70, v70
	v_fmac_f32_e32 v151, v72, v72
	v_add_f32_e32 v152, v150, v151
	v_add_f32_e32 v160, v160, v152
	v_cvt_pk_f16_f32 v172, v70, v71
	v_cvt_pk_f16_f32 v173, v72, v73
	v_mul_f32_e32 v150, v75, v75
	v_mul_f32_e32 v151, v77, v77
	v_fmac_f32_e32 v150, v74, v74
	v_fmac_f32_e32 v151, v76, v76
	v_add_f32_e32 v152, v150, v151
	v_add_f32_e32 v160, v160, v152
	v_cvt_pk_f16_f32 v174, v74, v75
	v_cvt_pk_f16_f32 v175, v76, v77
	v_mul_f32_e32 v150, v79, v79
	v_mul_f32_e32 v151, v81, v81
	v_fmac_f32_e32 v150, v78, v78
	v_fmac_f32_e32 v151, v80, v80
	v_add_f32_e32 v152, v150, v151
	v_add_f32_e32 v160, v160, v152
	v_cvt_pk_f16_f32 v176, v78, v79
	v_cvt_pk_f16_f32 v177, v80, v81
	global_store_dwordx2 v144, v[170:171], s[10:11]
	global_store_dwordx2 v144, v[172:173], s[10:11] offset:512
	global_store_dwordx2 v144, v[174:175], s[10:11] offset:1024
	global_store_dwordx2 v144, v[176:177], s[10:11] offset:1536
	v_mul_f32_e32 v150, v83, v83
	v_mul_f32_e32 v151, v85, v85
	v_fmac_f32_e32 v150, v82, v82
	v_fmac_f32_e32 v151, v84, v84
	v_add_f32_e32 v161, v150, v151
	v_cvt_pk_f16_f32 v178, v82, v83
	v_cvt_pk_f16_f32 v179, v84, v85
	v_mul_f32_e32 v150, v87, v87
	v_mul_f32_e32 v151, v89, v89
	v_fmac_f32_e32 v150, v86, v86
	v_fmac_f32_e32 v151, v88, v88
	v_add_f32_e32 v152, v150, v151
	v_add_f32_e32 v161, v161, v152
	v_cvt_pk_f16_f32 v180, v86, v87
	v_cvt_pk_f16_f32 v181, v88, v89
	v_mul_f32_e32 v150, v91, v91
	v_mul_f32_e32 v151, v93, v93
	v_fmac_f32_e32 v150, v90, v90
	v_fmac_f32_e32 v151, v92, v92
	v_add_f32_e32 v152, v150, v151
	v_add_f32_e32 v161, v161, v152
	v_cvt_pk_f16_f32 v182, v90, v91
	v_cvt_pk_f16_f32 v183, v92, v93
	v_mul_f32_e32 v150, v95, v95
	v_mul_f32_e32 v151, v97, v97
	v_fmac_f32_e32 v150, v94, v94
	v_fmac_f32_e32 v151, v96, v96
	v_add_f32_e32 v152, v150, v151
	v_add_f32_e32 v161, v161, v152
	v_cvt_pk_f16_f32 v184, v94, v95
	v_cvt_pk_f16_f32 v185, v96, v97
	global_store_dwordx2 v145, v[178:179], s[10:11]
	global_store_dwordx2 v145, v[180:181], s[10:11] offset:512
	global_store_dwordx2 v145, v[182:183], s[10:11] offset:1024
	global_store_dwordx2 v145, v[184:185], s[10:11] offset:1536
	v_mul_f32_e32 v150, v99, v99
	v_mul_f32_e32 v151, v101, v101
	v_fmac_f32_e32 v150, v98, v98
	v_fmac_f32_e32 v151, v100, v100
	v_add_f32_e32 v162, v150, v151
	v_cvt_pk_f16_f32 v170, v98, v99
	v_cvt_pk_f16_f32 v171, v100, v101
	v_mul_f32_e32 v150, v103, v103
	v_mul_f32_e32 v151, v105, v105
	v_fmac_f32_e32 v150, v102, v102
	v_fmac_f32_e32 v151, v104, v104
	v_add_f32_e32 v152, v150, v151
	v_add_f32_e32 v162, v162, v152
	v_cvt_pk_f16_f32 v172, v102, v103
	v_cvt_pk_f16_f32 v173, v104, v105
	v_mul_f32_e32 v150, v107, v107
	v_mul_f32_e32 v151, v109, v109
	v_fmac_f32_e32 v150, v106, v106
	v_fmac_f32_e32 v151, v108, v108
	v_add_f32_e32 v152, v150, v151
	v_add_f32_e32 v162, v162, v152
	v_cvt_pk_f16_f32 v174, v106, v107
	v_cvt_pk_f16_f32 v175, v108, v109
	v_mul_f32_e32 v150, v111, v111
	v_mul_f32_e32 v151, v113, v113
	v_fmac_f32_e32 v150, v110, v110
	v_fmac_f32_e32 v151, v112, v112
	v_add_f32_e32 v152, v150, v151
	v_add_f32_e32 v162, v162, v152
	v_cvt_pk_f16_f32 v176, v110, v111
	v_cvt_pk_f16_f32 v177, v112, v113
	global_store_dwordx2 v146, v[170:171], s[10:11]
	global_store_dwordx2 v146, v[172:173], s[10:11] offset:512
	global_store_dwordx2 v146, v[174:175], s[10:11] offset:1024
	global_store_dwordx2 v146, v[176:177], s[10:11] offset:1536
	v_mul_f32_e32 v150, v115, v115
	v_mul_f32_e32 v151, v117, v117
	v_fmac_f32_e32 v150, v114, v114
	v_fmac_f32_e32 v151, v116, v116
	v_add_f32_e32 v163, v150, v151
	v_cvt_pk_f16_f32 v178, v114, v115
	v_cvt_pk_f16_f32 v179, v116, v117
	v_mul_f32_e32 v150, v119, v119
	v_mul_f32_e32 v151, v121, v121
	v_fmac_f32_e32 v150, v118, v118
	v_fmac_f32_e32 v151, v120, v120
	v_add_f32_e32 v152, v150, v151
	v_add_f32_e32 v163, v163, v152
	v_cvt_pk_f16_f32 v180, v118, v119
	v_cvt_pk_f16_f32 v181, v120, v121
	v_mul_f32_e32 v150, v123, v123
	v_mul_f32_e32 v151, v125, v125
	v_fmac_f32_e32 v150, v122, v122
	v_fmac_f32_e32 v151, v124, v124
	v_add_f32_e32 v152, v150, v151
	v_add_f32_e32 v163, v163, v152
	v_cvt_pk_f16_f32 v182, v122, v123
	v_cvt_pk_f16_f32 v183, v124, v125
	v_mul_f32_e32 v150, v127, v127
	v_mul_f32_e32 v151, v129, v129
	v_fmac_f32_e32 v150, v126, v126
	v_fmac_f32_e32 v151, v128, v128
	v_add_f32_e32 v152, v150, v151
	v_add_f32_e32 v163, v163, v152
	v_cvt_pk_f16_f32 v184, v126, v127
	v_cvt_pk_f16_f32 v185, v128, v129
	global_store_dwordx2 v147, v[178:179], s[10:11]
	global_store_dwordx2 v147, v[180:181], s[10:11] offset:512
	global_store_dwordx2 v147, v[182:183], s[10:11] offset:1024
	global_store_dwordx2 v147, v[184:185], s[10:11] offset:1536
	ds_bpermute_b32 v164, v130, v160
	ds_bpermute_b32 v165, v130, v161
	ds_bpermute_b32 v166, v130, v162
	ds_bpermute_b32 v167, v130, v163
	s_waitcnt lgkmcnt(0)
	v_add_f32_e32 v160, v160, v164
	v_add_f32_e32 v161, v161, v165
	v_add_f32_e32 v162, v162, v166
	v_add_f32_e32 v163, v163, v167
	ds_bpermute_b32 v164, v131, v160
	ds_bpermute_b32 v165, v131, v161
	ds_bpermute_b32 v166, v131, v162
	ds_bpermute_b32 v167, v131, v163
	s_waitcnt lgkmcnt(0)
; __device__ void p0_xconv(const Args& a) {
;     ...
;         for (int r = 0; r < 4; ++r) {
;             const int row = row0 + r * nwv;
;             if (row < MROWS) {
;                 const float* src = (row < ROWS_PROMPT) ? a.x_prompt + (size_t)row * DM : a.x_sample + (size_t)(row - ROWS_PROMPT) * DM;
; #pragma unroll
;                 for (int i = 0; i < 4; ++i) v[r][i] = __builtin_nontemporal_load((const f32x4*)(src + i * 256 + lane * 4));
;             }
;         }
; #pragma unroll
;         for (int r = 0; r < 4; ++r) {
;             const int row = row0 + r * nwv;
;             if (row < MROWS) {
;                 float ss = 0.f;
; #pragma unroll
;                 for (int i = 0; i < 4; ++i) {
;                     const f32x4 x = v[r][i];
;                     ss += (x[0] * x[0] + x[1] * x[1]) + (x[2] * x[2] + x[3] * x[3]);
;                     f16x4 h; h[0] = (f16)x[0]; h[1] = (f16)x[1]; h[2] = (f16)x[2]; h[3] = (f16)x[3];
;                     *(f16x4*)(XH + (size_t)row * DM + i * 256 + lane * 4) = h;
;                 }
; #pragma unroll
;                 for (int o = 1; o < 64; o <<= 1) ss += __shfl_xor(ss, o);
;                 if (lane < 16) SS[(size_t)row * 16 + lane] = (lane == 0) ? ss : 0.f;
;             }
	v_add_f32_e32 v160, v160, v164
	v_add_f32_e32 v161, v161, v165
	v_add_f32_e32 v162, v162, v166
	v_add_f32_e32 v163, v163, v167
	ds_bpermute_b32 v164, v132, v160
	ds_bpermute_b32 v165, v132, v161
	ds_bpermute_b32 v166, v132, v162
	ds_bpermute_b32 v167, v132, v163
	s_waitcnt lgkmcnt(0)
	v_add_f32_e32 v160, v160, v164
	v_add_f32_e32 v161, v161, v165
	v_add_f32_e32 v162, v162, v166
	v_add_f32_e32 v163, v163, v167
	ds_bpermute_b32 v164, v133, v160
	ds_bpermute_b32 v165, v133, v161
	ds_bpermute_b32 v166, v133, v162
	ds_bpermute_b32 v167, v133, v163
	s_waitcnt lgkmcnt(0)
	v_add_f32_e32 v160, v160, v164
	v_add_f32_e32 v161, v161, v165
	v_add_f32_e32 v162, v162, v166
	v_add_f32_e32 v163, v163, v167
	ds_bpermute_b32 v164, v134, v160
	ds_bpermute_b32 v165, v134, v161
	ds_bpermute_b32 v166, v134, v162
	ds_bpermute_b32 v167, v134, v163
	s_waitcnt lgkmcnt(0)
	v_add_f32_e32 v160, v160, v164
	v_add_f32_e32 v161, v161, v165
	v_add_f32_e32 v162, v162, v166
	v_add_f32_e32 v163, v163, v167
	ds_bpermute_b32 v164, v135, v160
	ds_bpermute_b32 v165, v135, v161
	ds_bpermute_b32 v166, v135, v162
	ds_bpermute_b32 v167, v135, v163
	s_waitcnt lgkmcnt(0)
	v_add_f32_e32 v160, v160, v164
	v_add_f32_e32 v161, v161, v165
	v_add_f32_e32 v162, v162, v166
	v_add_f32_e32 v163, v163, v167
	v_cndmask_b32_e64 v164, 0, v160, s[12:13]
	v_cndmask_b32_e64 v165, 0, v161, s[12:13]
	v_cndmask_b32_e64 v166, 0, v162, s[12:13]
	v_cndmask_b32_e64 v167, 0, v163, s[12:13]
	s_mov_b64 exec, 0xffff
	global_store_dword v186, v164, s[6:7]
	global_store_dword v187, v165, s[6:7]
	global_store_dword v188, v166, s[6:7]
	global_store_dword v189, v167, s[6:7]
	s_mov_b64 exec, -1
	s_add_i32 s6, s3, 0x3000
	s_lshl_b32 s6, s6, 12
	s_add_u32 s4, s18, s6
	s_addc_u32 s5, s19, 0
	global_load_dwordx4 v[66:69], v140, s[4:5] nt
	global_load_dwordx4 v[70:73], v140, s[4:5] offset:1024 nt
	global_load_dwordx4 v[74:77], v140, s[4:5] offset:2048 nt
	global_load_dwordx4 v[78:81], v140, s[4:5] offset:3072 nt
	global_load_dwordx4 v[82:85], v141, s[4:5] nt
	global_load_dwordx4 v[86:89], v141, s[4:5] offset:1024 nt
	global_load_dwordx4 v[90:93], v141, s[4:5] offset:2048 nt
	global_load_dwordx4 v[94:97], v141, s[4:5] offset:3072 nt
	global_load_dwordx4 v[98:101], v142, s[4:5] nt
	global_load_dwordx4 v[102:105], v142, s[4:5] offset:1024 nt
	global_load_dwordx4 v[106:109], v142, s[4:5] offset:2048 nt
	global_load_dwordx4 v[110:113], v142, s[4:5] offset:3072 nt
	global_load_dwordx4 v[114:117], v143, s[4:5] nt
	global_load_dwordx4 v[118:121], v143, s[4:5] offset:1024 nt
	global_load_dwordx4 v[122:125], v143, s[4:5] offset:2048 nt
	global_load_dwordx4 v[126:129], v143, s[4:5] offset:3072 nt
	s_waitcnt vmcnt(36)
	s_add_i32 s6, s3, 0x6000
	s_lshl_b32 s7, s6, 11
	s_add_u32 s10, s40, s7
	s_addc_u32 s11, s41, 0
	s_lshl_b32 s7, s6, 6
	s_add_u32 s6, s40, s7
	s_addc_u32 s7, s41, 0
	s_add_u32 s6, s6, 0x1f800000
	s_addc_u32 s7, s7, 0
	v_mul_f32_e32 v150, v3, v3
	v_mul_f32_e32 v151, v5, v5
	v_fmac_f32_e32 v150, v2, v2
	v_fmac_f32_e32 v151, v4, v4
	v_add_f32_e32 v160, v150, v151
	v_cvt_pk_f16_f32 v170, v2, v3
	v_cvt_pk_f16_f32 v171, v4, v5
	v_mul_f32_e32 v150, v7, v7
	v_mul_f32_e32 v151, v9, v9
	v_fmac_f32_e32 v150, v6, v6
	v_fmac_f32_e32 v151, v8, v8
	v_add_f32_e32 v152, v150, v151
	v_add_f32_e32 v160, v160, v152
	v_cvt_pk_f16_f32 v172, v6, v7
	v_cvt_pk_f16_f32 v173, v8, v9
	v_mul_f32_e32 v150, v11, v11
	v_mul_f32_e32 v151, v13, v13
	v_fmac_f32_e32 v150, v10, v10
	v_fmac_f32_e32 v151, v12, v12
	v_add_f32_e32 v152, v150, v151
	v_add_f32_e32 v160, v160, v152
	v_cvt_pk_f16_f32 v174, v10, v11
	v_cvt_pk_f16_f32 v175, v12, v13
	v_mul_f32_e32 v150, v15, v15
	v_mul_f32_e32 v151, v17, v17
	v_fmac_f32_e32 v150, v14, v14
	v_fmac_f32_e32 v151, v16, v16
	v_add_f32_e32 v152, v150, v151
	v_add_f32_e32 v160, v160, v152
	v_cvt_pk_f16_f32 v176, v14, v15
	v_cvt_pk_f16_f32 v177, v16, v17
	global_store_dwordx2 v144, v[170:171], s[10:11]
	global_store_dwordx2 v144, v[172:173], s[10:11] offset:512
	global_store_dwordx2 v144, v[174:175], s[10:11] offset:1024
	global_store_dwordx2 v144, v[176:177], s[10:11] offset:1536
	v_mul_f32_e32 v150, v19, v19
	v_mul_f32_e32 v151, v21, v21
	v_fmac_f32_e32 v150, v18, v18
	v_fmac_f32_e32 v151, v20, v20
	v_add_f32_e32 v161, v150, v151
	v_cvt_pk_f16_f32 v178, v18, v19
	v_cvt_pk_f16_f32 v179, v20, v21
	v_mul_f32_e32 v150, v23, v23
	v_mul_f32_e32 v151, v25, v25
	v_fmac_f32_e32 v150, v22, v22
	v_fmac_f32_e32 v151, v24, v24
	v_add_f32_e32 v152, v150, v151
	v_add_f32_e32 v161, v161, v152
	v_cvt_pk_f16_f32 v180, v22, v23
	v_cvt_pk_f16_f32 v181, v24, v25
	v_mul_f32_e32 v150, v27, v27
	v_mul_f32_e32 v151, v29, v29
	v_fmac_f32_e32 v150, v26, v26
	v_fmac_f32_e32 v151, v28, v28
	v_add_f32_e32 v152, v150, v151
	v_add_f32_e32 v161, v161, v152
	v_cvt_pk_f16_f32 v182, v26, v27
	v_cvt_pk_f16_f32 v183, v28, v29
	v_mul_f32_e32 v150, v31, v31
	v_mul_f32_e32 v151, v33, v33
	v_fmac_f32_e32 v150, v30, v30
	v_fmac_f32_e32 v151, v32, v32
	v_add_f32_e32 v152, v150, v151
	v_add_f32_e32 v161, v161, v152
	v_cvt_pk_f16_f32 v184, v30, v31
	v_cvt_pk_f16_f32 v185, v32, v33
	global_store_dwordx2 v145, v[178:179], s[10:11]
	global_store_dwordx2 v145, v[180:181], s[10:11] offset:512
	global_store_dwordx2 v145, v[182:183], s[10:11] offset:1024
	global_store_dwordx2 v145, v[184:185], s[10:11] offset:1536
	v_mul_f32_e32 v150, v35, v35
	v_mul_f32_e32 v151, v37, v37
	v_fmac_f32_e32 v150, v34, v34
	v_fmac_f32_e32 v151, v36, v36
	v_add_f32_e32 v162, v150, v151
	v_cvt_pk_f16_f32 v170, v34, v35
	v_cvt_pk_f16_f32 v171, v36, v37
	v_mul_f32_e32 v150, v39, v39
	v_mul_f32_e32 v151, v41, v41
	v_fmac_f32_e32 v150, v38, v38
	v_fmac_f32_e32 v151, v40, v40
	v_add_f32_e32 v152, v150, v151
; __device__ void p0_xconv(const Args& a) {
;     ...
;         for (int r = 0; r < 4; ++r) {
;             const int row = row0 + r * nwv;
;             if (row < MROWS) {
;                 const float* src = (row < ROWS_PROMPT) ? a.x_prompt + (size_t)row * DM : a.x_sample + (size_t)(row - ROWS_PROMPT) * DM;
; #pragma unroll
;                 for (int i = 0; i < 4; ++i) v[r][i] = __builtin_nontemporal_load((const f32x4*)(src + i * 256 + lane * 4));
;             }
;         }
; #pragma unroll
;         for (int r = 0; r < 4; ++r) {
;             const int row = row0 + r * nwv;
;             if (row < MROWS) {
;                 float ss = 0.f;
; #pragma unroll
;                 for (int i = 0; i < 4; ++i) {
;                     const f32x4 x = v[r][i];
;                     ss += (x[0] * x[0] + x[1] * x[1]) + (x[2] * x[2] + x[3] * x[3]);
;                     f16x4 h; h[0] = (f16)x[0]; h[1] = (f16)x[1]; h[2] = (f16)x[2]; h[3] = (f16)x[3];
;                     *(f16x4*)(XH + (size_t)row * DM + i * 256 + lane * 4) = h;
;                 }
; #pragma unroll
;                 for (int o = 1; o < 64; o <<= 1) ss += __shfl_xor(ss, o);
;                 if (lane < 16) SS[(size_t)row * 16 + lane] = (lane == 0) ? ss : 0.f;
;             }
	v_add_f32_e32 v162, v162, v152
	v_cvt_pk_f16_f32 v172, v38, v39
	v_cvt_pk_f16_f32 v173, v40, v41
	v_mul_f32_e32 v150, v43, v43
	v_mul_f32_e32 v151, v45, v45
	v_fmac_f32_e32 v150, v42, v42
	v_fmac_f32_e32 v151, v44, v44
	v_add_f32_e32 v152, v150, v151
	v_add_f32_e32 v162, v162, v152
	v_cvt_pk_f16_f32 v174, v42, v43
	v_cvt_pk_f16_f32 v175, v44, v45
	v_mul_f32_e32 v150, v47, v47
	v_mul_f32_e32 v151, v49, v49
	v_fmac_f32_e32 v150, v46, v46
	v_fmac_f32_e32 v151, v48, v48
	v_add_f32_e32 v152, v150, v151
	v_add_f32_e32 v162, v162, v152
	v_cvt_pk_f16_f32 v176, v46, v47
	v_cvt_pk_f16_f32 v177, v48, v49
	global_store_dwordx2 v146, v[170:171], s[10:11]
	global_store_dwordx2 v146, v[172:173], s[10:11] offset:512
	global_store_dwordx2 v146, v[174:175], s[10:11] offset:1024
	global_store_dwordx2 v146, v[176:177], s[10:11] offset:1536
	v_mul_f32_e32 v150, v51, v51
	v_mul_f32_e32 v151, v53, v53
	v_fmac_f32_e32 v150, v50, v50
	v_fmac_f32_e32 v151, v52, v52
	v_add_f32_e32 v163, v150, v151
	v_cvt_pk_f16_f32 v178, v50, v51
	v_cvt_pk_f16_f32 v179, v52, v53
	v_mul_f32_e32 v150, v55, v55
	v_mul_f32_e32 v151, v57, v57
	v_fmac_f32_e32 v150, v54, v54
	v_fmac_f32_e32 v151, v56, v56
	v_add_f32_e32 v152, v150, v151
	v_add_f32_e32 v163, v163, v152
	v_cvt_pk_f16_f32 v180, v54, v55
	v_cvt_pk_f16_f32 v181, v56, v57
	v_mul_f32_e32 v150, v59, v59
	v_mul_f32_e32 v151, v61, v61
	v_fmac_f32_e32 v150, v58, v58
	v_fmac_f32_e32 v151, v60, v60
	v_add_f32_e32 v152, v150, v151
	v_add_f32_e32 v163, v163, v152
	v_cvt_pk_f16_f32 v182, v58, v59
	v_cvt_pk_f16_f32 v183, v60, v61
	v_mul_f32_e32 v150, v63, v63
	v_mul_f32_e32 v151, v65, v65
	v_fmac_f32_e32 v150, v62, v62
	v_fmac_f32_e32 v151, v64, v64
	v_add_f32_e32 v152, v150, v151
	v_add_f32_e32 v163, v163, v152
	v_cvt_pk_f16_f32 v184, v62, v63
	v_cvt_pk_f16_f32 v185, v64, v65
	global_store_dwordx2 v147, v[178:179], s[10:11]
	global_store_dwordx2 v147, v[180:181], s[10:11] offset:512
	global_store_dwordx2 v147, v[182:183], s[10:11] offset:1024
	global_store_dwordx2 v147, v[184:185], s[10:11] offset:1536
	ds_bpermute_b32 v164, v130, v160
	ds_bpermute_b32 v165, v130, v161
	ds_bpermute_b32 v166, v130, v162
	ds_bpermute_b32 v167, v130, v163
	s_waitcnt lgkmcnt(0)
	v_add_f32_e32 v160, v160, v164
	v_add_f32_e32 v161, v161, v165
	v_add_f32_e32 v162, v162, v166
	v_add_f32_e32 v163, v163, v167
	ds_bpermute_b32 v164, v131, v160
	ds_bpermute_b32 v165, v131, v161
	ds_bpermute_b32 v166, v131, v162
	ds_bpermute_b32 v167, v131, v163
	s_waitcnt lgkmcnt(0)
	v_add_f32_e32 v160, v160, v164
	v_add_f32_e32 v161, v161, v165
	v_add_f32_e32 v162, v162, v166
	v_add_f32_e32 v163, v163, v167
	ds_bpermute_b32 v164, v132, v160
	ds_bpermute_b32 v165, v132, v161
	ds_bpermute_b32 v166, v132, v162
	ds_bpermute_b32 v167, v132, v163
	s_waitcnt lgkmcnt(0)
	v_add_f32_e32 v160, v160, v164
	v_add_f32_e32 v161, v161, v165
	v_add_f32_e32 v162, v162, v166
	v_add_f32_e32 v163, v163, v167
	ds_bpermute_b32 v164, v133, v160
	ds_bpermute_b32 v165, v133, v161
	ds_bpermute_b32 v166, v133, v162
	ds_bpermute_b32 v167, v133, v163
	s_waitcnt lgkmcnt(0)
	v_add_f32_e32 v160, v160, v164
	v_add_f32_e32 v161, v161, v165
	v_add_f32_e32 v162, v162, v166
	v_add_f32_e32 v163, v163, v167
	ds_bpermute_b32 v164, v134, v160
	ds_bpermute_b32 v165, v134, v161
	ds_bpermute_b32 v166, v134, v162
	ds_bpermute_b32 v167, v134, v163
	s_waitcnt lgkmcnt(0)
	v_add_f32_e32 v160, v160, v164
	v_add_f32_e32 v161, v161, v165
	v_add_f32_e32 v162, v162, v166
	v_add_f32_e32 v163, v163, v167
	ds_bpermute_b32 v164, v135, v160
	ds_bpermute_b32 v165, v135, v161
	ds_bpermute_b32 v166, v135, v162
	ds_bpermute_b32 v167, v135, v163
	s_waitcnt lgkmcnt(0)
	v_add_f32_e32 v160, v160, v164
	v_add_f32_e32 v161, v161, v165
	v_add_f32_e32 v162, v162, v166
	v_add_f32_e32 v163, v163, v167
	v_cndmask_b32_e64 v164, 0, v160, s[12:13]
	v_cndmask_b32_e64 v165, 0, v161, s[12:13]
	v_cndmask_b32_e64 v166, 0, v162, s[12:13]
	v_cndmask_b32_e64 v167, 0, v163, s[12:13]
	s_mov_b64 exec, 0xffff
	global_store_dword v186, v164, s[6:7]
	global_store_dword v187, v165, s[6:7]
	global_store_dword v188, v166, s[6:7]
	global_store_dword v189, v167, s[6:7]
	s_mov_b64 exec, -1
	s_add_i32 s6, s3, 0x4000
	s_lshl_b32 s6, s6, 12
	s_add_u32 s4, s18, s6
	s_addc_u32 s5, s19, 0
	global_load_dwordx4 v[2:5], v140, s[4:5] nt
	global_load_dwordx4 v[6:9], v140, s[4:5] offset:1024 nt
	global_load_dwordx4 v[10:13], v140, s[4:5] offset:2048 nt
	global_load_dwordx4 v[14:17], v140, s[4:5] offset:3072 nt
	global_load_dwordx4 v[18:21], v141, s[4:5] nt
	global_load_dwordx4 v[22:25], v141, s[4:5] offset:1024 nt
	global_load_dwordx4 v[26:29], v141, s[4:5] offset:2048 nt
	global_load_dwordx4 v[30:33], v141, s[4:5] offset:3072 nt
	global_load_dwordx4 v[34:37], v142, s[4:5] nt
	global_load_dwordx4 v[38:41], v142, s[4:5] offset:1024 nt
	global_load_dwordx4 v[42:45], v142, s[4:5] offset:2048 nt
	global_load_dwordx4 v[46:49], v142, s[4:5] offset:3072 nt
	global_load_dwordx4 v[50:53], v143, s[4:5] nt
	global_load_dwordx4 v[54:57], v143, s[4:5] offset:1024 nt
	global_load_dwordx4 v[58:61], v143, s[4:5] offset:2048 nt
	global_load_dwordx4 v[62:65], v143, s[4:5] offset:3072 nt
	s_waitcnt vmcnt(36)
; __device__ void p0_xconv(const Args& a) {
;     ...
;         for (int r = 0; r < 4; ++r) {
;             const int row = row0 + r * nwv;
;             if (row < MROWS) {
;                 float ss = 0.f;
; #pragma unroll
;                 for (int i = 0; i < 4; ++i) {
;                     const f32x4 x = v[r][i];
;                     ss += (x[0] * x[0] + x[1] * x[1]) + (x[2] * x[2] + x[3] * x[3]);
;                     f16x4 h; h[0] = (f16)x[0]; h[1] = (f16)x[1]; h[2] = (f16)x[2]; h[3] = (f16)x[3];
;                     *(f16x4*)(XH + (size_t)row * DM + i * 256 + lane * 4) = h;
;                 }
; #pragma unroll
;                 for (int o = 1; o < 64; o <<= 1) ss += __shfl_xor(ss, o);
	s_add_i32 s6, s3, 0x7000
	s_lshl_b32 s7, s6, 11
	s_add_u32 s10, s40, s7
	s_addc_u32 s11, s41, 0
	s_lshl_b32 s7, s6, 6
	s_add_u32 s6, s40, s7
	s_addc_u32 s7, s41, 0
	s_add_u32 s6, s6, 0x1f800000
	s_addc_u32 s7, s7, 0
	v_mul_f32_e32 v150, v67, v67
	v_mul_f32_e32 v151, v69, v69
	v_fmac_f32_e32 v150, v66, v66
	v_fmac_f32_e32 v151, v68, v68
	v_add_f32_e32 v160, v150, v151
	v_cvt_pk_f16_f32 v170, v66, v67
	v_cvt_pk_f16_f32 v171, v68, v69
	v_mul_f32_e32 v150, v71, v71
	v_mul_f32_e32 v151, v73, v73
	v_fmac_f32_e32 v150, v70, v70
	v_fmac_f32_e32 v151, v72, v72
	v_add_f32_e32 v152, v150, v151
	v_add_f32_e32 v160, v160, v152
	v_cvt_pk_f16_f32 v172, v70, v71
	v_cvt_pk_f16_f32 v173, v72, v73
	v_mul_f32_e32 v150, v75, v75
	v_mul_f32_e32 v151, v77, v77
	v_fmac_f32_e32 v150, v74, v74
	v_fmac_f32_e32 v151, v76, v76
	v_add_f32_e32 v152, v150, v151
	v_add_f32_e32 v160, v160, v152
	v_cvt_pk_f16_f32 v174, v74, v75
	v_cvt_pk_f16_f32 v175, v76, v77
	v_mul_f32_e32 v150, v79, v79
	v_mul_f32_e32 v151, v81, v81
	v_fmac_f32_e32 v150, v78, v78
	v_fmac_f32_e32 v151, v80, v80
	v_add_f32_e32 v152, v150, v151
	v_add_f32_e32 v160, v160, v152
	v_cvt_pk_f16_f32 v176, v78, v79
	v_cvt_pk_f16_f32 v177, v80, v81
	global_store_dwordx2 v144, v[170:171], s[10:11]
	global_store_dwordx2 v144, v[172:173], s[10:11] offset:512
	global_store_dwordx2 v144, v[174:175], s[10:11] offset:1024
	global_store_dwordx2 v144, v[176:177], s[10:11] offset:1536
	v_mul_f32_e32 v150, v83, v83
	v_mul_f32_e32 v151, v85, v85
	v_fmac_f32_e32 v150, v82, v82
	v_fmac_f32_e32 v151, v84, v84
	v_add_f32_e32 v161, v150, v151
	v_cvt_pk_f16_f32 v178, v82, v83
	v_cvt_pk_f16_f32 v179, v84, v85
	v_mul_f32_e32 v150, v87, v87
	v_mul_f32_e32 v151, v89, v89
	v_fmac_f32_e32 v150, v86, v86
	v_fmac_f32_e32 v151, v88, v88
	v_add_f32_e32 v152, v150, v151
	v_add_f32_e32 v161, v161, v152
	v_cvt_pk_f16_f32 v180, v86, v87
	v_cvt_pk_f16_f32 v181, v88, v89
	v_mul_f32_e32 v150, v91, v91
	v_mul_f32_e32 v151, v93, v93
	v_fmac_f32_e32 v150, v90, v90
	v_fmac_f32_e32 v151, v92, v92
	v_add_f32_e32 v152, v150, v151
	v_add_f32_e32 v161, v161, v152
	v_cvt_pk_f16_f32 v182, v90, v91
	v_cvt_pk_f16_f32 v183, v92, v93
	v_mul_f32_e32 v150, v95, v95
	v_mul_f32_e32 v151, v97, v97
	v_fmac_f32_e32 v150, v94, v94
	v_fmac_f32_e32 v151, v96, v96
	v_add_f32_e32 v152, v150, v151
	v_add_f32_e32 v161, v161, v152
	v_cvt_pk_f16_f32 v184, v94, v95
	v_cvt_pk_f16_f32 v185, v96, v97
	global_store_dwordx2 v145, v[178:179], s[10:11]
	global_store_dwordx2 v145, v[180:181], s[10:11] offset:512
	global_store_dwordx2 v145, v[182:183], s[10:11] offset:1024
	global_store_dwordx2 v145, v[184:185], s[10:11] offset:1536
	v_mul_f32_e32 v150, v99, v99
	v_mul_f32_e32 v151, v101, v101
	v_fmac_f32_e32 v150, v98, v98
	v_fmac_f32_e32 v151, v100, v100
	v_add_f32_e32 v162, v150, v151
	v_cvt_pk_f16_f32 v170, v98, v99
	v_cvt_pk_f16_f32 v171, v100, v101
	v_mul_f32_e32 v150, v103, v103
	v_mul_f32_e32 v151, v105, v105
	v_fmac_f32_e32 v150, v102, v102
	v_fmac_f32_e32 v151, v104, v104
	v_add_f32_e32 v152, v150, v151
	v_add_f32_e32 v162, v162, v152
	v_cvt_pk_f16_f32 v172, v102, v103
	v_cvt_pk_f16_f32 v173, v104, v105
	v_mul_f32_e32 v150, v107, v107
	v_mul_f32_e32 v151, v109, v109
	v_fmac_f32_e32 v150, v106, v106
	v_fmac_f32_e32 v151, v108, v108
	v_add_f32_e32 v152, v150, v151
	v_add_f32_e32 v162, v162, v152
	v_cvt_pk_f16_f32 v174, v106, v107
	v_cvt_pk_f16_f32 v175, v108, v109
	v_mul_f32_e32 v150, v111, v111
	v_mul_f32_e32 v151, v113, v113
	v_fmac_f32_e32 v150, v110, v110
	v_fmac_f32_e32 v151, v112, v112
	v_add_f32_e32 v152, v150, v151
	v_add_f32_e32 v162, v162, v152
	v_cvt_pk_f16_f32 v176, v110, v111
	v_cvt_pk_f16_f32 v177, v112, v113
	global_store_dwordx2 v146, v[170:171], s[10:11]
	global_store_dwordx2 v146, v[172:173], s[10:11] offset:512
	global_store_dwordx2 v146, v[174:175], s[10:11] offset:1024
	global_store_dwordx2 v146, v[176:177], s[10:11] offset:1536
	v_mul_f32_e32 v150, v115, v115
	v_mul_f32_e32 v151, v117, v117
	v_fmac_f32_e32 v150, v114, v114
	v_fmac_f32_e32 v151, v116, v116
	v_add_f32_e32 v163, v150, v151
	v_cvt_pk_f16_f32 v178, v114, v115
	v_cvt_pk_f16_f32 v179, v116, v117
	v_mul_f32_e32 v150, v119, v119
	v_mul_f32_e32 v151, v121, v121
	v_fmac_f32_e32 v150, v118, v118
	v_fmac_f32_e32 v151, v120, v120
	v_add_f32_e32 v152, v150, v151
	v_add_f32_e32 v163, v163, v152
	v_cvt_pk_f16_f32 v180, v118, v119
	v_cvt_pk_f16_f32 v181, v120, v121
	v_mul_f32_e32 v150, v123, v123
	v_mul_f32_e32 v151, v125, v125
	v_fmac_f32_e32 v150, v122, v122
	v_fmac_f32_e32 v151, v124, v124
	v_add_f32_e32 v152, v150, v151
	v_add_f32_e32 v163, v163, v152
	v_cvt_pk_f16_f32 v182, v122, v123
	v_cvt_pk_f16_f32 v183, v124, v125
	v_mul_f32_e32 v150, v127, v127
	v_mul_f32_e32 v151, v129, v129
	v_fmac_f32_e32 v150, v126, v126
	v_fmac_f32_e32 v151, v128, v128
	v_add_f32_e32 v152, v150, v151
	v_add_f32_e32 v163, v163, v152
	v_cvt_pk_f16_f32 v184, v126, v127
	v_cvt_pk_f16_f32 v185, v128, v129
	global_store_dwordx2 v147, v[178:179], s[10:11]
	global_store_dwordx2 v147, v[180:181], s[10:11] offset:512
	global_store_dwordx2 v147, v[182:183], s[10:11] offset:1024
	global_store_dwordx2 v147, v[184:185], s[10:11] offset:1536
	ds_bpermute_b32 v164, v130, v160
	ds_bpermute_b32 v165, v130, v161
	ds_bpermute_b32 v166, v130, v162
	ds_bpermute_b32 v167, v130, v163
	s_waitcnt lgkmcnt(0)
	v_add_f32_e32 v160, v160, v164
	v_add_f32_e32 v161, v161, v165
	v_add_f32_e32 v162, v162, v166
	v_add_f32_e32 v163, v163, v167
	ds_bpermute_b32 v164, v131, v160
	ds_bpermute_b32 v165, v131, v161
	ds_bpermute_b32 v166, v131, v162
	ds_bpermute_b32 v167, v131, v163
	s_waitcnt lgkmcnt(0)
; __device__ void p0_xconv(const Args& a) {
;     ...
;         for (int r = 0; r < 4; ++r) {
;             const int row = row0 + r * nwv;
;             if (row < MROWS) {
;                 float ss = 0.f;
; #pragma unroll
;                 for (int i = 0; i < 4; ++i) {
;                     const f32x4 x = v[r][i];
;                     ss += (x[0] * x[0] + x[1] * x[1]) + (x[2] * x[2] + x[3] * x[3]);
;                     f16x4 h; h[0] = (f16)x[0]; h[1] = (f16)x[1]; h[2] = (f16)x[2]; h[3] = (f16)x[3];
;                     *(f16x4*)(XH + (size_t)row * DM + i * 256 + lane * 4) = h;
;                 }
; #pragma unroll
;                 for (int o = 1; o < 64; o <<= 1) ss += __shfl_xor(ss, o);
;                 if (lane < 16) SS[(size_t)row * 16 + lane] = (lane == 0) ? ss : 0.f;
;             }
	v_add_f32_e32 v160, v160, v164
	v_add_f32_e32 v161, v161, v165
	v_add_f32_e32 v162, v162, v166
	v_add_f32_e32 v163, v163, v167
	ds_bpermute_b32 v164, v132, v160
	ds_bpermute_b32 v165, v132, v161
	ds_bpermute_b32 v166, v132, v162
	ds_bpermute_b32 v167, v132, v163
	s_waitcnt lgkmcnt(0)
	v_add_f32_e32 v160, v160, v164
	v_add_f32_e32 v161, v161, v165
	v_add_f32_e32 v162, v162, v166
	v_add_f32_e32 v163, v163, v167
	ds_bpermute_b32 v164, v133, v160
	ds_bpermute_b32 v165, v133, v161
	ds_bpermute_b32 v166, v133, v162
	ds_bpermute_b32 v167, v133, v163
	s_waitcnt lgkmcnt(0)
	v_add_f32_e32 v160, v160, v164
	v_add_f32_e32 v161, v161, v165
	v_add_f32_e32 v162, v162, v166
	v_add_f32_e32 v163, v163, v167
	ds_bpermute_b32 v164, v134, v160
	ds_bpermute_b32 v165, v134, v161
	ds_bpermute_b32 v166, v134, v162
	ds_bpermute_b32 v167, v134, v163
	s_waitcnt lgkmcnt(0)
	v_add_f32_e32 v160, v160, v164
	v_add_f32_e32 v161, v161, v165
	v_add_f32_e32 v162, v162, v166
	v_add_f32_e32 v163, v163, v167
	ds_bpermute_b32 v164, v135, v160
	ds_bpermute_b32 v165, v135, v161
	ds_bpermute_b32 v166, v135, v162
	ds_bpermute_b32 v167, v135, v163
	s_waitcnt lgkmcnt(0)
	v_add_f32_e32 v160, v160, v164
	v_add_f32_e32 v161, v161, v165
	v_add_f32_e32 v162, v162, v166
	v_add_f32_e32 v163, v163, v167
	v_cndmask_b32_e64 v164, 0, v160, s[12:13]
	v_cndmask_b32_e64 v165, 0, v161, s[12:13]
	v_cndmask_b32_e64 v166, 0, v162, s[12:13]
	v_cndmask_b32_e64 v167, 0, v163, s[12:13]
	s_mov_b64 exec, 0xffff
	global_store_dword v186, v164, s[6:7]
	global_store_dword v187, v165, s[6:7]
	global_store_dword v188, v166, s[6:7]
	global_store_dword v189, v167, s[6:7]
	s_mov_b64 exec, -1
	s_waitcnt vmcnt(20)
	s_add_i32 s6, s3, 0x8000
	s_lshl_b32 s7, s6, 11
	s_add_u32 s10, s40, s7
	s_addc_u32 s11, s41, 0
	s_lshl_b32 s7, s6, 6
	s_add_u32 s6, s40, s7
	s_addc_u32 s7, s41, 0
	s_add_u32 s6, s6, 0x1f800000
	s_addc_u32 s7, s7, 0
	v_mul_f32_e32 v150, v3, v3
	v_mul_f32_e32 v151, v5, v5
	v_fmac_f32_e32 v150, v2, v2
	v_fmac_f32_e32 v151, v4, v4
	v_add_f32_e32 v160, v150, v151
	v_cvt_pk_f16_f32 v170, v2, v3
	v_cvt_pk_f16_f32 v171, v4, v5
	v_mul_f32_e32 v150, v7, v7
	v_mul_f32_e32 v151, v9, v9
	v_fmac_f32_e32 v150, v6, v6
	v_fmac_f32_e32 v151, v8, v8
	v_add_f32_e32 v152, v150, v151
	v_add_f32_e32 v160, v160, v152
	v_cvt_pk_f16_f32 v172, v6, v7
	v_cvt_pk_f16_f32 v173, v8, v9
	v_mul_f32_e32 v150, v11, v11
	v_mul_f32_e32 v151, v13, v13
	v_fmac_f32_e32 v150, v10, v10
	v_fmac_f32_e32 v151, v12, v12
	v_add_f32_e32 v152, v150, v151
	v_add_f32_e32 v160, v160, v152
	v_cvt_pk_f16_f32 v174, v10, v11
	v_cvt_pk_f16_f32 v175, v12, v13
	v_mul_f32_e32 v150, v15, v15
	v_mul_f32_e32 v151, v17, v17
	v_fmac_f32_e32 v150, v14, v14
	v_fmac_f32_e32 v151, v16, v16
	v_add_f32_e32 v152, v150, v151
	v_add_f32_e32 v160, v160, v152
	v_cvt_pk_f16_f32 v176, v14, v15
	v_cvt_pk_f16_f32 v177, v16, v17
	global_store_dwordx2 v144, v[170:171], s[10:11]
	global_store_dwordx2 v144, v[172:173], s[10:11] offset:512
	global_store_dwordx2 v144, v[174:175], s[10:11] offset:1024
	global_store_dwordx2 v144, v[176:177], s[10:11] offset:1536
	v_mul_f32_e32 v150, v19, v19
	v_mul_f32_e32 v151, v21, v21
	v_fmac_f32_e32 v150, v18, v18
	v_fmac_f32_e32 v151, v20, v20
	v_add_f32_e32 v161, v150, v151
	v_cvt_pk_f16_f32 v178, v18, v19
	v_cvt_pk_f16_f32 v179, v20, v21
	v_mul_f32_e32 v150, v23, v23
	v_mul_f32_e32 v151, v25, v25
	v_fmac_f32_e32 v150, v22, v22
	v_fmac_f32_e32 v151, v24, v24
	v_add_f32_e32 v152, v150, v151
	v_add_f32_e32 v161, v161, v152
	v_cvt_pk_f16_f32 v180, v22, v23
	v_cvt_pk_f16_f32 v181, v24, v25
	v_mul_f32_e32 v150, v27, v27
	v_mul_f32_e32 v151, v29, v29
	v_fmac_f32_e32 v150, v26, v26
	v_fmac_f32_e32 v151, v28, v28
	v_add_f32_e32 v152, v150, v151
	v_add_f32_e32 v161, v161, v152
	v_cvt_pk_f16_f32 v182, v26, v27
	v_cvt_pk_f16_f32 v183, v28, v29
	v_mul_f32_e32 v150, v31, v31
	v_mul_f32_e32 v151, v33, v33
	v_fmac_f32_e32 v150, v30, v30
	v_fmac_f32_e32 v151, v32, v32
	v_add_f32_e32 v152, v150, v151
	v_add_f32_e32 v161, v161, v152
	v_cvt_pk_f16_f32 v184, v30, v31
	v_cvt_pk_f16_f32 v185, v32, v33
	global_store_dwordx2 v145, v[178:179], s[10:11]
	global_store_dwordx2 v145, v[180:181], s[10:11] offset:512
	global_store_dwordx2 v145, v[182:183], s[10:11] offset:1024
	global_store_dwordx2 v145, v[184:185], s[10:11] offset:1536
	v_mul_f32_e32 v150, v35, v35
	v_mul_f32_e32 v151, v37, v37
	v_fmac_f32_e32 v150, v34, v34
	v_fmac_f32_e32 v151, v36, v36
	v_add_f32_e32 v162, v150, v151
	v_cvt_pk_f16_f32 v170, v34, v35
	v_cvt_pk_f16_f32 v171, v36, v37
	v_mul_f32_e32 v150, v39, v39
	v_mul_f32_e32 v151, v41, v41
	v_fmac_f32_e32 v150, v38, v38
	v_fmac_f32_e32 v151, v40, v40
	v_add_f32_e32 v152, v150, v151
	v_add_f32_e32 v162, v162, v152
	v_cvt_pk_f16_f32 v172, v38, v39
	v_cvt_pk_f16_f32 v173, v40, v41
	v_mul_f32_e32 v150, v43, v43
	v_mul_f32_e32 v151, v45, v45
	v_fmac_f32_e32 v150, v42, v42
	v_fmac_f32_e32 v151, v44, v44
	v_add_f32_e32 v152, v150, v151
	v_add_f32_e32 v162, v162, v152
	v_cvt_pk_f16_f32 v174, v42, v43
	v_cvt_pk_f16_f32 v175, v44, v45
	v_mul_f32_e32 v150, v47, v47
	v_mul_f32_e32 v151, v49, v49
	v_fmac_f32_e32 v150, v46, v46
	v_fmac_f32_e32 v151, v48, v48
	v_add_f32_e32 v152, v150, v151
	v_add_f32_e32 v162, v162, v152
	v_cvt_pk_f16_f32 v176, v46, v47
	v_cvt_pk_f16_f32 v177, v48, v49
	global_store_dwordx2 v146, v[170:171], s[10:11]
	global_store_dwordx2 v146, v[172:173], s[10:11] offset:512
	global_store_dwordx2 v146, v[174:175], s[10:11] offset:1024
	global_store_dwordx2 v146, v[176:177], s[10:11] offset:1536
	v_mul_f32_e32 v150, v51, v51
	v_mul_f32_e32 v151, v53, v53
	v_fmac_f32_e32 v150, v50, v50
	v_fmac_f32_e32 v151, v52, v52
	v_add_f32_e32 v163, v150, v151
	v_cvt_pk_f16_f32 v178, v50, v51
	v_cvt_pk_f16_f32 v179, v52, v53
	v_mul_f32_e32 v150, v55, v55
	v_mul_f32_e32 v151, v57, v57
	v_fmac_f32_e32 v150, v54, v54
	v_fmac_f32_e32 v151, v56, v56
	v_add_f32_e32 v152, v150, v151
	v_add_f32_e32 v163, v163, v152
	v_cvt_pk_f16_f32 v180, v54, v55
	v_cvt_pk_f16_f32 v181, v56, v57
	v_mul_f32_e32 v150, v59, v59
	v_mul_f32_e32 v151, v61, v61
	v_fmac_f32_e32 v150, v58, v58
	v_fmac_f32_e32 v151, v60, v60
	v_add_f32_e32 v152, v150, v151
	v_add_f32_e32 v163, v163, v152
	v_cvt_pk_f16_f32 v182, v58, v59
	v_cvt_pk_f16_f32 v183, v60, v61
	v_mul_f32_e32 v150, v63, v63
	v_mul_f32_e32 v151, v65, v65
	v_fmac_f32_e32 v150, v62, v62
	v_fmac_f32_e32 v151, v64, v64
	v_add_f32_e32 v152, v150, v151
	v_add_f32_e32 v163, v163, v152
	v_cvt_pk_f16_f32 v184, v62, v63
	v_cvt_pk_f16_f32 v185, v64, v65
	global_store_dwordx2 v147, v[178:179], s[10:11]
	global_store_dwordx2 v147, v[180:181], s[10:11] offset:512
	global_store_dwordx2 v147, v[182:183], s[10:11] offset:1024
	global_store_dwordx2 v147, v[184:185], s[10:11] offset:1536
	ds_bpermute_b32 v164, v130, v160
	ds_bpermute_b32 v165, v130, v161
	ds_bpermute_b32 v166, v130, v162
	ds_bpermute_b32 v167, v130, v163
	s_waitcnt lgkmcnt(0)
; __device__ void p0_xconv(const Args& a) {
;     ...
;                 for (int o = 1; o < 64; o <<= 1) ss += __shfl_xor(ss, o);
;                 if (lane < 16) SS[(size_t)row * 16 + lane] = (lane == 0) ? ss : 0.f;
	v_add_f32_e32 v160, v160, v164
	v_add_f32_e32 v161, v161, v165
	v_add_f32_e32 v162, v162, v166
	v_add_f32_e32 v163, v163, v167
	ds_bpermute_b32 v164, v131, v160
	ds_bpermute_b32 v165, v131, v161
	ds_bpermute_b32 v166, v131, v162
	ds_bpermute_b32 v167, v131, v163
	s_waitcnt lgkmcnt(0)
	v_add_f32_e32 v160, v160, v164
	v_add_f32_e32 v161, v161, v165
	v_add_f32_e32 v162, v162, v166
	v_add_f32_e32 v163, v163, v167
	ds_bpermute_b32 v164, v132, v160
	ds_bpermute_b32 v165, v132, v161
	ds_bpermute_b32 v166, v132, v162
	ds_bpermute_b32 v167, v132, v163
	s_waitcnt lgkmcnt(0)
	v_add_f32_e32 v160, v160, v164
	v_add_f32_e32 v161, v161, v165
	v_add_f32_e32 v162, v162, v166
	v_add_f32_e32 v163, v163, v167
	ds_bpermute_b32 v164, v133, v160
	ds_bpermute_b32 v165, v133, v161
	ds_bpermute_b32 v166, v133, v162
	ds_bpermute_b32 v167, v133, v163
	s_waitcnt lgkmcnt(0)
	v_add_f32_e32 v160, v160, v164
	v_add_f32_e32 v161, v161, v165
	v_add_f32_e32 v162, v162, v166
	v_add_f32_e32 v163, v163, v167
	ds_bpermute_b32 v164, v134, v160
	ds_bpermute_b32 v165, v134, v161
	ds_bpermute_b32 v166, v134, v162
	ds_bpermute_b32 v167, v134, v163
	s_waitcnt lgkmcnt(0)
	v_add_f32_e32 v160, v160, v164
	v_add_f32_e32 v161, v161, v165
	v_add_f32_e32 v162, v162, v166
	v_add_f32_e32 v163, v163, v167
	ds_bpermute_b32 v164, v135, v160
	ds_bpermute_b32 v165, v135, v161
	ds_bpermute_b32 v166, v135, v162
	ds_bpermute_b32 v167, v135, v163
	s_waitcnt lgkmcnt(0)
	v_add_f32_e32 v160, v160, v164
	v_add_f32_e32 v161, v161, v165
	v_add_f32_e32 v162, v162, v166
	v_add_f32_e32 v163, v163, v167
	v_cndmask_b32_e64 v164, 0, v160, s[12:13]
	v_cndmask_b32_e64 v165, 0, v161, s[12:13]
	v_cndmask_b32_e64 v166, 0, v162, s[12:13]
	v_cndmask_b32_e64 v167, 0, v163, s[12:13]
	s_mov_b64 exec, 0xffff
	global_store_dword v186, v164, s[6:7]
	global_store_dword v187, v165, s[6:7]
	global_store_dword v188, v166, s[6:7]
	global_store_dword v189, v167, s[6:7]
	s_mov_b64 exec, -1
	s_branch .LBB0_37
